# row-norm rsq: dead denormal pre-scale selects removed at 42 sites (argument is mean square + eps)
# speedup vs baseline: 1.0041x; 1.0041x over previous
.LBB0_181:
	v_lshl_add_u32 v150, s14, 8, v154
	v_ashrrev_i32_e32 v151, 31, v150
	v_lshlrev_b64 v[148:149], 7, v[150:151]
	v_lshl_add_u64 v[148:149], v[138:139], 0, v[148:149]
	global_load_dwordx4 v[164:167], v[148:149], off
	global_load_dwordx4 v[168:171], v[148:149], off offset:16
	v_and_b32_e32 v149, 64, v160
	v_xor_b32_e32 v137, 16, v160
	v_add_u32_e32 v149, 64, v149
	v_cmp_lt_i32_e32 vcc, v137, v149
	v_lshl_or_b32 v148, s12, 8, v156
	s_cmp_gt_i32 s12, 7
	v_cndmask_b32_e32 v137, v160, v137, vcc
	v_lshlrev_b32_e32 v162, 2, v137
	s_cselect_b64 s[46:47], -1, 0
	s_and_b64 s[46:47], s[4:5], s[46:47]
	s_waitcnt vmcnt(0)
	v_mov_b32_e32 v152, v164
	v_mov_b32_e32 v153, v168
	v_mov_b32_e32 v168, v165
	v_mov_b32_e32 v164, v166
	v_mov_b32_e32 v165, v170
	v_mov_b32_e32 v170, v167
	v_pk_add_f32 v[152:153], v[152:153], v[168:169]
	v_pk_add_f32 v[164:165], v[164:165], v[170:171]
	s_nop 0
	v_pk_add_f32 v[152:153], v[152:153], v[164:165]
	s_nop 0
	v_add_f32_e32 v137, 0, v152
	v_add_f32_e32 v137, v137, v153
	ds_bpermute_b32 v152, v162, v137
	v_xor_b32_e32 v153, 32, v160
	v_cmp_lt_i32_e32 vcc, v153, v149
	s_waitcnt lgkmcnt(0)
	v_add_f32_e32 v137, v137, v152
	v_cndmask_b32_e32 v149, v160, v153, vcc
	v_lshlrev_b32_e32 v163, 2, v149
	ds_bpermute_b32 v152, v163, v137
	v_ashrrev_i32_e32 v149, 31, v148
	s_waitcnt lgkmcnt(0)
	v_add_f32_e32 v137, v137, v152
	v_fmamk_f32 v137, v137, 0x3a000000, v161
	v_rsq_f32_e32 v164, v137
	v_lshlrev_b64 v[152:153], 13, v[150:151]
	v_lshl_add_u64 v[152:153], s[18:19], 0, v[152:153]
	v_lshl_add_u64 v[152:153], v[148:149], 1, v[152:153]
	v_pk_mul_f32 v[124:125], v[124:125], v[164:165] op_sel_hi:[1,0]
	v_pk_mul_f32 v[120:121], v[120:121], v[164:165] op_sel_hi:[1,0]
	v_pk_mul_f32 v[126:127], v[126:127], v[164:165] op_sel_hi:[1,0]
	v_pk_mul_f32 v[122:123], v[122:123], v[164:165] op_sel_hi:[1,0]
	v_pk_mul_f32 v[118:119], v[118:119], v[164:165] op_sel_hi:[1,0]
	v_pk_mul_f32 v[116:117], v[116:117], v[164:165] op_sel_hi:[1,0]
	v_pk_mul_f32 v[166:167], v[112:113], v[164:165] op_sel_hi:[1,0]
	v_mul_f32_e32 v137, 0x3d122279, v124
	v_mul_f32_e32 v165, 0x3d122279, v120
	v_mul_f32_e32 v168, 0x3d122279, v125
	v_mul_f32_e32 v169, 0x3d122279, v121
	v_mul_f32_e32 v170, 0x3d122279, v126
	v_mul_f32_e32 v171, 0x3d122279, v122
	v_fmaak_f32 v137, v124, v137, 0x3f4c422a
	v_fmaak_f32 v165, v120, v165, 0x3f4c422a
	v_mov_b32_e32 v112, v124
	v_mov_b32_e32 v113, v120
	v_fmaak_f32 v168, v125, v168, 0x3f4c422a
	v_fmaak_f32 v169, v121, v169, 0x3f4c422a
	v_fmaak_f32 v170, v126, v170, 0x3f4c422a
	v_fmaak_f32 v171, v122, v171, 0x3f4c422a
	v_mul_f32_e32 v124, v124, v137
	v_mul_f32_e32 v120, v120, v165
	v_mul_f32_e32 v137, v125, v168
	v_mul_f32_e32 v165, v121, v169
	v_mul_f32_e32 v168, v126, v170
	v_mul_f32_e32 v169, v122, v171
	v_add_f32_e32 v124, v124, v124
	v_add_f32_e32 v120, v120, v120
	v_mul_f32_e32 v172, 0x3d122279, v127
	v_mul_f32_e32 v173, 0x3d122279, v123
	v_add_f32_e32 v168, v168, v168
	v_add_f32_e32 v169, v169, v169
	v_mul_f32_e32 v124, 0xbfb8aa3b, v124
	v_mul_f32_e32 v120, 0xbfb8aa3b, v120
	v_fmaak_f32 v172, v127, v172, 0x3f4c422a
	v_fmaak_f32 v173, v123, v173, 0x3f4c422a
	v_add_f32_e32 v165, v165, v165
	v_mul_f32_e32 v168, 0xbfb8aa3b, v168
	v_mul_f32_e32 v169, 0xbfb8aa3b, v169
	v_exp_f32_e32 v124, v124
	v_exp_f32_e32 v120, v120
	v_mul_f32_e32 v170, v127, v172
	v_mul_f32_e32 v171, v123, v173
	v_mul_f32_e32 v165, 0xbfb8aa3b, v165
	v_exp_f32_e32 v168, v168
	v_exp_f32_e32 v169, v169
	v_mul_f32_e32 v174, 0x3d122279, v116
	v_add_f32_e32 v137, v137, v137
	v_add_f32_e32 v170, v170, v170
	v_add_f32_e32 v171, v171, v171
	v_exp_f32_e32 v165, v165
	v_fmaak_f32 v174, v116, v174, 0x3f4c422a
	v_mul_f32_e32 v137, 0xbfb8aa3b, v137
	v_mul_f32_e32 v170, 0xbfb8aa3b, v170
	v_mul_f32_e32 v171, 0xbfb8aa3b, v171
	v_mul_f32_e32 v172, v116, v174
	v_exp_f32_e32 v137, v137
	v_exp_f32_e32 v170, v170
	v_exp_f32_e32 v171, v171
	v_add_f32_e32 v124, 1.0, v124
	v_add_f32_e32 v120, 1.0, v120
	v_add_f32_e32 v172, v172, v172
	v_add_f32_e32 v173, 1.0, v168
	v_add_f32_e32 v174, 1.0, v169
	v_rcp_f32_e32 v168, v124
	v_rcp_f32_e32 v169, v120
	v_mul_f32_e32 v172, 0xbfb8aa3b, v172
	v_add_f32_e32 v165, 1.0, v165
	v_exp_f32_e32 v172, v172
	v_rcp_f32_e32 v120, v165
	v_rcp_f32_e32 v165, v174
	v_add_f32_e32 v137, 1.0, v137
	v_add_f32_e32 v170, 1.0, v170
	v_add_f32_e32 v171, 1.0, v171
	v_rcp_f32_e32 v124, v137
	v_rcp_f32_e32 v137, v173
	v_rcp_f32_e32 v173, v170
	v_rcp_f32_e32 v174, v171
	v_pk_mul_f32 v[170:171], v[112:113], v[168:169]
	v_pk_mul_f32 v[114:115], v[114:115], v[164:165] op_sel_hi:[1,0]
	v_pk_fma_f32 v[112:113], v[112:113], v[168:169], v[170:171] op_sel:[0,0,1] op_sel_hi:[1,1,0]
	v_add_f32_e32 v164, 1.0, v172
	v_mul_f32_e32 v113, 0x3d122279, v166
	v_fmaak_f32 v113, v166, v113, 0x3f4c422a
	v_rcp_f32_e32 v178, v164
	v_mul_f32_e32 v164, 0x3d122279, v117
	v_mul_f32_e32 v113, v166, v113
	v_fmaak_f32 v164, v117, v164, 0x3f4c422a
	v_mul_f32_e32 v168, 0x3d122279, v167
	v_add_f32_e32 v113, v113, v113
	v_mul_f32_e32 v164, v117, v164
	v_fmaak_f32 v168, v167, v168, 0x3f4c422a
	v_mul_f32_e32 v113, 0xbfb8aa3b, v113
	v_add_f32_e32 v164, v164, v164
	v_mul_f32_e32 v168, v167, v168
	v_exp_f32_e32 v113, v113
	v_mul_f32_e32 v164, 0xbfb8aa3b, v164
	v_add_f32_e32 v168, v168, v168
	v_exp_f32_e32 v164, v164
	v_mul_f32_e32 v168, 0xbfb8aa3b, v168
	v_exp_f32_e32 v168, v168
	v_add_f32_e32 v113, 1.0, v113
	v_rcp_f32_e32 v179, v113
	v_add_f32_e32 v113, 1.0, v164
	v_mul_f32_e32 v164, 0x3d122279, v118
	v_rcp_f32_e32 v180, v113
	v_add_f32_e32 v113, 1.0, v168
	v_fmaak_f32 v164, v118, v164, 0x3f4c422a
	v_mul_f32_e32 v168, 0x3d122279, v114
	v_mul_f32_e32 v164, v118, v164
	v_fmaak_f32 v168, v114, v168, 0x3f4c422a
	v_add_f32_e32 v164, v164, v164
	v_mul_f32_e32 v168, v114, v168
	v_mul_f32_e32 v164, 0xbfb8aa3b, v164
	v_add_f32_e32 v168, v168, v168
	v_exp_f32_e32 v164, v164
	v_mul_f32_e32 v168, 0xbfb8aa3b, v168
	v_exp_f32_e32 v168, v168
	v_rcp_f32_e32 v181, v113
	v_add_f32_e32 v113, 1.0, v164
	v_mul_f32_e32 v164, 0x3d122279, v119
	v_rcp_f32_e32 v182, v113
	v_add_f32_e32 v113, 1.0, v168
	v_fmaak_f32 v164, v119, v164, 0x3f4c422a
	v_mul_f32_e32 v168, 0x3d122279, v115
	v_mul_f32_e32 v164, v119, v164
	v_fmaak_f32 v168, v115, v168, 0x3f4c422a
	v_add_f32_e32 v164, v164, v164
	v_mul_f32_e32 v168, v115, v168
	v_mul_f32_e32 v164, 0xbfb8aa3b, v164
	v_add_f32_e32 v168, v168, v168
	v_exp_f32_e32 v164, v164
	v_mul_f32_e32 v168, 0xbfb8aa3b, v168
	v_exp_f32_e32 v168, v168
	v_rcp_f32_e32 v183, v113
	v_add_f32_e32 v113, 1.0, v164
	v_mul_f32_e32 v164, v127, v173
	v_mov_b32_e32 v172, v125
	v_mov_b32_e32 v173, v170
	v_mov_b32_e32 v125, v170
	v_mov_b32_e32 v176, v121
	v_mov_b32_e32 v177, v171
	v_mov_b32_e32 v121, v171
	v_rcp_f32_e32 v184, v113
	v_add_f32_e32 v113, 1.0, v168
	v_mul_f32_e32 v168, v123, v174
	v_pk_mul_f32 v[174:175], v[172:173], v[124:125]
	v_pk_mul_f32 v[120:121], v[176:177], v[120:121]
	v_rcp_f32_e32 v185, v113
	v_pk_fma_f32 v[124:125], v[172:173], v[124:125], v[120:121]
	v_pk_mul_f32 v[172:173], v[174:175], v[174:175]
	v_pk_mul_f32 v[176:177], v[120:121], v[120:121]
	v_mul_f32_e32 v126, v126, v137
	v_mul_f32_e32 v122, v122, v165
	v_mov_b32_e32 v113, v172
	v_mov_b32_e32 v137, v176
	v_pk_add_f32 v[112:113], v[112:113], v[136:137]
	v_mul_f32_e32 v127, v126, v126
	v_mul_f32_e32 v123, v122, v122
	v_pk_add_f32 v[112:113], v[124:125], v[112:113]
	v_pk_add_f32 v[124:125], v[126:127], v[122:123]
	v_mul_f32_e32 v165, v164, v164
	v_mul_f32_e32 v169, v168, v168
	v_pk_add_f32 v[112:113], v[124:125], v[112:113]
	v_pk_add_f32 v[124:125], v[164:165], v[168:169]
	v_mul_f32_e32 v116, v116, v178
	v_pk_add_f32 v[124:125], v[124:125], v[112:113]
	v_cvt_pk_bf16_f32 v112, v170, v174
	v_cvt_pk_bf16_f32 v113, v126, v164
	v_mul_f32_e32 v126, v166, v179
	v_mul_f32_e32 v164, v117, v180
	v_mul_f32_e32 v166, v167, v181
	v_mul_f32_e32 v117, v116, v116
	v_mul_f32_e32 v127, v126, v126
	v_mul_f32_e32 v118, v118, v182
	v_mul_f32_e32 v172, v114, v183
	v_mul_f32_e32 v176, v115, v185
	v_pk_add_f32 v[114:115], v[116:117], v[126:127]
	v_mul_f32_e32 v165, v164, v164
	v_mul_f32_e32 v167, v166, v166
	v_mul_f32_e32 v174, v119, v184
	v_pk_add_f32 v[114:115], v[114:115], v[124:125]
	v_pk_add_f32 v[124:125], v[164:165], v[166:167]
	v_mul_f32_e32 v119, v118, v118
	v_mul_f32_e32 v173, v172, v172
	v_pk_add_f32 v[114:115], v[124:125], v[114:115]
	v_pk_add_f32 v[124:125], v[118:119], v[172:173]
	v_mul_f32_e32 v175, v174, v174
	v_mul_f32_e32 v177, v176, v176
	v_pk_add_f32 v[114:115], v[124:125], v[114:115]
	v_pk_add_f32 v[124:125], v[174:175], v[176:177]
	s_nop 0
	v_pk_add_f32 v[124:125], v[124:125], v[114:115]
	ds_bpermute_b32 v178, v162, v124
	ds_bpermute_b32 v179, v162, v125
	v_cvt_pk_bf16_f32 v114, v171, v120
	v_cvt_pk_bf16_f32 v115, v122, v168
	global_store_dwordx4 v[152:153], v[112:115], off
	v_cvt_pk_bf16_f32 v116, v116, v164
	v_cvt_pk_bf16_f32 v117, v118, v174
	v_cvt_pk_bf16_f32 v118, v126, v166
	v_cvt_pk_bf16_f32 v119, v172, v176
	global_store_dwordx4 v[152:153], v[116:119], off offset:256
	s_waitcnt lgkmcnt(0)
	v_pk_add_f32 v[112:113], v[124:125], v[178:179]
	ds_bpermute_b32 v114, v163, v112
	ds_bpermute_b32 v115, v163, v113
	s_and_saveexec_b64 s[48:49], s[46:47]
	s_cbranch_execz .LBB0_183
	s_lshl_b32 s14, s12, 2
	v_lshlrev_b64 v[116:117], 5, v[150:151]
	s_sub_i32 s14, s14, 32
	v_lshl_add_u64 v[116:117], v[116:117], 0, s[14:15]
	v_or_b32_e32 v116, s56, v116
	v_lshl_add_u64 v[116:117], v[116:117], 3, s[20:21]
	s_waitcnt lgkmcnt(0)
	v_pk_add_f32 v[112:113], v[112:113], v[114:115]
	global_store_dwordx2 v[116:117], v[112:113], off
.LBB0_183:
	s_or_b64 exec, exec, s[48:49]
	v_or_b32_e32 v112, 16, v150
	v_ashrrev_i32_e32 v113, 31, v112
	s_waitcnt lgkmcnt(0)
	v_lshlrev_b64 v[114:115], 7, v[112:113]
	v_lshl_add_u64 v[118:119], v[138:139], 0, v[114:115]
	global_load_dwordx4 v[114:117], v[118:119], off
	s_nop 0
	global_load_dwordx4 v[118:121], v[118:119], off offset:16
	s_waitcnt vmcnt(1)
	v_mov_b32_e32 v122, v114
	s_waitcnt vmcnt(0)
	v_mov_b32_e32 v123, v118
	v_mov_b32_e32 v118, v115
	v_mov_b32_e32 v114, v116
	v_mov_b32_e32 v115, v120
	v_mov_b32_e32 v120, v117
	v_pk_add_f32 v[116:117], v[122:123], v[118:119]
	v_pk_add_f32 v[114:115], v[114:115], v[120:121]
	s_nop 0
	v_pk_add_f32 v[114:115], v[116:117], v[114:115]
	s_nop 0
	v_add_f32_e32 v114, 0, v114
	v_add_f32_e32 v114, v114, v115
	ds_bpermute_b32 v115, v162, v114
	s_waitcnt lgkmcnt(0)
	v_add_f32_e32 v114, v114, v115
	ds_bpermute_b32 v115, v163, v114
	s_waitcnt lgkmcnt(0)
	v_add_f32_e32 v114, v114, v115
	v_fmamk_f32 v114, v114, 0x3a000000, v161
	v_rsq_f32_e32 v116, v114
	v_lshlrev_b64 v[114:115], 13, v[112:113]
	v_lshl_add_u64 v[114:115], s[18:19], 0, v[114:115]
	v_lshl_add_u64 v[114:115], v[148:149], 1, v[114:115]
	v_pk_mul_f32 v[108:109], v[108:109], v[116:117] op_sel_hi:[1,0]
	v_pk_mul_f32 v[104:105], v[104:105], v[116:117] op_sel_hi:[1,0]
	v_mul_f32_e32 v118, 0x3d122279, v108
	v_mul_f32_e32 v119, 0x3d122279, v104
	v_mul_f32_e32 v120, 0x3d122279, v109
	v_mul_f32_e32 v121, 0x3d122279, v105
	v_fmaak_f32 v118, v108, v118, 0x3f4c422a
	v_fmaak_f32 v119, v104, v119, 0x3f4c422a
	v_pk_mul_f32 v[110:111], v[110:111], v[116:117] op_sel_hi:[1,0]
	v_pk_mul_f32 v[106:107], v[106:107], v[116:117] op_sel_hi:[1,0]
	v_pk_mul_f32 v[102:103], v[102:103], v[116:117] op_sel_hi:[1,0]
	v_pk_mul_f32 v[100:101], v[100:101], v[116:117] op_sel_hi:[1,0]
	v_pk_mul_f32 v[98:99], v[98:99], v[116:117] op_sel_hi:[1,0]
	v_pk_mul_f32 v[116:117], v[96:97], v[116:117] op_sel_hi:[1,0]
	v_mov_b32_e32 v96, v108
	v_mov_b32_e32 v97, v104
	v_fmaak_f32 v120, v109, v120, 0x3f4c422a
	v_fmaak_f32 v121, v105, v121, 0x3f4c422a
	v_mul_f32_e32 v108, v108, v118
	v_mul_f32_e32 v104, v104, v119
	v_mul_f32_e32 v118, v109, v120
	v_mul_f32_e32 v119, v105, v121
	v_add_f32_e32 v108, v108, v108
	v_add_f32_e32 v104, v104, v104
	v_mul_f32_e32 v122, 0x3d122279, v110
	v_mul_f32_e32 v123, 0x3d122279, v106
	v_add_f32_e32 v118, v118, v118
	v_add_f32_e32 v119, v119, v119
	v_mul_f32_e32 v108, 0xbfb8aa3b, v108
	v_mul_f32_e32 v104, 0xbfb8aa3b, v104
	v_fmaak_f32 v122, v110, v122, 0x3f4c422a
	v_fmaak_f32 v123, v106, v123, 0x3f4c422a
	v_mul_f32_e32 v118, 0xbfb8aa3b, v118
	v_mul_f32_e32 v119, 0xbfb8aa3b, v119
	v_exp_f32_e32 v108, v108
	v_exp_f32_e32 v104, v104
	v_mul_f32_e32 v120, v110, v122
	v_mul_f32_e32 v121, v106, v123
	v_exp_f32_e32 v118, v118
	v_exp_f32_e32 v119, v119
	v_add_f32_e32 v120, v120, v120
	v_add_f32_e32 v121, v121, v121
	v_mul_f32_e32 v124, 0x3d122279, v111
	v_mul_f32_e32 v125, 0x3d122279, v107
	v_mul_f32_e32 v126, 0x3d122279, v100
	v_mul_f32_e32 v127, 0x3d122279, v116
	v_mul_f32_e32 v137, 0x3d122279, v101
	v_mul_f32_e32 v120, 0xbfb8aa3b, v120
	v_mul_f32_e32 v121, 0xbfb8aa3b, v121
	v_fmaak_f32 v124, v111, v124, 0x3f4c422a
	v_fmaak_f32 v125, v107, v125, 0x3f4c422a
	v_fmaak_f32 v126, v100, v126, 0x3f4c422a
	v_fmaak_f32 v127, v116, v127, 0x3f4c422a
	v_fmaak_f32 v137, v101, v137, 0x3f4c422a
	v_exp_f32_e32 v120, v120
	v_exp_f32_e32 v121, v121
	v_add_f32_e32 v108, 1.0, v108
	v_add_f32_e32 v104, 1.0, v104
	v_mul_f32_e32 v122, v111, v124
	v_mul_f32_e32 v123, v107, v125
	v_mul_f32_e32 v124, v100, v126
	v_mul_f32_e32 v125, v116, v127
	v_mul_f32_e32 v126, v101, v137
	v_add_f32_e32 v127, 1.0, v118
	v_add_f32_e32 v137, 1.0, v119
	v_rcp_f32_e32 v118, v108
	v_rcp_f32_e32 v119, v104
	v_add_f32_e32 v120, 1.0, v120
	v_add_f32_e32 v121, 1.0, v121
	v_rcp_f32_e32 v108, v127
	v_rcp_f32_e32 v104, v137
	v_rcp_f32_e32 v127, v120
	v_rcp_f32_e32 v137, v121
	v_pk_mul_f32 v[120:121], v[96:97], v[118:119]
	v_add_f32_e32 v126, v126, v126
	v_pk_fma_f32 v[96:97], v[96:97], v[118:119], v[120:121] op_sel:[0,0,1] op_sel_hi:[1,1,0]
	v_mul_f32_e32 v118, 0x3d122279, v117
	v_fmaak_f32 v118, v117, v118, 0x3f4c422a
	v_mul_f32_e32 v118, v117, v118
	v_mul_f32_e32 v97, 0xbfb8aa3b, v126
	v_add_f32_e32 v118, v118, v118
	v_exp_f32_e32 v97, v97
	v_mul_f32_e32 v118, 0xbfb8aa3b, v118
	v_exp_f32_e32 v118, v118
	v_mul_f32_e32 v119, 0x3d122279, v98
	v_add_f32_e32 v97, 1.0, v97
	v_rcp_f32_e32 v165, v97
	v_add_f32_e32 v97, 1.0, v118
	v_mul_f32_e32 v118, 0x3d122279, v102
	v_fmaak_f32 v118, v102, v118, 0x3f4c422a
	v_mul_f32_e32 v118, v102, v118
	v_fmaak_f32 v119, v98, v119, 0x3f4c422a
	v_add_f32_e32 v118, v118, v118
	v_mul_f32_e32 v119, v98, v119
	v_mul_f32_e32 v118, 0xbfb8aa3b, v118
	v_add_f32_e32 v119, v119, v119
	v_exp_f32_e32 v118, v118
	v_mul_f32_e32 v119, 0xbfb8aa3b, v119
	v_exp_f32_e32 v119, v119
	v_rcp_f32_e32 v166, v97
	v_add_f32_e32 v97, 1.0, v118
	v_mul_f32_e32 v118, 0x3d122279, v103
	v_add_f32_e32 v122, v122, v122
	v_add_f32_e32 v123, v123, v123
	v_add_f32_e32 v124, v124, v124
	v_add_f32_e32 v125, v125, v125
	v_rcp_f32_e32 v167, v97
	v_add_f32_e32 v97, 1.0, v119
	v_fmaak_f32 v118, v103, v118, 0x3f4c422a
	v_mul_f32_e32 v119, 0x3d122279, v99
	v_mul_f32_e32 v122, 0xbfb8aa3b, v122
	v_mul_f32_e32 v123, 0xbfb8aa3b, v123
	v_mul_f32_e32 v124, 0xbfb8aa3b, v124
	v_mul_f32_e32 v125, 0xbfb8aa3b, v125
	v_mul_f32_e32 v118, v103, v118
	v_fmaak_f32 v119, v99, v119, 0x3f4c422a
	v_exp_f32_e32 v122, v122
	v_exp_f32_e32 v123, v123
	v_exp_f32_e32 v124, v124
	v_exp_f32_e32 v125, v125
	v_add_f32_e32 v118, v118, v118
	v_mul_f32_e32 v119, v99, v119
	v_mul_f32_e32 v118, 0xbfb8aa3b, v118
	v_add_f32_e32 v119, v119, v119
	v_exp_f32_e32 v118, v118
	v_mul_f32_e32 v119, 0xbfb8aa3b, v119
	v_exp_f32_e32 v119, v119
	v_add_f32_e32 v122, 1.0, v122
	v_add_f32_e32 v123, 1.0, v123
	v_add_f32_e32 v124, 1.0, v124
	v_add_f32_e32 v125, 1.0, v125
	v_rcp_f32_e32 v122, v122
	v_rcp_f32_e32 v123, v123
	v_rcp_f32_e32 v151, v124
	v_rcp_f32_e32 v164, v125
	v_mov_b32_e32 v124, v109
	v_mov_b32_e32 v125, v120
	v_mov_b32_e32 v109, v120
	v_mov_b32_e32 v152, v105
	v_mov_b32_e32 v153, v121
	v_mov_b32_e32 v105, v121
	v_rcp_f32_e32 v168, v97
	v_add_f32_e32 v97, 1.0, v118
	v_mul_f32_e32 v110, v110, v127
	v_pk_mul_f32 v[126:127], v[124:125], v[108:109]
	v_pk_mul_f32 v[104:105], v[152:153], v[104:105]
	v_rcp_f32_e32 v169, v97
	v_add_f32_e32 v97, 1.0, v119
	v_pk_fma_f32 v[108:109], v[124:125], v[108:109], v[104:105]
	v_pk_mul_f32 v[124:125], v[126:127], v[126:127]
	v_pk_mul_f32 v[152:153], v[104:105], v[104:105]
	v_rcp_f32_e32 v170, v97
	v_mul_f32_e32 v106, v106, v137
	v_mov_b32_e32 v97, v124
	v_mov_b32_e32 v137, v152
	v_mul_f32_e32 v118, v111, v122
	v_mul_f32_e32 v122, v107, v123
	v_pk_add_f32 v[96:97], v[96:97], v[136:137]
	v_mul_f32_e32 v111, v110, v110
	v_mul_f32_e32 v107, v106, v106
	v_pk_add_f32 v[96:97], v[108:109], v[96:97]
	v_pk_add_f32 v[108:109], v[110:111], v[106:107]
	v_mul_f32_e32 v119, v118, v118
	v_mul_f32_e32 v123, v122, v122
	v_pk_add_f32 v[96:97], v[108:109], v[96:97]
	v_pk_add_f32 v[108:109], v[118:119], v[122:123]
	v_mul_f32_e32 v100, v100, v151
	v_pk_add_f32 v[108:109], v[108:109], v[96:97]
	v_cvt_pk_bf16_f32 v96, v120, v126
	v_cvt_pk_bf16_f32 v97, v110, v118
	v_mul_f32_e32 v110, v116, v164
	v_mul_f32_e32 v116, v101, v165
	v_mul_f32_e32 v118, v117, v166
	v_mul_f32_e32 v101, v100, v100
	v_mul_f32_e32 v111, v110, v110
	v_mul_f32_e32 v102, v102, v167
	v_mul_f32_e32 v124, v98, v168
	v_mul_f32_e32 v152, v99, v170
	v_pk_add_f32 v[98:99], v[100:101], v[110:111]
	v_mul_f32_e32 v117, v116, v116
	v_mul_f32_e32 v119, v118, v118
	v_mul_f32_e32 v126, v103, v169
	v_pk_add_f32 v[98:99], v[98:99], v[108:109]
	v_pk_add_f32 v[108:109], v[116:117], v[118:119]
	v_mul_f32_e32 v103, v102, v102
	v_mul_f32_e32 v125, v124, v124
	v_pk_add_f32 v[98:99], v[108:109], v[98:99]
	v_pk_add_f32 v[108:109], v[102:103], v[124:125]
	v_mul_f32_e32 v127, v126, v126
	v_mul_f32_e32 v153, v152, v152
	v_pk_add_f32 v[98:99], v[108:109], v[98:99]
	v_pk_add_f32 v[108:109], v[126:127], v[152:153]
	s_nop 0
	v_pk_add_f32 v[108:109], v[108:109], v[98:99]
	ds_bpermute_b32 v164, v162, v108
	ds_bpermute_b32 v165, v162, v109
	v_cvt_pk_bf16_f32 v98, v121, v104
	v_cvt_pk_bf16_f32 v99, v106, v122
	global_store_dwordx4 v[114:115], v[96:99], off
	v_cvt_pk_bf16_f32 v100, v100, v116
	v_cvt_pk_bf16_f32 v101, v102, v126
	v_cvt_pk_bf16_f32 v102, v110, v118
	v_cvt_pk_bf16_f32 v103, v124, v152
	global_store_dwordx4 v[114:115], v[100:103], off offset:256
	s_waitcnt lgkmcnt(0)
	v_pk_add_f32 v[96:97], v[108:109], v[164:165]
	ds_bpermute_b32 v98, v163, v96
	ds_bpermute_b32 v99, v163, v97
	s_and_saveexec_b64 s[48:49], s[46:47]
	s_cbranch_execz .LBB0_185
	s_lshl_b32 s14, s12, 2
	v_lshlrev_b64 v[100:101], 5, v[112:113]
	s_sub_i32 s14, s14, 32
	v_lshl_add_u64 v[100:101], v[100:101], 0, s[14:15]
	v_or_b32_e32 v100, s56, v100
	v_lshl_add_u64 v[100:101], v[100:101], 3, s[20:21]
	s_waitcnt lgkmcnt(0)
	v_pk_add_f32 v[96:97], v[96:97], v[98:99]
	global_store_dwordx2 v[100:101], v[96:97], off
.LBB0_185:
	s_or_b64 exec, exec, s[48:49]
	v_or_b32_e32 v96, 32, v150
	v_ashrrev_i32_e32 v97, 31, v96
	s_waitcnt lgkmcnt(0)
	v_lshlrev_b64 v[98:99], 7, v[96:97]
	v_lshl_add_u64 v[102:103], v[138:139], 0, v[98:99]
	global_load_dwordx4 v[98:101], v[102:103], off
	s_nop 0
	global_load_dwordx4 v[102:105], v[102:103], off offset:16
	s_waitcnt vmcnt(1)
	v_mov_b32_e32 v106, v98
	s_waitcnt vmcnt(0)
	v_mov_b32_e32 v107, v102
	v_mov_b32_e32 v102, v99
	v_mov_b32_e32 v98, v100
	v_mov_b32_e32 v99, v104
	v_mov_b32_e32 v104, v101
	v_pk_add_f32 v[100:101], v[106:107], v[102:103]
	v_pk_add_f32 v[98:99], v[98:99], v[104:105]
	s_nop 0
	v_pk_add_f32 v[98:99], v[100:101], v[98:99]
	s_nop 0
	v_add_f32_e32 v98, 0, v98
	v_add_f32_e32 v98, v98, v99
	ds_bpermute_b32 v99, v162, v98
	s_waitcnt lgkmcnt(0)
	v_add_f32_e32 v98, v98, v99
	ds_bpermute_b32 v99, v163, v98
	s_waitcnt lgkmcnt(0)
	v_add_f32_e32 v98, v98, v99
	v_fmamk_f32 v98, v98, 0x3a000000, v161
	v_rsq_f32_e32 v100, v98
	v_lshlrev_b64 v[98:99], 13, v[96:97]
	v_lshl_add_u64 v[98:99], s[18:19], 0, v[98:99]
	v_lshl_add_u64 v[98:99], v[148:149], 1, v[98:99]
	v_pk_mul_f32 v[92:93], v[92:93], v[100:101] op_sel_hi:[1,0]
	v_pk_mul_f32 v[88:89], v[88:89], v[100:101] op_sel_hi:[1,0]
	v_mul_f32_e32 v102, 0x3d122279, v92
	v_mul_f32_e32 v103, 0x3d122279, v88
	v_mul_f32_e32 v104, 0x3d122279, v93
	v_mul_f32_e32 v105, 0x3d122279, v89
	v_fmaak_f32 v102, v92, v102, 0x3f4c422a
	v_fmaak_f32 v103, v88, v103, 0x3f4c422a
	v_pk_mul_f32 v[94:95], v[94:95], v[100:101] op_sel_hi:[1,0]
	v_pk_mul_f32 v[90:91], v[90:91], v[100:101] op_sel_hi:[1,0]
	v_pk_mul_f32 v[86:87], v[86:87], v[100:101] op_sel_hi:[1,0]
	v_pk_mul_f32 v[84:85], v[84:85], v[100:101] op_sel_hi:[1,0]
	v_pk_mul_f32 v[82:83], v[82:83], v[100:101] op_sel_hi:[1,0]
	v_pk_mul_f32 v[100:101], v[80:81], v[100:101] op_sel_hi:[1,0]
	v_mov_b32_e32 v80, v92
	v_mov_b32_e32 v81, v88
	v_fmaak_f32 v104, v93, v104, 0x3f4c422a
	v_fmaak_f32 v105, v89, v105, 0x3f4c422a
	v_mul_f32_e32 v92, v92, v102
	v_mul_f32_e32 v88, v88, v103
	v_mul_f32_e32 v102, v93, v104
	v_mul_f32_e32 v103, v89, v105
	v_add_f32_e32 v92, v92, v92
	v_add_f32_e32 v88, v88, v88
	v_mul_f32_e32 v106, 0x3d122279, v94
	v_mul_f32_e32 v107, 0x3d122279, v90
	v_add_f32_e32 v102, v102, v102
	v_add_f32_e32 v103, v103, v103
	v_mul_f32_e32 v92, 0xbfb8aa3b, v92
	v_mul_f32_e32 v88, 0xbfb8aa3b, v88
	v_fmaak_f32 v106, v94, v106, 0x3f4c422a
	v_fmaak_f32 v107, v90, v107, 0x3f4c422a
	v_mul_f32_e32 v102, 0xbfb8aa3b, v102
	v_mul_f32_e32 v103, 0xbfb8aa3b, v103
	v_exp_f32_e32 v92, v92
	v_exp_f32_e32 v88, v88
	v_mul_f32_e32 v104, v94, v106
	v_mul_f32_e32 v105, v90, v107
	v_exp_f32_e32 v102, v102
	v_exp_f32_e32 v103, v103
	v_add_f32_e32 v104, v104, v104
	v_add_f32_e32 v105, v105, v105
	v_mul_f32_e32 v108, 0x3d122279, v95
	v_mul_f32_e32 v109, 0x3d122279, v91
	v_mul_f32_e32 v110, 0x3d122279, v84
	v_mul_f32_e32 v111, 0x3d122279, v100
	v_mul_f32_e32 v112, 0x3d122279, v85
	v_mul_f32_e32 v104, 0xbfb8aa3b, v104
	v_mul_f32_e32 v105, 0xbfb8aa3b, v105
	v_fmaak_f32 v108, v95, v108, 0x3f4c422a
	v_fmaak_f32 v109, v91, v109, 0x3f4c422a
	v_fmaak_f32 v110, v84, v110, 0x3f4c422a
	v_fmaak_f32 v111, v100, v111, 0x3f4c422a
	v_fmaak_f32 v112, v85, v112, 0x3f4c422a
	v_exp_f32_e32 v104, v104
	v_exp_f32_e32 v105, v105
	v_add_f32_e32 v92, 1.0, v92
	v_add_f32_e32 v88, 1.0, v88
	v_mul_f32_e32 v106, v95, v108
	v_mul_f32_e32 v107, v91, v109
	v_mul_f32_e32 v108, v84, v110
	v_mul_f32_e32 v109, v100, v111
	v_mul_f32_e32 v110, v85, v112
	v_add_f32_e32 v111, 1.0, v102
	v_add_f32_e32 v112, 1.0, v103
	v_rcp_f32_e32 v102, v92
	v_rcp_f32_e32 v103, v88
	v_add_f32_e32 v104, 1.0, v104
	v_add_f32_e32 v105, 1.0, v105
	v_rcp_f32_e32 v92, v111
	v_rcp_f32_e32 v88, v112
	v_rcp_f32_e32 v111, v104
	v_rcp_f32_e32 v112, v105
	v_pk_mul_f32 v[104:105], v[80:81], v[102:103]
	v_add_f32_e32 v110, v110, v110
	v_pk_fma_f32 v[80:81], v[80:81], v[102:103], v[104:105] op_sel:[0,0,1] op_sel_hi:[1,1,0]
	v_mul_f32_e32 v102, 0x3d122279, v101
	v_fmaak_f32 v102, v101, v102, 0x3f4c422a
	v_mul_f32_e32 v102, v101, v102
	v_mul_f32_e32 v81, 0xbfb8aa3b, v110
	v_add_f32_e32 v102, v102, v102
	v_exp_f32_e32 v81, v81
	v_mul_f32_e32 v102, 0xbfb8aa3b, v102
	v_exp_f32_e32 v102, v102
	v_mul_f32_e32 v103, 0x3d122279, v82
	v_add_f32_e32 v81, 1.0, v81
	v_rcp_f32_e32 v116, v81
	v_add_f32_e32 v81, 1.0, v102
	v_mul_f32_e32 v102, 0x3d122279, v86
	v_fmaak_f32 v102, v86, v102, 0x3f4c422a
	v_mul_f32_e32 v102, v86, v102
	v_fmaak_f32 v103, v82, v103, 0x3f4c422a
	v_add_f32_e32 v102, v102, v102
	v_mul_f32_e32 v103, v82, v103
	v_mul_f32_e32 v102, 0xbfb8aa3b, v102
	v_add_f32_e32 v103, v103, v103
	v_exp_f32_e32 v102, v102
	v_mul_f32_e32 v103, 0xbfb8aa3b, v103
	v_exp_f32_e32 v103, v103
	v_rcp_f32_e32 v117, v81
	v_add_f32_e32 v81, 1.0, v102
	v_mul_f32_e32 v102, 0x3d122279, v87
	v_add_f32_e32 v106, v106, v106
	v_add_f32_e32 v107, v107, v107
	v_add_f32_e32 v108, v108, v108
	v_add_f32_e32 v109, v109, v109
	v_rcp_f32_e32 v118, v81
	v_add_f32_e32 v81, 1.0, v103
	v_fmaak_f32 v102, v87, v102, 0x3f4c422a
	v_mul_f32_e32 v103, 0x3d122279, v83
	v_mul_f32_e32 v106, 0xbfb8aa3b, v106
	v_mul_f32_e32 v107, 0xbfb8aa3b, v107
	v_mul_f32_e32 v108, 0xbfb8aa3b, v108
	v_mul_f32_e32 v109, 0xbfb8aa3b, v109
	v_mul_f32_e32 v102, v87, v102
	v_fmaak_f32 v103, v83, v103, 0x3f4c422a
	v_exp_f32_e32 v106, v106
	v_exp_f32_e32 v107, v107
	v_exp_f32_e32 v108, v108
	v_exp_f32_e32 v109, v109
	v_add_f32_e32 v102, v102, v102
	v_mul_f32_e32 v103, v83, v103
	v_mul_f32_e32 v102, 0xbfb8aa3b, v102
	v_add_f32_e32 v103, v103, v103
	v_exp_f32_e32 v102, v102
	v_mul_f32_e32 v103, 0xbfb8aa3b, v103
	v_exp_f32_e32 v103, v103
	v_add_f32_e32 v106, 1.0, v106
	v_add_f32_e32 v107, 1.0, v107
	v_add_f32_e32 v108, 1.0, v108
	v_add_f32_e32 v109, 1.0, v109
	v_rcp_f32_e32 v106, v106
	v_rcp_f32_e32 v107, v107
	v_rcp_f32_e32 v114, v108
	v_rcp_f32_e32 v115, v109
	v_mul_f32_e32 v90, v90, v112
	v_mov_b32_e32 v108, v93
	v_mov_b32_e32 v109, v104
	v_mov_b32_e32 v93, v104
	v_mov_b32_e32 v112, v89
	v_mov_b32_e32 v113, v105
	v_mov_b32_e32 v89, v105
	v_rcp_f32_e32 v119, v81
	v_add_f32_e32 v81, 1.0, v102
	v_mul_f32_e32 v94, v94, v111
	v_pk_mul_f32 v[110:111], v[108:109], v[92:93]
	v_pk_mul_f32 v[88:89], v[112:113], v[88:89]
	v_rcp_f32_e32 v120, v81
	v_add_f32_e32 v81, 1.0, v103
	v_pk_fma_f32 v[92:93], v[108:109], v[92:93], v[88:89]
	v_pk_mul_f32 v[108:109], v[110:111], v[110:111]
	v_pk_mul_f32 v[112:113], v[88:89], v[88:89]
	v_rcp_f32_e32 v121, v81
	v_mov_b32_e32 v81, v108
	v_mov_b32_e32 v137, v112
	v_mul_f32_e32 v102, v95, v106
	v_mul_f32_e32 v106, v91, v107
	v_pk_add_f32 v[80:81], v[80:81], v[136:137]
	v_mul_f32_e32 v95, v94, v94
	v_mul_f32_e32 v91, v90, v90
	v_pk_add_f32 v[80:81], v[92:93], v[80:81]
	v_pk_add_f32 v[92:93], v[94:95], v[90:91]
	v_mul_f32_e32 v103, v102, v102
	v_mul_f32_e32 v107, v106, v106
	v_pk_add_f32 v[80:81], v[92:93], v[80:81]
	v_pk_add_f32 v[92:93], v[102:103], v[106:107]
	v_mul_f32_e32 v84, v84, v114
	v_pk_add_f32 v[92:93], v[92:93], v[80:81]
	v_cvt_pk_bf16_f32 v80, v104, v110
	v_cvt_pk_bf16_f32 v81, v94, v102
	v_mul_f32_e32 v94, v100, v115
	v_mul_f32_e32 v100, v85, v116
	v_mul_f32_e32 v102, v101, v117
	v_mul_f32_e32 v85, v84, v84
	v_mul_f32_e32 v95, v94, v94
	v_mul_f32_e32 v86, v86, v118
	v_mul_f32_e32 v108, v82, v119
	v_mul_f32_e32 v112, v83, v121
	v_pk_add_f32 v[82:83], v[84:85], v[94:95]
	v_mul_f32_e32 v101, v100, v100
	v_mul_f32_e32 v103, v102, v102
	v_mul_f32_e32 v110, v87, v120
	v_pk_add_f32 v[82:83], v[82:83], v[92:93]
	v_pk_add_f32 v[92:93], v[100:101], v[102:103]
	v_mul_f32_e32 v87, v86, v86
	v_mul_f32_e32 v109, v108, v108
	v_pk_add_f32 v[82:83], v[92:93], v[82:83]
	v_pk_add_f32 v[92:93], v[86:87], v[108:109]
	v_mul_f32_e32 v111, v110, v110
	v_mul_f32_e32 v113, v112, v112
	v_pk_add_f32 v[82:83], v[92:93], v[82:83]
	v_pk_add_f32 v[92:93], v[110:111], v[112:113]
	s_nop 0
	v_pk_add_f32 v[92:93], v[92:93], v[82:83]
	ds_bpermute_b32 v114, v162, v92
	ds_bpermute_b32 v115, v162, v93
	v_cvt_pk_bf16_f32 v82, v105, v88
	v_cvt_pk_bf16_f32 v83, v90, v106
	global_store_dwordx4 v[98:99], v[80:83], off
	v_cvt_pk_bf16_f32 v84, v84, v100
	v_cvt_pk_bf16_f32 v85, v86, v110
	v_cvt_pk_bf16_f32 v86, v94, v102
	v_cvt_pk_bf16_f32 v87, v108, v112
	global_store_dwordx4 v[98:99], v[84:87], off offset:256
	s_waitcnt lgkmcnt(0)
	v_pk_add_f32 v[80:81], v[92:93], v[114:115]
	ds_bpermute_b32 v82, v163, v80
	ds_bpermute_b32 v83, v163, v81
	s_and_saveexec_b64 s[48:49], s[46:47]
	s_cbranch_execz .LBB0_187
	s_lshl_b32 s14, s12, 2
	v_lshlrev_b64 v[84:85], 5, v[96:97]
	s_sub_i32 s14, s14, 32
	v_lshl_add_u64 v[84:85], v[84:85], 0, s[14:15]
	v_or_b32_e32 v84, s56, v84
	v_lshl_add_u64 v[84:85], v[84:85], 3, s[20:21]
	s_waitcnt lgkmcnt(0)
	v_pk_add_f32 v[80:81], v[80:81], v[82:83]
	global_store_dwordx2 v[84:85], v[80:81], off
.LBB0_187:
	s_or_b64 exec, exec, s[48:49]
	v_or_b32_e32 v80, 48, v150
	v_ashrrev_i32_e32 v81, 31, v80
	s_waitcnt lgkmcnt(0)
	v_lshlrev_b64 v[82:83], 7, v[80:81]
	v_lshl_add_u64 v[86:87], v[138:139], 0, v[82:83]
	global_load_dwordx4 v[82:85], v[86:87], off
	s_nop 0
	global_load_dwordx4 v[86:89], v[86:87], off offset:16
	s_waitcnt vmcnt(1)
	v_mov_b32_e32 v90, v82
	s_waitcnt vmcnt(0)
	v_mov_b32_e32 v91, v86
	v_mov_b32_e32 v86, v83
	v_mov_b32_e32 v82, v84
	v_mov_b32_e32 v83, v88
	v_mov_b32_e32 v88, v85
	v_pk_add_f32 v[84:85], v[90:91], v[86:87]
	v_pk_add_f32 v[82:83], v[82:83], v[88:89]
	s_nop 0
	v_pk_add_f32 v[82:83], v[84:85], v[82:83]
	s_nop 0
	v_add_f32_e32 v82, 0, v82
	v_add_f32_e32 v82, v82, v83
	ds_bpermute_b32 v83, v162, v82
	s_waitcnt lgkmcnt(0)
	v_add_f32_e32 v82, v82, v83
	ds_bpermute_b32 v83, v163, v82
	s_waitcnt lgkmcnt(0)
	v_add_f32_e32 v82, v82, v83
	v_fmamk_f32 v82, v82, 0x3a000000, v161
	v_rsq_f32_e32 v84, v82
	v_lshlrev_b64 v[82:83], 13, v[80:81]
	v_lshl_add_u64 v[82:83], s[18:19], 0, v[82:83]
	v_lshl_add_u64 v[82:83], v[148:149], 1, v[82:83]
	v_pk_mul_f32 v[76:77], v[76:77], v[84:85] op_sel_hi:[1,0]
	v_pk_mul_f32 v[72:73], v[72:73], v[84:85] op_sel_hi:[1,0]
	v_mul_f32_e32 v86, 0x3d122279, v76
	v_mul_f32_e32 v87, 0x3d122279, v72
	v_mul_f32_e32 v88, 0x3d122279, v77
	v_mul_f32_e32 v89, 0x3d122279, v73
	v_fmaak_f32 v86, v76, v86, 0x3f4c422a
	v_fmaak_f32 v87, v72, v87, 0x3f4c422a
	v_pk_mul_f32 v[78:79], v[78:79], v[84:85] op_sel_hi:[1,0]
	v_pk_mul_f32 v[74:75], v[74:75], v[84:85] op_sel_hi:[1,0]
	v_pk_mul_f32 v[70:71], v[70:71], v[84:85] op_sel_hi:[1,0]
	v_pk_mul_f32 v[68:69], v[68:69], v[84:85] op_sel_hi:[1,0]
	v_pk_mul_f32 v[66:67], v[66:67], v[84:85] op_sel_hi:[1,0]
	v_pk_mul_f32 v[84:85], v[64:65], v[84:85] op_sel_hi:[1,0]
	v_mov_b32_e32 v64, v76
	v_mov_b32_e32 v65, v72
	v_fmaak_f32 v88, v77, v88, 0x3f4c422a
	v_fmaak_f32 v89, v73, v89, 0x3f4c422a
	v_mul_f32_e32 v76, v76, v86
	v_mul_f32_e32 v72, v72, v87
	v_mul_f32_e32 v86, v77, v88
	v_mul_f32_e32 v87, v73, v89
	v_add_f32_e32 v76, v76, v76
	v_add_f32_e32 v72, v72, v72
	v_mul_f32_e32 v90, 0x3d122279, v78
	v_mul_f32_e32 v91, 0x3d122279, v74
	v_add_f32_e32 v86, v86, v86
	v_add_f32_e32 v87, v87, v87
	v_mul_f32_e32 v76, 0xbfb8aa3b, v76
	v_mul_f32_e32 v72, 0xbfb8aa3b, v72
	v_fmaak_f32 v90, v78, v90, 0x3f4c422a
	v_fmaak_f32 v91, v74, v91, 0x3f4c422a
	v_mul_f32_e32 v86, 0xbfb8aa3b, v86
	v_mul_f32_e32 v87, 0xbfb8aa3b, v87
	v_exp_f32_e32 v76, v76
	v_exp_f32_e32 v72, v72
	v_mul_f32_e32 v88, v78, v90
	v_mul_f32_e32 v89, v74, v91
	v_exp_f32_e32 v86, v86
	v_exp_f32_e32 v87, v87
	v_add_f32_e32 v88, v88, v88
	v_add_f32_e32 v89, v89, v89
	v_mul_f32_e32 v92, 0x3d122279, v79
	v_mul_f32_e32 v93, 0x3d122279, v75
	v_mul_f32_e32 v94, 0x3d122279, v68
	v_mul_f32_e32 v95, 0x3d122279, v84
	v_mul_f32_e32 v96, 0x3d122279, v69
	v_mul_f32_e32 v88, 0xbfb8aa3b, v88
	v_mul_f32_e32 v89, 0xbfb8aa3b, v89
	v_fmaak_f32 v92, v79, v92, 0x3f4c422a
	v_fmaak_f32 v93, v75, v93, 0x3f4c422a
	v_fmaak_f32 v94, v68, v94, 0x3f4c422a
	v_fmaak_f32 v95, v84, v95, 0x3f4c422a
	v_fmaak_f32 v96, v69, v96, 0x3f4c422a
	v_exp_f32_e32 v88, v88
	v_exp_f32_e32 v89, v89
	v_add_f32_e32 v76, 1.0, v76
	v_add_f32_e32 v72, 1.0, v72
	v_mul_f32_e32 v90, v79, v92
	v_mul_f32_e32 v91, v75, v93
	v_mul_f32_e32 v92, v68, v94
	v_mul_f32_e32 v93, v84, v95
	v_mul_f32_e32 v94, v69, v96
	v_add_f32_e32 v95, 1.0, v86
	v_add_f32_e32 v96, 1.0, v87
	v_rcp_f32_e32 v86, v76
	v_rcp_f32_e32 v87, v72
	v_add_f32_e32 v88, 1.0, v88
	v_add_f32_e32 v89, 1.0, v89
	v_rcp_f32_e32 v76, v95
	v_rcp_f32_e32 v72, v96
	v_rcp_f32_e32 v95, v88
	v_rcp_f32_e32 v96, v89
	v_pk_mul_f32 v[88:89], v[64:65], v[86:87]
	v_add_f32_e32 v94, v94, v94
	v_pk_fma_f32 v[64:65], v[64:65], v[86:87], v[88:89] op_sel:[0,0,1] op_sel_hi:[1,1,0]
	v_mul_f32_e32 v86, 0x3d122279, v85
	v_fmaak_f32 v86, v85, v86, 0x3f4c422a
	v_mul_f32_e32 v86, v85, v86
	v_mul_f32_e32 v65, 0xbfb8aa3b, v94
	v_add_f32_e32 v86, v86, v86
	v_exp_f32_e32 v65, v65
	v_mul_f32_e32 v86, 0xbfb8aa3b, v86
	v_exp_f32_e32 v86, v86
	v_mul_f32_e32 v87, 0x3d122279, v66
	v_add_f32_e32 v65, 1.0, v65
	v_rcp_f32_e32 v100, v65
	v_add_f32_e32 v65, 1.0, v86
	v_mul_f32_e32 v86, 0x3d122279, v70
	v_fmaak_f32 v86, v70, v86, 0x3f4c422a
	v_mul_f32_e32 v86, v70, v86
	v_fmaak_f32 v87, v66, v87, 0x3f4c422a
	v_add_f32_e32 v86, v86, v86
	v_mul_f32_e32 v87, v66, v87
	v_mul_f32_e32 v86, 0xbfb8aa3b, v86
	v_add_f32_e32 v87, v87, v87
	v_exp_f32_e32 v86, v86
	v_mul_f32_e32 v87, 0xbfb8aa3b, v87
	v_exp_f32_e32 v87, v87
	v_rcp_f32_e32 v101, v65
	v_add_f32_e32 v65, 1.0, v86
	v_mul_f32_e32 v86, 0x3d122279, v71
	v_add_f32_e32 v90, v90, v90
	v_add_f32_e32 v91, v91, v91
	v_add_f32_e32 v92, v92, v92
	v_add_f32_e32 v93, v93, v93
	v_rcp_f32_e32 v102, v65
	v_add_f32_e32 v65, 1.0, v87
	v_fmaak_f32 v86, v71, v86, 0x3f4c422a
	v_mul_f32_e32 v87, 0x3d122279, v67
	v_mul_f32_e32 v90, 0xbfb8aa3b, v90
	v_mul_f32_e32 v91, 0xbfb8aa3b, v91
	v_mul_f32_e32 v92, 0xbfb8aa3b, v92
	v_mul_f32_e32 v93, 0xbfb8aa3b, v93
	v_mul_f32_e32 v86, v71, v86
	v_fmaak_f32 v87, v67, v87, 0x3f4c422a
	v_exp_f32_e32 v90, v90
	v_exp_f32_e32 v91, v91
	v_exp_f32_e32 v92, v92
	v_exp_f32_e32 v93, v93
	v_add_f32_e32 v86, v86, v86
	v_mul_f32_e32 v87, v67, v87
	v_mul_f32_e32 v86, 0xbfb8aa3b, v86
	v_add_f32_e32 v87, v87, v87
	v_exp_f32_e32 v86, v86
	v_mul_f32_e32 v87, 0xbfb8aa3b, v87
	v_exp_f32_e32 v87, v87
	v_add_f32_e32 v90, 1.0, v90
	v_add_f32_e32 v91, 1.0, v91
	v_add_f32_e32 v92, 1.0, v92
	v_add_f32_e32 v93, 1.0, v93
	v_rcp_f32_e32 v90, v90
	v_rcp_f32_e32 v91, v91
	v_rcp_f32_e32 v98, v92
	v_rcp_f32_e32 v99, v93
	v_mul_f32_e32 v74, v74, v96
	v_mov_b32_e32 v92, v77
	v_mov_b32_e32 v93, v88
	v_mov_b32_e32 v77, v88
	v_mov_b32_e32 v96, v73
	v_mov_b32_e32 v97, v89
	v_mov_b32_e32 v73, v89
	v_rcp_f32_e32 v103, v65
	v_add_f32_e32 v65, 1.0, v86
	v_mul_f32_e32 v78, v78, v95
	v_pk_mul_f32 v[94:95], v[92:93], v[76:77]
	v_pk_mul_f32 v[72:73], v[96:97], v[72:73]
	v_rcp_f32_e32 v104, v65
	v_add_f32_e32 v65, 1.0, v87
	v_pk_fma_f32 v[76:77], v[92:93], v[76:77], v[72:73]
	v_pk_mul_f32 v[92:93], v[94:95], v[94:95]
	v_pk_mul_f32 v[96:97], v[72:73], v[72:73]
	v_rcp_f32_e32 v105, v65
	v_mov_b32_e32 v65, v92
	v_mov_b32_e32 v137, v96
	v_mul_f32_e32 v86, v79, v90
	v_mul_f32_e32 v90, v75, v91
	v_pk_add_f32 v[64:65], v[64:65], v[136:137]
	v_mul_f32_e32 v79, v78, v78
	v_mul_f32_e32 v75, v74, v74
	v_pk_add_f32 v[64:65], v[76:77], v[64:65]
	v_pk_add_f32 v[76:77], v[78:79], v[74:75]
	v_mul_f32_e32 v87, v86, v86
	v_mul_f32_e32 v91, v90, v90
	v_pk_add_f32 v[64:65], v[76:77], v[64:65]
	v_pk_add_f32 v[76:77], v[86:87], v[90:91]
	v_mul_f32_e32 v68, v68, v98
	v_pk_add_f32 v[76:77], v[76:77], v[64:65]
	v_cvt_pk_bf16_f32 v64, v88, v94
	v_cvt_pk_bf16_f32 v65, v78, v86
	v_mul_f32_e32 v78, v84, v99
	v_mul_f32_e32 v84, v69, v100
	v_mul_f32_e32 v86, v85, v101
	v_mul_f32_e32 v69, v68, v68
	v_mul_f32_e32 v79, v78, v78
	v_mul_f32_e32 v70, v70, v102
	v_mul_f32_e32 v92, v66, v103
	v_mul_f32_e32 v96, v67, v105
	v_pk_add_f32 v[66:67], v[68:69], v[78:79]
	v_mul_f32_e32 v85, v84, v84
	v_mul_f32_e32 v87, v86, v86
	v_mul_f32_e32 v94, v71, v104
	v_pk_add_f32 v[66:67], v[66:67], v[76:77]
	v_pk_add_f32 v[76:77], v[84:85], v[86:87]
	v_mul_f32_e32 v71, v70, v70
	v_mul_f32_e32 v93, v92, v92
	v_pk_add_f32 v[66:67], v[76:77], v[66:67]
	v_pk_add_f32 v[76:77], v[70:71], v[92:93]
	v_mul_f32_e32 v95, v94, v94
	v_mul_f32_e32 v97, v96, v96
	v_pk_add_f32 v[66:67], v[76:77], v[66:67]
	v_pk_add_f32 v[76:77], v[94:95], v[96:97]
	s_nop 0
	v_pk_add_f32 v[76:77], v[76:77], v[66:67]
	ds_bpermute_b32 v98, v162, v76
	ds_bpermute_b32 v99, v162, v77
	v_cvt_pk_bf16_f32 v66, v89, v72
	v_cvt_pk_bf16_f32 v67, v74, v90
	global_store_dwordx4 v[82:83], v[64:67], off
	v_cvt_pk_bf16_f32 v68, v68, v84
	v_cvt_pk_bf16_f32 v69, v70, v94
	v_cvt_pk_bf16_f32 v70, v78, v86
	v_cvt_pk_bf16_f32 v71, v92, v96
	global_store_dwordx4 v[82:83], v[68:71], off offset:256
	s_waitcnt lgkmcnt(0)
	v_pk_add_f32 v[64:65], v[76:77], v[98:99]
	ds_bpermute_b32 v66, v163, v64
	ds_bpermute_b32 v67, v163, v65
	s_and_saveexec_b64 s[48:49], s[46:47]
	s_cbranch_execz .LBB0_189
	s_lshl_b32 s14, s12, 2
	v_lshlrev_b64 v[68:69], 5, v[80:81]
	s_sub_i32 s14, s14, 32
	v_lshl_add_u64 v[68:69], v[68:69], 0, s[14:15]
	v_or_b32_e32 v68, s56, v68
	v_lshl_add_u64 v[68:69], v[68:69], 3, s[20:21]
	s_waitcnt lgkmcnt(0)
	v_pk_add_f32 v[64:65], v[64:65], v[66:67]
	global_store_dwordx2 v[68:69], v[64:65], off
.LBB0_189:
	s_or_b64 exec, exec, s[48:49]
	v_add_u32_e32 v64, 0x80, v150
	v_ashrrev_i32_e32 v65, 31, v64
	s_waitcnt lgkmcnt(0)
	v_lshlrev_b64 v[66:67], 7, v[64:65]
	v_lshl_add_u64 v[70:71], v[138:139], 0, v[66:67]
	global_load_dwordx4 v[66:69], v[70:71], off
	s_nop 0
	global_load_dwordx4 v[70:73], v[70:71], off offset:16
	s_waitcnt vmcnt(1)
	v_mov_b32_e32 v74, v66
	s_waitcnt vmcnt(0)
	v_mov_b32_e32 v75, v70
	v_mov_b32_e32 v70, v67
	v_mov_b32_e32 v66, v68
	v_mov_b32_e32 v67, v72
	v_mov_b32_e32 v72, v69
	v_pk_add_f32 v[68:69], v[74:75], v[70:71]
	v_pk_add_f32 v[66:67], v[66:67], v[72:73]
	s_nop 0
	v_pk_add_f32 v[66:67], v[68:69], v[66:67]
	s_nop 0
	v_add_f32_e32 v66, 0, v66
	v_add_f32_e32 v66, v66, v67
	ds_bpermute_b32 v67, v162, v66
	s_waitcnt lgkmcnt(0)
	v_add_f32_e32 v66, v66, v67
	ds_bpermute_b32 v67, v163, v66
	s_waitcnt lgkmcnt(0)
	v_add_f32_e32 v66, v66, v67
	v_fmamk_f32 v66, v66, 0x3a000000, v161
	v_rsq_f32_e32 v68, v66
	v_lshlrev_b64 v[66:67], 13, v[64:65]
	v_lshl_add_u64 v[66:67], s[18:19], 0, v[66:67]
	v_lshl_add_u64 v[66:67], v[148:149], 1, v[66:67]
	v_pk_mul_f32 v[60:61], v[60:61], v[68:69] op_sel_hi:[1,0]
	v_pk_mul_f32 v[56:57], v[56:57], v[68:69] op_sel_hi:[1,0]
	v_mul_f32_e32 v70, 0x3d122279, v60
	v_mul_f32_e32 v71, 0x3d122279, v56
	v_mul_f32_e32 v72, 0x3d122279, v61
	v_mul_f32_e32 v73, 0x3d122279, v57
	v_fmaak_f32 v70, v60, v70, 0x3f4c422a
	v_fmaak_f32 v71, v56, v71, 0x3f4c422a
	v_pk_mul_f32 v[62:63], v[62:63], v[68:69] op_sel_hi:[1,0]
	v_pk_mul_f32 v[58:59], v[58:59], v[68:69] op_sel_hi:[1,0]
	v_pk_mul_f32 v[54:55], v[54:55], v[68:69] op_sel_hi:[1,0]
	v_pk_mul_f32 v[52:53], v[52:53], v[68:69] op_sel_hi:[1,0]
	v_pk_mul_f32 v[50:51], v[50:51], v[68:69] op_sel_hi:[1,0]
	v_pk_mul_f32 v[68:69], v[48:49], v[68:69] op_sel_hi:[1,0]
	v_mov_b32_e32 v48, v60
	v_mov_b32_e32 v49, v56
	v_fmaak_f32 v72, v61, v72, 0x3f4c422a
	v_fmaak_f32 v73, v57, v73, 0x3f4c422a
	v_mul_f32_e32 v60, v60, v70
	v_mul_f32_e32 v56, v56, v71
	v_mul_f32_e32 v70, v61, v72
	v_mul_f32_e32 v71, v57, v73
	v_add_f32_e32 v60, v60, v60
	v_add_f32_e32 v56, v56, v56
	v_mul_f32_e32 v74, 0x3d122279, v62
	v_mul_f32_e32 v75, 0x3d122279, v58
	v_add_f32_e32 v70, v70, v70
	v_add_f32_e32 v71, v71, v71
	v_mul_f32_e32 v60, 0xbfb8aa3b, v60
	v_mul_f32_e32 v56, 0xbfb8aa3b, v56
	v_fmaak_f32 v74, v62, v74, 0x3f4c422a
	v_fmaak_f32 v75, v58, v75, 0x3f4c422a
	v_mul_f32_e32 v70, 0xbfb8aa3b, v70
	v_mul_f32_e32 v71, 0xbfb8aa3b, v71
	v_exp_f32_e32 v60, v60
	v_exp_f32_e32 v56, v56
	v_mul_f32_e32 v72, v62, v74
	v_mul_f32_e32 v73, v58, v75
	v_exp_f32_e32 v70, v70
	v_exp_f32_e32 v71, v71
	v_add_f32_e32 v72, v72, v72
	v_add_f32_e32 v73, v73, v73
	v_mul_f32_e32 v76, 0x3d122279, v63
	v_mul_f32_e32 v77, 0x3d122279, v59
	v_mul_f32_e32 v78, 0x3d122279, v52
	v_mul_f32_e32 v79, 0x3d122279, v68
	v_mul_f32_e32 v80, 0x3d122279, v53
	v_mul_f32_e32 v72, 0xbfb8aa3b, v72
	v_mul_f32_e32 v73, 0xbfb8aa3b, v73
	v_fmaak_f32 v76, v63, v76, 0x3f4c422a
	v_fmaak_f32 v77, v59, v77, 0x3f4c422a
	v_fmaak_f32 v78, v52, v78, 0x3f4c422a
	v_fmaak_f32 v79, v68, v79, 0x3f4c422a
	v_fmaak_f32 v80, v53, v80, 0x3f4c422a
	v_exp_f32_e32 v72, v72
	v_exp_f32_e32 v73, v73
	v_add_f32_e32 v60, 1.0, v60
	v_add_f32_e32 v56, 1.0, v56
	v_mul_f32_e32 v74, v63, v76
	v_mul_f32_e32 v75, v59, v77
	v_mul_f32_e32 v76, v52, v78
	v_mul_f32_e32 v77, v68, v79
	v_mul_f32_e32 v78, v53, v80
	v_add_f32_e32 v79, 1.0, v70
	v_add_f32_e32 v80, 1.0, v71
	v_rcp_f32_e32 v70, v60
	v_rcp_f32_e32 v71, v56
	v_add_f32_e32 v72, 1.0, v72
	v_add_f32_e32 v73, 1.0, v73
	v_rcp_f32_e32 v60, v79
	v_rcp_f32_e32 v56, v80
	v_rcp_f32_e32 v79, v72
	v_rcp_f32_e32 v80, v73
	v_pk_mul_f32 v[72:73], v[48:49], v[70:71]
	v_add_f32_e32 v78, v78, v78
	v_pk_fma_f32 v[48:49], v[48:49], v[70:71], v[72:73] op_sel:[0,0,1] op_sel_hi:[1,1,0]
	v_mul_f32_e32 v70, 0x3d122279, v69
	v_fmaak_f32 v70, v69, v70, 0x3f4c422a
	v_mul_f32_e32 v70, v69, v70
	v_mul_f32_e32 v49, 0xbfb8aa3b, v78
	v_add_f32_e32 v70, v70, v70
	v_exp_f32_e32 v49, v49
	v_mul_f32_e32 v70, 0xbfb8aa3b, v70
	v_exp_f32_e32 v70, v70
	v_mul_f32_e32 v71, 0x3d122279, v50
	v_add_f32_e32 v49, 1.0, v49
	v_rcp_f32_e32 v84, v49
	v_add_f32_e32 v49, 1.0, v70
	v_mul_f32_e32 v70, 0x3d122279, v54
	v_fmaak_f32 v70, v54, v70, 0x3f4c422a
	v_mul_f32_e32 v70, v54, v70
	v_fmaak_f32 v71, v50, v71, 0x3f4c422a
	v_add_f32_e32 v70, v70, v70
	v_mul_f32_e32 v71, v50, v71
	v_mul_f32_e32 v70, 0xbfb8aa3b, v70
	v_add_f32_e32 v71, v71, v71
	v_exp_f32_e32 v70, v70
	v_mul_f32_e32 v71, 0xbfb8aa3b, v71
	v_exp_f32_e32 v71, v71
	v_rcp_f32_e32 v85, v49
	v_add_f32_e32 v49, 1.0, v70
	v_mul_f32_e32 v70, 0x3d122279, v55
	v_add_f32_e32 v74, v74, v74
	v_add_f32_e32 v75, v75, v75
	v_add_f32_e32 v76, v76, v76
	v_add_f32_e32 v77, v77, v77
	v_rcp_f32_e32 v86, v49
	v_add_f32_e32 v49, 1.0, v71
	v_fmaak_f32 v70, v55, v70, 0x3f4c422a
	v_mul_f32_e32 v71, 0x3d122279, v51
	v_mul_f32_e32 v74, 0xbfb8aa3b, v74
	v_mul_f32_e32 v75, 0xbfb8aa3b, v75
	v_mul_f32_e32 v76, 0xbfb8aa3b, v76
	v_mul_f32_e32 v77, 0xbfb8aa3b, v77
	v_mul_f32_e32 v70, v55, v70
	v_fmaak_f32 v71, v51, v71, 0x3f4c422a
	v_exp_f32_e32 v74, v74
	v_exp_f32_e32 v75, v75
	v_exp_f32_e32 v76, v76
	v_exp_f32_e32 v77, v77
	v_add_f32_e32 v70, v70, v70
	v_mul_f32_e32 v71, v51, v71
	v_mul_f32_e32 v70, 0xbfb8aa3b, v70
	v_add_f32_e32 v71, v71, v71
	v_exp_f32_e32 v70, v70
	v_mul_f32_e32 v71, 0xbfb8aa3b, v71
	v_exp_f32_e32 v71, v71
	v_add_f32_e32 v74, 1.0, v74
	v_add_f32_e32 v75, 1.0, v75
	v_add_f32_e32 v76, 1.0, v76
	v_add_f32_e32 v77, 1.0, v77
	v_rcp_f32_e32 v74, v74
	v_rcp_f32_e32 v75, v75
	v_rcp_f32_e32 v82, v76
	v_rcp_f32_e32 v83, v77
	v_mul_f32_e32 v58, v58, v80
	v_mov_b32_e32 v76, v61
	v_mov_b32_e32 v77, v72
	v_mov_b32_e32 v61, v72
	v_mov_b32_e32 v80, v57
	v_mov_b32_e32 v81, v73
	v_mov_b32_e32 v57, v73
	v_rcp_f32_e32 v87, v49
	v_add_f32_e32 v49, 1.0, v70
	v_mul_f32_e32 v62, v62, v79
	v_pk_mul_f32 v[78:79], v[76:77], v[60:61]
	v_pk_mul_f32 v[56:57], v[80:81], v[56:57]
	v_rcp_f32_e32 v88, v49
	v_add_f32_e32 v49, 1.0, v71
	v_pk_fma_f32 v[60:61], v[76:77], v[60:61], v[56:57]
	v_pk_mul_f32 v[76:77], v[78:79], v[78:79]
	v_pk_mul_f32 v[80:81], v[56:57], v[56:57]
	v_rcp_f32_e32 v89, v49
	v_mov_b32_e32 v49, v76
	v_mov_b32_e32 v137, v80
	v_mul_f32_e32 v70, v63, v74
	v_mul_f32_e32 v74, v59, v75
	v_pk_add_f32 v[48:49], v[48:49], v[136:137]
	v_mul_f32_e32 v63, v62, v62
	v_mul_f32_e32 v59, v58, v58
	v_pk_add_f32 v[48:49], v[60:61], v[48:49]
	v_pk_add_f32 v[60:61], v[62:63], v[58:59]
	v_mul_f32_e32 v71, v70, v70
	v_mul_f32_e32 v75, v74, v74
	v_pk_add_f32 v[48:49], v[60:61], v[48:49]
	v_pk_add_f32 v[60:61], v[70:71], v[74:75]
	v_mul_f32_e32 v52, v52, v82
	v_pk_add_f32 v[60:61], v[60:61], v[48:49]
	v_cvt_pk_bf16_f32 v48, v72, v78
	v_cvt_pk_bf16_f32 v49, v62, v70
	v_mul_f32_e32 v62, v68, v83
	v_mul_f32_e32 v68, v53, v84
	v_mul_f32_e32 v70, v69, v85
	v_mul_f32_e32 v53, v52, v52
	v_mul_f32_e32 v63, v62, v62
	v_mul_f32_e32 v54, v54, v86
	v_mul_f32_e32 v76, v50, v87
	v_mul_f32_e32 v80, v51, v89
	v_pk_add_f32 v[50:51], v[52:53], v[62:63]
	v_mul_f32_e32 v69, v68, v68
	v_mul_f32_e32 v71, v70, v70
	v_mul_f32_e32 v78, v55, v88
	v_pk_add_f32 v[50:51], v[50:51], v[60:61]
	v_pk_add_f32 v[60:61], v[68:69], v[70:71]
	v_mul_f32_e32 v55, v54, v54
	v_mul_f32_e32 v77, v76, v76
	v_pk_add_f32 v[50:51], v[60:61], v[50:51]
	v_pk_add_f32 v[60:61], v[54:55], v[76:77]
	v_mul_f32_e32 v79, v78, v78
	v_mul_f32_e32 v81, v80, v80
	v_pk_add_f32 v[50:51], v[60:61], v[50:51]
	v_pk_add_f32 v[60:61], v[78:79], v[80:81]
	s_nop 0
	v_pk_add_f32 v[60:61], v[60:61], v[50:51]
	ds_bpermute_b32 v82, v162, v60
	ds_bpermute_b32 v83, v162, v61
	v_cvt_pk_bf16_f32 v50, v73, v56
	v_cvt_pk_bf16_f32 v51, v58, v74
	global_store_dwordx4 v[66:67], v[48:51], off
	v_cvt_pk_bf16_f32 v52, v52, v68
	v_cvt_pk_bf16_f32 v53, v54, v78
	v_cvt_pk_bf16_f32 v54, v62, v70
	v_cvt_pk_bf16_f32 v55, v76, v80
	global_store_dwordx4 v[66:67], v[52:55], off offset:256
	s_waitcnt lgkmcnt(0)
	v_pk_add_f32 v[48:49], v[60:61], v[82:83]
	ds_bpermute_b32 v50, v163, v48
	ds_bpermute_b32 v51, v163, v49
	s_and_saveexec_b64 s[48:49], s[46:47]
	s_cbranch_execz .LBB0_191
	s_lshl_b32 s14, s12, 2
	v_lshlrev_b64 v[52:53], 5, v[64:65]
	s_sub_i32 s14, s14, 32
	v_lshl_add_u64 v[52:53], v[52:53], 0, s[14:15]
	v_or_b32_e32 v52, s56, v52
	v_lshl_add_u64 v[52:53], v[52:53], 3, s[20:21]
	s_waitcnt lgkmcnt(0)
	v_pk_add_f32 v[48:49], v[48:49], v[50:51]
	global_store_dwordx2 v[52:53], v[48:49], off
.LBB0_191:
	s_or_b64 exec, exec, s[48:49]
	v_add_u32_e32 v48, 0x90, v150
	v_ashrrev_i32_e32 v49, 31, v48
	s_waitcnt lgkmcnt(0)
	v_lshlrev_b64 v[50:51], 7, v[48:49]
	v_lshl_add_u64 v[54:55], v[138:139], 0, v[50:51]
	global_load_dwordx4 v[50:53], v[54:55], off
	s_nop 0
	global_load_dwordx4 v[54:57], v[54:55], off offset:16
	s_waitcnt vmcnt(1)
	v_mov_b32_e32 v58, v50
	s_waitcnt vmcnt(0)
	v_mov_b32_e32 v59, v54
	v_mov_b32_e32 v54, v51
	v_mov_b32_e32 v50, v52
	v_mov_b32_e32 v51, v56
	v_mov_b32_e32 v56, v53
	v_pk_add_f32 v[52:53], v[58:59], v[54:55]
	v_pk_add_f32 v[50:51], v[50:51], v[56:57]
	s_nop 0
	v_pk_add_f32 v[50:51], v[52:53], v[50:51]
	s_nop 0
	v_add_f32_e32 v50, 0, v50
	v_add_f32_e32 v50, v50, v51
	ds_bpermute_b32 v51, v162, v50
	s_waitcnt lgkmcnt(0)
	v_add_f32_e32 v50, v50, v51
	ds_bpermute_b32 v51, v163, v50
	s_waitcnt lgkmcnt(0)
	v_add_f32_e32 v50, v50, v51
	v_fmamk_f32 v50, v50, 0x3a000000, v161
	v_rsq_f32_e32 v52, v50
	v_lshlrev_b64 v[50:51], 13, v[48:49]
	v_lshl_add_u64 v[50:51], s[18:19], 0, v[50:51]
	v_lshl_add_u64 v[50:51], v[148:149], 1, v[50:51]
	v_pk_mul_f32 v[44:45], v[44:45], v[52:53] op_sel_hi:[1,0]
	v_pk_mul_f32 v[40:41], v[40:41], v[52:53] op_sel_hi:[1,0]
	v_mul_f32_e32 v54, 0x3d122279, v44
	v_mul_f32_e32 v55, 0x3d122279, v40
	v_mul_f32_e32 v56, 0x3d122279, v45
	v_mul_f32_e32 v57, 0x3d122279, v41
	v_fmaak_f32 v54, v44, v54, 0x3f4c422a
	v_fmaak_f32 v55, v40, v55, 0x3f4c422a
	v_pk_mul_f32 v[46:47], v[46:47], v[52:53] op_sel_hi:[1,0]
	v_pk_mul_f32 v[42:43], v[42:43], v[52:53] op_sel_hi:[1,0]
	v_pk_mul_f32 v[38:39], v[38:39], v[52:53] op_sel_hi:[1,0]
	v_pk_mul_f32 v[36:37], v[36:37], v[52:53] op_sel_hi:[1,0]
	v_pk_mul_f32 v[34:35], v[34:35], v[52:53] op_sel_hi:[1,0]
	v_pk_mul_f32 v[52:53], v[32:33], v[52:53] op_sel_hi:[1,0]
	v_mov_b32_e32 v32, v44
	v_mov_b32_e32 v33, v40
	v_fmaak_f32 v56, v45, v56, 0x3f4c422a
	v_fmaak_f32 v57, v41, v57, 0x3f4c422a
	v_mul_f32_e32 v44, v44, v54
	v_mul_f32_e32 v40, v40, v55
	v_mul_f32_e32 v54, v45, v56
	v_mul_f32_e32 v55, v41, v57
	v_add_f32_e32 v44, v44, v44
	v_add_f32_e32 v40, v40, v40
	v_mul_f32_e32 v58, 0x3d122279, v46
	v_mul_f32_e32 v59, 0x3d122279, v42
	v_add_f32_e32 v54, v54, v54
	v_add_f32_e32 v55, v55, v55
	v_mul_f32_e32 v44, 0xbfb8aa3b, v44
	v_mul_f32_e32 v40, 0xbfb8aa3b, v40
	v_fmaak_f32 v58, v46, v58, 0x3f4c422a
	v_fmaak_f32 v59, v42, v59, 0x3f4c422a
	v_mul_f32_e32 v54, 0xbfb8aa3b, v54
	v_mul_f32_e32 v55, 0xbfb8aa3b, v55
	v_exp_f32_e32 v44, v44
	v_exp_f32_e32 v40, v40
	v_mul_f32_e32 v56, v46, v58
	v_mul_f32_e32 v57, v42, v59
	v_exp_f32_e32 v54, v54
	v_exp_f32_e32 v55, v55
	v_add_f32_e32 v56, v56, v56
	v_add_f32_e32 v57, v57, v57
	v_mul_f32_e32 v60, 0x3d122279, v47
	v_mul_f32_e32 v61, 0x3d122279, v43
	v_mul_f32_e32 v62, 0x3d122279, v36
	v_mul_f32_e32 v63, 0x3d122279, v52
	v_mul_f32_e32 v64, 0x3d122279, v37
	v_mul_f32_e32 v56, 0xbfb8aa3b, v56
	v_mul_f32_e32 v57, 0xbfb8aa3b, v57
	v_fmaak_f32 v60, v47, v60, 0x3f4c422a
	v_fmaak_f32 v61, v43, v61, 0x3f4c422a
	v_fmaak_f32 v62, v36, v62, 0x3f4c422a
	v_fmaak_f32 v63, v52, v63, 0x3f4c422a
	v_fmaak_f32 v64, v37, v64, 0x3f4c422a
	v_exp_f32_e32 v56, v56
	v_exp_f32_e32 v57, v57
	v_add_f32_e32 v44, 1.0, v44
	v_add_f32_e32 v40, 1.0, v40
	v_mul_f32_e32 v58, v47, v60
	v_mul_f32_e32 v59, v43, v61
	v_mul_f32_e32 v60, v36, v62
	v_mul_f32_e32 v61, v52, v63
	v_mul_f32_e32 v62, v37, v64
	v_add_f32_e32 v63, 1.0, v54
	v_add_f32_e32 v64, 1.0, v55
	v_rcp_f32_e32 v54, v44
	v_rcp_f32_e32 v55, v40
	v_add_f32_e32 v56, 1.0, v56
	v_add_f32_e32 v57, 1.0, v57
	v_rcp_f32_e32 v44, v63
	v_rcp_f32_e32 v40, v64
	v_rcp_f32_e32 v63, v56
	v_rcp_f32_e32 v64, v57
	v_pk_mul_f32 v[56:57], v[32:33], v[54:55]
	v_add_f32_e32 v62, v62, v62
	v_pk_fma_f32 v[32:33], v[32:33], v[54:55], v[56:57] op_sel:[0,0,1] op_sel_hi:[1,1,0]
	v_mul_f32_e32 v54, 0x3d122279, v53
	v_fmaak_f32 v54, v53, v54, 0x3f4c422a
	v_mul_f32_e32 v54, v53, v54
	v_mul_f32_e32 v33, 0xbfb8aa3b, v62
	v_add_f32_e32 v54, v54, v54
	v_exp_f32_e32 v33, v33
	v_mul_f32_e32 v54, 0xbfb8aa3b, v54
	v_exp_f32_e32 v54, v54
	v_mul_f32_e32 v55, 0x3d122279, v34
	v_add_f32_e32 v33, 1.0, v33
	v_rcp_f32_e32 v68, v33
	v_add_f32_e32 v33, 1.0, v54
	v_mul_f32_e32 v54, 0x3d122279, v38
	v_fmaak_f32 v54, v38, v54, 0x3f4c422a
	v_mul_f32_e32 v54, v38, v54
	v_fmaak_f32 v55, v34, v55, 0x3f4c422a
	v_add_f32_e32 v54, v54, v54
	v_mul_f32_e32 v55, v34, v55
	v_mul_f32_e32 v54, 0xbfb8aa3b, v54
	v_add_f32_e32 v55, v55, v55
	v_exp_f32_e32 v54, v54
	v_mul_f32_e32 v55, 0xbfb8aa3b, v55
	v_exp_f32_e32 v55, v55
	v_rcp_f32_e32 v69, v33
	v_add_f32_e32 v33, 1.0, v54
	v_mul_f32_e32 v54, 0x3d122279, v39
	v_add_f32_e32 v58, v58, v58
	v_add_f32_e32 v59, v59, v59
	v_add_f32_e32 v60, v60, v60
	v_add_f32_e32 v61, v61, v61
	v_rcp_f32_e32 v70, v33
	v_add_f32_e32 v33, 1.0, v55
	v_fmaak_f32 v54, v39, v54, 0x3f4c422a
	v_mul_f32_e32 v55, 0x3d122279, v35
	v_mul_f32_e32 v58, 0xbfb8aa3b, v58
	v_mul_f32_e32 v59, 0xbfb8aa3b, v59
	v_mul_f32_e32 v60, 0xbfb8aa3b, v60
	v_mul_f32_e32 v61, 0xbfb8aa3b, v61
	v_mul_f32_e32 v54, v39, v54
	v_fmaak_f32 v55, v35, v55, 0x3f4c422a
	v_exp_f32_e32 v58, v58
	v_exp_f32_e32 v59, v59
	v_exp_f32_e32 v60, v60
	v_exp_f32_e32 v61, v61
	v_add_f32_e32 v54, v54, v54
	v_mul_f32_e32 v55, v35, v55
	v_mul_f32_e32 v54, 0xbfb8aa3b, v54
	v_add_f32_e32 v55, v55, v55
	v_exp_f32_e32 v54, v54
	v_mul_f32_e32 v55, 0xbfb8aa3b, v55
	v_exp_f32_e32 v55, v55
	v_add_f32_e32 v58, 1.0, v58
	v_add_f32_e32 v59, 1.0, v59
	v_add_f32_e32 v60, 1.0, v60
	v_add_f32_e32 v61, 1.0, v61
	v_rcp_f32_e32 v58, v58
	v_rcp_f32_e32 v59, v59
	v_rcp_f32_e32 v66, v60
	v_rcp_f32_e32 v67, v61
	v_mul_f32_e32 v42, v42, v64
	v_mov_b32_e32 v60, v45
	v_mov_b32_e32 v61, v56
	v_mov_b32_e32 v45, v56
	v_mov_b32_e32 v64, v41
	v_mov_b32_e32 v65, v57
	v_mov_b32_e32 v41, v57
	v_rcp_f32_e32 v71, v33
	v_add_f32_e32 v33, 1.0, v54
	v_mul_f32_e32 v46, v46, v63
	v_pk_mul_f32 v[62:63], v[60:61], v[44:45]
	v_pk_mul_f32 v[40:41], v[64:65], v[40:41]
	v_rcp_f32_e32 v72, v33
	v_add_f32_e32 v33, 1.0, v55
	v_pk_fma_f32 v[44:45], v[60:61], v[44:45], v[40:41]
	v_pk_mul_f32 v[60:61], v[62:63], v[62:63]
	v_pk_mul_f32 v[64:65], v[40:41], v[40:41]
	v_rcp_f32_e32 v73, v33
	v_mov_b32_e32 v33, v60
	v_mov_b32_e32 v137, v64
	v_mul_f32_e32 v54, v47, v58
	v_mul_f32_e32 v58, v43, v59
	v_pk_add_f32 v[32:33], v[32:33], v[136:137]
	v_mul_f32_e32 v47, v46, v46
	v_mul_f32_e32 v43, v42, v42
	v_pk_add_f32 v[32:33], v[44:45], v[32:33]
	v_pk_add_f32 v[44:45], v[46:47], v[42:43]
	v_mul_f32_e32 v55, v54, v54
	v_mul_f32_e32 v59, v58, v58
	v_pk_add_f32 v[32:33], v[44:45], v[32:33]
	v_pk_add_f32 v[44:45], v[54:55], v[58:59]
	v_mul_f32_e32 v36, v36, v66
	v_pk_add_f32 v[44:45], v[44:45], v[32:33]
	v_cvt_pk_bf16_f32 v32, v56, v62
	v_cvt_pk_bf16_f32 v33, v46, v54
	v_mul_f32_e32 v46, v52, v67
	v_mul_f32_e32 v52, v37, v68
	v_mul_f32_e32 v54, v53, v69
	v_mul_f32_e32 v37, v36, v36
	v_mul_f32_e32 v47, v46, v46
	v_mul_f32_e32 v38, v38, v70
	v_mul_f32_e32 v60, v34, v71
	v_mul_f32_e32 v64, v35, v73
	v_pk_add_f32 v[34:35], v[36:37], v[46:47]
	v_mul_f32_e32 v53, v52, v52
	v_mul_f32_e32 v55, v54, v54
	v_mul_f32_e32 v62, v39, v72
	v_pk_add_f32 v[34:35], v[34:35], v[44:45]
	v_pk_add_f32 v[44:45], v[52:53], v[54:55]
	v_mul_f32_e32 v39, v38, v38
	v_mul_f32_e32 v61, v60, v60
	v_pk_add_f32 v[34:35], v[44:45], v[34:35]
	v_pk_add_f32 v[44:45], v[38:39], v[60:61]
	v_mul_f32_e32 v63, v62, v62
	v_mul_f32_e32 v65, v64, v64
	v_pk_add_f32 v[34:35], v[44:45], v[34:35]
	v_pk_add_f32 v[44:45], v[62:63], v[64:65]
	s_nop 0
	v_pk_add_f32 v[44:45], v[44:45], v[34:35]
	ds_bpermute_b32 v66, v162, v44
	ds_bpermute_b32 v67, v162, v45
	v_cvt_pk_bf16_f32 v34, v57, v40
	v_cvt_pk_bf16_f32 v35, v42, v58
	global_store_dwordx4 v[50:51], v[32:35], off
	v_cvt_pk_bf16_f32 v36, v36, v52
	v_cvt_pk_bf16_f32 v37, v38, v62
	v_cvt_pk_bf16_f32 v38, v46, v54
	v_cvt_pk_bf16_f32 v39, v60, v64
	global_store_dwordx4 v[50:51], v[36:39], off offset:256
	s_waitcnt lgkmcnt(0)
	v_pk_add_f32 v[32:33], v[44:45], v[66:67]
	ds_bpermute_b32 v34, v163, v32
	ds_bpermute_b32 v35, v163, v33
	s_and_saveexec_b64 s[48:49], s[46:47]
	s_cbranch_execz .LBB0_193
	s_lshl_b32 s14, s12, 2
	v_lshlrev_b64 v[36:37], 5, v[48:49]
	s_sub_i32 s14, s14, 32
	v_lshl_add_u64 v[36:37], v[36:37], 0, s[14:15]
	v_or_b32_e32 v36, s56, v36
	v_lshl_add_u64 v[36:37], v[36:37], 3, s[20:21]
	s_waitcnt lgkmcnt(0)
	v_pk_add_f32 v[32:33], v[32:33], v[34:35]
	global_store_dwordx2 v[36:37], v[32:33], off
.LBB0_193:
	s_or_b64 exec, exec, s[48:49]
	v_add_u32_e32 v32, 0xa0, v150
	v_ashrrev_i32_e32 v33, 31, v32
	s_waitcnt lgkmcnt(0)
	v_lshlrev_b64 v[34:35], 7, v[32:33]
	v_lshl_add_u64 v[38:39], v[138:139], 0, v[34:35]
	global_load_dwordx4 v[34:37], v[38:39], off
	s_nop 0
	global_load_dwordx4 v[38:41], v[38:39], off offset:16
	s_waitcnt vmcnt(1)
	v_mov_b32_e32 v42, v34
	s_waitcnt vmcnt(0)
	v_mov_b32_e32 v43, v38
	v_mov_b32_e32 v38, v35
	v_mov_b32_e32 v34, v36
	v_mov_b32_e32 v35, v40
	v_mov_b32_e32 v40, v37
	v_pk_add_f32 v[36:37], v[42:43], v[38:39]
	v_pk_add_f32 v[34:35], v[34:35], v[40:41]
	s_nop 0
	v_pk_add_f32 v[34:35], v[36:37], v[34:35]
	s_nop 0
	v_add_f32_e32 v34, 0, v34
	v_add_f32_e32 v34, v34, v35
	ds_bpermute_b32 v35, v162, v34
	s_waitcnt lgkmcnt(0)
	v_add_f32_e32 v34, v34, v35
	ds_bpermute_b32 v35, v163, v34
	s_waitcnt lgkmcnt(0)
	v_add_f32_e32 v34, v34, v35
	v_fmamk_f32 v34, v34, 0x3a000000, v161
	v_rsq_f32_e32 v36, v34
	v_lshlrev_b64 v[34:35], 13, v[32:33]
	v_lshl_add_u64 v[34:35], s[18:19], 0, v[34:35]
	v_lshl_add_u64 v[34:35], v[148:149], 1, v[34:35]
	v_pk_mul_f32 v[28:29], v[28:29], v[36:37] op_sel_hi:[1,0]
	v_pk_mul_f32 v[24:25], v[24:25], v[36:37] op_sel_hi:[1,0]
	v_mul_f32_e32 v38, 0x3d122279, v28
	v_mul_f32_e32 v39, 0x3d122279, v24
	v_mul_f32_e32 v40, 0x3d122279, v29
	v_mul_f32_e32 v41, 0x3d122279, v25
	v_fmaak_f32 v38, v28, v38, 0x3f4c422a
	v_fmaak_f32 v39, v24, v39, 0x3f4c422a
	v_pk_mul_f32 v[30:31], v[30:31], v[36:37] op_sel_hi:[1,0]
	v_pk_mul_f32 v[26:27], v[26:27], v[36:37] op_sel_hi:[1,0]
	v_pk_mul_f32 v[22:23], v[22:23], v[36:37] op_sel_hi:[1,0]
	v_pk_mul_f32 v[20:21], v[20:21], v[36:37] op_sel_hi:[1,0]
	v_pk_mul_f32 v[18:19], v[18:19], v[36:37] op_sel_hi:[1,0]
	v_pk_mul_f32 v[36:37], v[16:17], v[36:37] op_sel_hi:[1,0]
	v_mov_b32_e32 v16, v28
	v_mov_b32_e32 v17, v24
	v_fmaak_f32 v40, v29, v40, 0x3f4c422a
	v_fmaak_f32 v41, v25, v41, 0x3f4c422a
	v_mul_f32_e32 v28, v28, v38
	v_mul_f32_e32 v24, v24, v39
	v_mul_f32_e32 v38, v29, v40
	v_mul_f32_e32 v39, v25, v41
	v_add_f32_e32 v28, v28, v28
	v_add_f32_e32 v24, v24, v24
	v_mul_f32_e32 v42, 0x3d122279, v30
	v_mul_f32_e32 v43, 0x3d122279, v26
	v_add_f32_e32 v38, v38, v38
	v_add_f32_e32 v39, v39, v39
	v_mul_f32_e32 v28, 0xbfb8aa3b, v28
	v_mul_f32_e32 v24, 0xbfb8aa3b, v24
	v_fmaak_f32 v42, v30, v42, 0x3f4c422a
	v_fmaak_f32 v43, v26, v43, 0x3f4c422a
	v_mul_f32_e32 v38, 0xbfb8aa3b, v38
	v_mul_f32_e32 v39, 0xbfb8aa3b, v39
	v_exp_f32_e32 v28, v28
	v_exp_f32_e32 v24, v24
	v_mul_f32_e32 v40, v30, v42
	v_mul_f32_e32 v41, v26, v43
	v_exp_f32_e32 v38, v38
	v_exp_f32_e32 v39, v39
	v_add_f32_e32 v40, v40, v40
	v_add_f32_e32 v41, v41, v41
	v_mul_f32_e32 v44, 0x3d122279, v31
	v_mul_f32_e32 v45, 0x3d122279, v27
	v_mul_f32_e32 v46, 0x3d122279, v20
	v_mul_f32_e32 v47, 0x3d122279, v36
	v_mul_f32_e32 v48, 0x3d122279, v21
	v_mul_f32_e32 v40, 0xbfb8aa3b, v40
	v_mul_f32_e32 v41, 0xbfb8aa3b, v41
	v_fmaak_f32 v44, v31, v44, 0x3f4c422a
	v_fmaak_f32 v45, v27, v45, 0x3f4c422a
	v_fmaak_f32 v46, v20, v46, 0x3f4c422a
	v_fmaak_f32 v47, v36, v47, 0x3f4c422a
	v_fmaak_f32 v48, v21, v48, 0x3f4c422a
	v_exp_f32_e32 v40, v40
	v_exp_f32_e32 v41, v41
	v_add_f32_e32 v28, 1.0, v28
	v_add_f32_e32 v24, 1.0, v24
	v_mul_f32_e32 v42, v31, v44
	v_mul_f32_e32 v43, v27, v45
	v_mul_f32_e32 v44, v20, v46
	v_mul_f32_e32 v45, v36, v47
	v_mul_f32_e32 v46, v21, v48
	v_add_f32_e32 v47, 1.0, v38
	v_add_f32_e32 v48, 1.0, v39
	v_rcp_f32_e32 v38, v28
	v_rcp_f32_e32 v39, v24
	v_add_f32_e32 v40, 1.0, v40
	v_add_f32_e32 v41, 1.0, v41
	v_rcp_f32_e32 v28, v47
	v_rcp_f32_e32 v24, v48
	v_rcp_f32_e32 v47, v40
	v_rcp_f32_e32 v48, v41
	v_pk_mul_f32 v[40:41], v[16:17], v[38:39]
	v_add_f32_e32 v46, v46, v46
	v_pk_fma_f32 v[16:17], v[16:17], v[38:39], v[40:41] op_sel:[0,0,1] op_sel_hi:[1,1,0]
	v_mul_f32_e32 v38, 0x3d122279, v37
	v_fmaak_f32 v38, v37, v38, 0x3f4c422a
	v_mul_f32_e32 v38, v37, v38
	v_mul_f32_e32 v17, 0xbfb8aa3b, v46
	v_add_f32_e32 v38, v38, v38
	v_exp_f32_e32 v17, v17
	v_mul_f32_e32 v38, 0xbfb8aa3b, v38
	v_exp_f32_e32 v38, v38
	v_mul_f32_e32 v39, 0x3d122279, v18
	v_add_f32_e32 v17, 1.0, v17
	v_rcp_f32_e32 v52, v17
	v_add_f32_e32 v17, 1.0, v38
	v_mul_f32_e32 v38, 0x3d122279, v22
	v_fmaak_f32 v38, v22, v38, 0x3f4c422a
	v_mul_f32_e32 v38, v22, v38
	v_fmaak_f32 v39, v18, v39, 0x3f4c422a
	v_add_f32_e32 v38, v38, v38
	v_mul_f32_e32 v39, v18, v39
	v_mul_f32_e32 v38, 0xbfb8aa3b, v38
	v_add_f32_e32 v39, v39, v39
	v_exp_f32_e32 v38, v38
	v_mul_f32_e32 v39, 0xbfb8aa3b, v39
	v_exp_f32_e32 v39, v39
	v_rcp_f32_e32 v53, v17
	v_add_f32_e32 v17, 1.0, v38
	v_mul_f32_e32 v38, 0x3d122279, v23
	v_add_f32_e32 v42, v42, v42
	v_add_f32_e32 v43, v43, v43
	v_add_f32_e32 v44, v44, v44
	v_add_f32_e32 v45, v45, v45
	v_rcp_f32_e32 v54, v17
	v_add_f32_e32 v17, 1.0, v39
	v_fmaak_f32 v38, v23, v38, 0x3f4c422a
	v_mul_f32_e32 v39, 0x3d122279, v19
	v_mul_f32_e32 v42, 0xbfb8aa3b, v42
	v_mul_f32_e32 v43, 0xbfb8aa3b, v43
	v_mul_f32_e32 v44, 0xbfb8aa3b, v44
	v_mul_f32_e32 v45, 0xbfb8aa3b, v45
	v_mul_f32_e32 v38, v23, v38
	v_fmaak_f32 v39, v19, v39, 0x3f4c422a
	v_exp_f32_e32 v42, v42
	v_exp_f32_e32 v43, v43
	v_exp_f32_e32 v44, v44
	v_exp_f32_e32 v45, v45
	v_add_f32_e32 v38, v38, v38
	v_mul_f32_e32 v39, v19, v39
	v_mul_f32_e32 v38, 0xbfb8aa3b, v38
	v_add_f32_e32 v39, v39, v39
	v_exp_f32_e32 v38, v38
	v_mul_f32_e32 v39, 0xbfb8aa3b, v39
	v_exp_f32_e32 v39, v39
	v_add_f32_e32 v42, 1.0, v42
	v_add_f32_e32 v43, 1.0, v43
	v_add_f32_e32 v44, 1.0, v44
	v_add_f32_e32 v45, 1.0, v45
	v_rcp_f32_e32 v42, v42
	v_rcp_f32_e32 v43, v43
	v_rcp_f32_e32 v50, v44
	v_rcp_f32_e32 v51, v45
	v_mul_f32_e32 v26, v26, v48
	v_mov_b32_e32 v44, v29
	v_mov_b32_e32 v45, v40
	v_mov_b32_e32 v29, v40
	v_mov_b32_e32 v48, v25
	v_mov_b32_e32 v49, v41
	v_mov_b32_e32 v25, v41
	v_rcp_f32_e32 v55, v17
	v_add_f32_e32 v17, 1.0, v38
	v_mul_f32_e32 v30, v30, v47
	v_pk_mul_f32 v[46:47], v[44:45], v[28:29]
	v_pk_mul_f32 v[24:25], v[48:49], v[24:25]
	v_rcp_f32_e32 v56, v17
	v_add_f32_e32 v17, 1.0, v39
	v_pk_fma_f32 v[28:29], v[44:45], v[28:29], v[24:25]
	v_pk_mul_f32 v[44:45], v[46:47], v[46:47]
	v_pk_mul_f32 v[48:49], v[24:25], v[24:25]
	v_rcp_f32_e32 v57, v17
	v_mov_b32_e32 v17, v44
	v_mov_b32_e32 v137, v48
	v_mul_f32_e32 v38, v31, v42
	v_mul_f32_e32 v42, v27, v43
	v_pk_add_f32 v[16:17], v[16:17], v[136:137]
	v_mul_f32_e32 v31, v30, v30
	v_mul_f32_e32 v27, v26, v26
	v_pk_add_f32 v[16:17], v[28:29], v[16:17]
	v_pk_add_f32 v[28:29], v[30:31], v[26:27]
	v_mul_f32_e32 v39, v38, v38
	v_mul_f32_e32 v43, v42, v42
	v_pk_add_f32 v[16:17], v[28:29], v[16:17]
	v_pk_add_f32 v[28:29], v[38:39], v[42:43]
	v_mul_f32_e32 v20, v20, v50
	v_pk_add_f32 v[28:29], v[28:29], v[16:17]
	v_cvt_pk_bf16_f32 v16, v40, v46
	v_cvt_pk_bf16_f32 v17, v30, v38
	v_mul_f32_e32 v30, v36, v51
	v_mul_f32_e32 v36, v21, v52
	v_mul_f32_e32 v38, v37, v53
	v_mul_f32_e32 v21, v20, v20
	v_mul_f32_e32 v31, v30, v30
	v_mul_f32_e32 v22, v22, v54
	v_mul_f32_e32 v44, v18, v55
	v_mul_f32_e32 v48, v19, v57
	v_pk_add_f32 v[18:19], v[20:21], v[30:31]
	v_mul_f32_e32 v37, v36, v36
	v_mul_f32_e32 v39, v38, v38
	v_mul_f32_e32 v46, v23, v56
	v_pk_add_f32 v[18:19], v[18:19], v[28:29]
	v_pk_add_f32 v[28:29], v[36:37], v[38:39]
	v_mul_f32_e32 v23, v22, v22
	v_mul_f32_e32 v45, v44, v44
	v_pk_add_f32 v[18:19], v[28:29], v[18:19]
	v_pk_add_f32 v[28:29], v[22:23], v[44:45]
	v_mul_f32_e32 v47, v46, v46
	v_mul_f32_e32 v49, v48, v48
	v_pk_add_f32 v[18:19], v[28:29], v[18:19]
	v_pk_add_f32 v[28:29], v[46:47], v[48:49]
	s_nop 0
	v_pk_add_f32 v[28:29], v[28:29], v[18:19]
	ds_bpermute_b32 v50, v162, v28
	ds_bpermute_b32 v51, v162, v29
	v_cvt_pk_bf16_f32 v18, v41, v24
	v_cvt_pk_bf16_f32 v19, v26, v42
	global_store_dwordx4 v[34:35], v[16:19], off
	v_cvt_pk_bf16_f32 v20, v20, v36
	v_cvt_pk_bf16_f32 v21, v22, v46
	v_cvt_pk_bf16_f32 v22, v30, v38
	v_cvt_pk_bf16_f32 v23, v44, v48
	global_store_dwordx4 v[34:35], v[20:23], off offset:256
	s_waitcnt lgkmcnt(0)
	v_pk_add_f32 v[16:17], v[28:29], v[50:51]
	ds_bpermute_b32 v18, v163, v16
	ds_bpermute_b32 v19, v163, v17
	s_and_saveexec_b64 s[48:49], s[46:47]
	s_cbranch_execz .LBB0_195
	s_lshl_b32 s14, s12, 2
	v_lshlrev_b64 v[20:21], 5, v[32:33]
	s_sub_i32 s14, s14, 32
	v_lshl_add_u64 v[20:21], v[20:21], 0, s[14:15]
	v_or_b32_e32 v20, s56, v20
	v_lshl_add_u64 v[20:21], v[20:21], 3, s[20:21]
	s_waitcnt lgkmcnt(0)
	v_pk_add_f32 v[16:17], v[16:17], v[18:19]
	global_store_dwordx2 v[20:21], v[16:17], off
.LBB0_195:
	s_or_b64 exec, exec, s[48:49]
	v_add_u32_e32 v16, 0xb0, v150
	v_ashrrev_i32_e32 v17, 31, v16
	s_waitcnt lgkmcnt(0)
	v_lshlrev_b64 v[18:19], 7, v[16:17]
	v_lshl_add_u64 v[22:23], v[138:139], 0, v[18:19]
	global_load_dwordx4 v[18:21], v[22:23], off
	s_nop 0
	global_load_dwordx4 v[22:25], v[22:23], off offset:16
	s_waitcnt vmcnt(1)
	v_mov_b32_e32 v26, v18
	s_waitcnt vmcnt(0)
	v_mov_b32_e32 v27, v22
	v_mov_b32_e32 v22, v19
	v_mov_b32_e32 v18, v20
	v_mov_b32_e32 v19, v24
	v_mov_b32_e32 v24, v21
	v_pk_add_f32 v[20:21], v[26:27], v[22:23]
	v_pk_add_f32 v[18:19], v[18:19], v[24:25]
	s_nop 0
	v_pk_add_f32 v[18:19], v[20:21], v[18:19]
	s_nop 0
	v_add_f32_e32 v18, 0, v18
	v_add_f32_e32 v18, v18, v19
	ds_bpermute_b32 v19, v162, v18
	s_waitcnt lgkmcnt(0)
	v_add_f32_e32 v18, v18, v19
	ds_bpermute_b32 v19, v163, v18
	s_waitcnt lgkmcnt(0)
	v_add_f32_e32 v18, v18, v19
	v_fmamk_f32 v18, v18, 0x3a000000, v161
	v_rsq_f32_e32 v20, v18
	v_lshlrev_b64 v[18:19], 13, v[16:17]
	v_lshl_add_u64 v[18:19], s[18:19], 0, v[18:19]
	v_lshl_add_u64 v[18:19], v[148:149], 1, v[18:19]
	v_pk_mul_f32 v[12:13], v[12:13], v[20:21] op_sel_hi:[1,0]
	v_pk_mul_f32 v[8:9], v[8:9], v[20:21] op_sel_hi:[1,0]
	v_mul_f32_e32 v22, 0x3d122279, v12
	v_mul_f32_e32 v23, 0x3d122279, v8
	v_mul_f32_e32 v24, 0x3d122279, v13
	v_mul_f32_e32 v25, 0x3d122279, v9
	v_fmaak_f32 v22, v12, v22, 0x3f4c422a
	v_fmaak_f32 v23, v8, v23, 0x3f4c422a
	v_pk_mul_f32 v[14:15], v[14:15], v[20:21] op_sel_hi:[1,0]
	v_pk_mul_f32 v[10:11], v[10:11], v[20:21] op_sel_hi:[1,0]
	v_pk_mul_f32 v[6:7], v[6:7], v[20:21] op_sel_hi:[1,0]
	v_pk_mul_f32 v[4:5], v[4:5], v[20:21] op_sel_hi:[1,0]
	v_pk_mul_f32 v[2:3], v[2:3], v[20:21] op_sel_hi:[1,0]
	v_pk_mul_f32 v[20:21], v[0:1], v[20:21] op_sel_hi:[1,0]
	v_mov_b32_e32 v0, v12
	v_mov_b32_e32 v1, v8
	v_fmaak_f32 v24, v13, v24, 0x3f4c422a
	v_fmaak_f32 v25, v9, v25, 0x3f4c422a
	v_mul_f32_e32 v12, v12, v22
	v_mul_f32_e32 v8, v8, v23
	v_mul_f32_e32 v22, v13, v24
	v_mul_f32_e32 v23, v9, v25
	v_add_f32_e32 v12, v12, v12
	v_add_f32_e32 v8, v8, v8
	v_mul_f32_e32 v26, 0x3d122279, v14
	v_mul_f32_e32 v27, 0x3d122279, v10
	v_add_f32_e32 v22, v22, v22
	v_add_f32_e32 v23, v23, v23
	v_mul_f32_e32 v12, 0xbfb8aa3b, v12
	v_mul_f32_e32 v8, 0xbfb8aa3b, v8
	v_fmaak_f32 v26, v14, v26, 0x3f4c422a
	v_fmaak_f32 v27, v10, v27, 0x3f4c422a
	v_mul_f32_e32 v22, 0xbfb8aa3b, v22
	v_mul_f32_e32 v23, 0xbfb8aa3b, v23
	v_exp_f32_e32 v12, v12
	v_exp_f32_e32 v8, v8
	v_mul_f32_e32 v24, v14, v26
	v_mul_f32_e32 v25, v10, v27
	v_exp_f32_e32 v22, v22
	v_exp_f32_e32 v23, v23
	v_add_f32_e32 v24, v24, v24
	v_add_f32_e32 v25, v25, v25
	v_mul_f32_e32 v28, 0x3d122279, v15
	v_mul_f32_e32 v29, 0x3d122279, v11
	v_mul_f32_e32 v30, 0x3d122279, v4
	v_mul_f32_e32 v31, 0x3d122279, v20
	v_mul_f32_e32 v32, 0x3d122279, v5
	v_mul_f32_e32 v24, 0xbfb8aa3b, v24
	v_mul_f32_e32 v25, 0xbfb8aa3b, v25
	v_fmaak_f32 v28, v15, v28, 0x3f4c422a
	v_fmaak_f32 v29, v11, v29, 0x3f4c422a
	v_fmaak_f32 v30, v4, v30, 0x3f4c422a
	v_fmaak_f32 v31, v20, v31, 0x3f4c422a
	v_fmaak_f32 v32, v5, v32, 0x3f4c422a
	v_exp_f32_e32 v24, v24
	v_exp_f32_e32 v25, v25
	v_add_f32_e32 v12, 1.0, v12
	v_add_f32_e32 v8, 1.0, v8
	v_mul_f32_e32 v26, v15, v28
	v_mul_f32_e32 v27, v11, v29
	v_mul_f32_e32 v28, v4, v30
	v_mul_f32_e32 v29, v20, v31
	v_mul_f32_e32 v30, v5, v32
	v_add_f32_e32 v31, 1.0, v22
	v_add_f32_e32 v32, 1.0, v23
	v_rcp_f32_e32 v22, v12
	v_rcp_f32_e32 v23, v8
	v_add_f32_e32 v24, 1.0, v24
	v_add_f32_e32 v25, 1.0, v25
	v_rcp_f32_e32 v12, v31
	v_rcp_f32_e32 v8, v32
	v_rcp_f32_e32 v31, v24
	v_rcp_f32_e32 v32, v25
	v_pk_mul_f32 v[24:25], v[0:1], v[22:23]
	v_add_f32_e32 v30, v30, v30
	v_pk_fma_f32 v[0:1], v[0:1], v[22:23], v[24:25] op_sel:[0,0,1] op_sel_hi:[1,1,0]
	v_mul_f32_e32 v22, 0x3d122279, v21
	v_fmaak_f32 v22, v21, v22, 0x3f4c422a
	v_mul_f32_e32 v22, v21, v22
	v_mul_f32_e32 v1, 0xbfb8aa3b, v30
	v_add_f32_e32 v22, v22, v22
	v_exp_f32_e32 v1, v1
	v_mul_f32_e32 v22, 0xbfb8aa3b, v22
	v_exp_f32_e32 v22, v22
	v_mul_f32_e32 v23, 0x3d122279, v2
	v_add_f32_e32 v1, 1.0, v1
	v_rcp_f32_e32 v36, v1
	v_add_f32_e32 v1, 1.0, v22
	v_mul_f32_e32 v22, 0x3d122279, v6
	v_fmaak_f32 v22, v6, v22, 0x3f4c422a
	v_mul_f32_e32 v22, v6, v22
	v_fmaak_f32 v23, v2, v23, 0x3f4c422a
	v_add_f32_e32 v22, v22, v22
	v_mul_f32_e32 v23, v2, v23
	v_mul_f32_e32 v22, 0xbfb8aa3b, v22
	v_add_f32_e32 v23, v23, v23
	v_exp_f32_e32 v22, v22
	v_mul_f32_e32 v23, 0xbfb8aa3b, v23
	v_exp_f32_e32 v23, v23
	v_rcp_f32_e32 v37, v1
	v_add_f32_e32 v1, 1.0, v22
	v_mul_f32_e32 v22, 0x3d122279, v7
	v_add_f32_e32 v26, v26, v26
	v_add_f32_e32 v27, v27, v27
	v_add_f32_e32 v28, v28, v28
	v_add_f32_e32 v29, v29, v29
	v_rcp_f32_e32 v38, v1
	v_add_f32_e32 v1, 1.0, v23
	v_fmaak_f32 v22, v7, v22, 0x3f4c422a
	v_mul_f32_e32 v23, 0x3d122279, v3
	v_mul_f32_e32 v26, 0xbfb8aa3b, v26
	v_mul_f32_e32 v27, 0xbfb8aa3b, v27
	v_mul_f32_e32 v28, 0xbfb8aa3b, v28
	v_mul_f32_e32 v29, 0xbfb8aa3b, v29
	v_mul_f32_e32 v22, v7, v22
	v_fmaak_f32 v23, v3, v23, 0x3f4c422a
	v_exp_f32_e32 v26, v26
	v_exp_f32_e32 v27, v27
	v_exp_f32_e32 v28, v28
	v_exp_f32_e32 v29, v29
	v_add_f32_e32 v22, v22, v22
	v_mul_f32_e32 v23, v3, v23
	v_mul_f32_e32 v22, 0xbfb8aa3b, v22
	v_add_f32_e32 v23, v23, v23
	v_exp_f32_e32 v22, v22
	v_mul_f32_e32 v23, 0xbfb8aa3b, v23
	v_exp_f32_e32 v23, v23
	v_add_f32_e32 v26, 1.0, v26
	v_add_f32_e32 v27, 1.0, v27
	v_add_f32_e32 v28, 1.0, v28
	v_add_f32_e32 v29, 1.0, v29
	v_rcp_f32_e32 v26, v26
	v_rcp_f32_e32 v27, v27
	v_rcp_f32_e32 v34, v28
	v_rcp_f32_e32 v35, v29
	v_mul_f32_e32 v10, v10, v32
	v_mov_b32_e32 v28, v13
	v_mov_b32_e32 v29, v24
	v_mov_b32_e32 v13, v24
	v_mov_b32_e32 v32, v9
	v_mov_b32_e32 v33, v25
	v_mov_b32_e32 v9, v25
	v_rcp_f32_e32 v39, v1
	v_add_f32_e32 v1, 1.0, v22
	v_mul_f32_e32 v14, v14, v31
	v_pk_mul_f32 v[30:31], v[28:29], v[12:13]
	v_pk_mul_f32 v[8:9], v[32:33], v[8:9]
	v_rcp_f32_e32 v40, v1
	v_add_f32_e32 v1, 1.0, v23
	v_pk_fma_f32 v[12:13], v[28:29], v[12:13], v[8:9]
	v_pk_mul_f32 v[28:29], v[30:31], v[30:31]
	v_pk_mul_f32 v[32:33], v[8:9], v[8:9]
	v_rcp_f32_e32 v41, v1
	v_mov_b32_e32 v1, v28
	v_mov_b32_e32 v137, v32
	v_mul_f32_e32 v22, v15, v26
	v_mul_f32_e32 v26, v11, v27
	v_pk_add_f32 v[0:1], v[0:1], v[136:137]
	v_mul_f32_e32 v15, v14, v14
	v_mul_f32_e32 v11, v10, v10
	v_pk_add_f32 v[0:1], v[12:13], v[0:1]
	v_pk_add_f32 v[12:13], v[14:15], v[10:11]
	v_mul_f32_e32 v23, v22, v22
	v_mul_f32_e32 v27, v26, v26
	v_pk_add_f32 v[0:1], v[12:13], v[0:1]
	v_pk_add_f32 v[12:13], v[22:23], v[26:27]
	v_mul_f32_e32 v4, v4, v34
	v_pk_add_f32 v[12:13], v[12:13], v[0:1]
	v_cvt_pk_bf16_f32 v0, v24, v30
	v_cvt_pk_bf16_f32 v1, v14, v22
	v_mul_f32_e32 v14, v20, v35
	v_mul_f32_e32 v20, v5, v36
	v_mul_f32_e32 v22, v21, v37
	v_mul_f32_e32 v5, v4, v4
	v_mul_f32_e32 v15, v14, v14
	v_mul_f32_e32 v6, v6, v38
	v_mul_f32_e32 v28, v2, v39
	v_mul_f32_e32 v32, v3, v41
	v_pk_add_f32 v[2:3], v[4:5], v[14:15]
	v_mul_f32_e32 v21, v20, v20
	v_mul_f32_e32 v23, v22, v22
	v_mul_f32_e32 v30, v7, v40
	v_pk_add_f32 v[2:3], v[2:3], v[12:13]
	v_pk_add_f32 v[12:13], v[20:21], v[22:23]
	v_mul_f32_e32 v7, v6, v6
	v_mul_f32_e32 v29, v28, v28
	v_pk_add_f32 v[2:3], v[12:13], v[2:3]
	v_pk_add_f32 v[12:13], v[6:7], v[28:29]
	v_mul_f32_e32 v31, v30, v30
	v_mul_f32_e32 v33, v32, v32
	v_pk_add_f32 v[2:3], v[12:13], v[2:3]
	v_pk_add_f32 v[12:13], v[30:31], v[32:33]
	s_nop 0
	v_pk_add_f32 v[12:13], v[12:13], v[2:3]
	ds_bpermute_b32 v34, v162, v12
	ds_bpermute_b32 v35, v162, v13
	v_cvt_pk_bf16_f32 v2, v25, v8
	v_cvt_pk_bf16_f32 v3, v10, v26
	global_store_dwordx4 v[18:19], v[0:3], off
	v_cvt_pk_bf16_f32 v4, v4, v20
	v_cvt_pk_bf16_f32 v5, v6, v30
	v_cvt_pk_bf16_f32 v6, v14, v22
	v_cvt_pk_bf16_f32 v7, v28, v32
	global_store_dwordx4 v[18:19], v[4:7], off offset:256
	s_waitcnt lgkmcnt(0)
	v_pk_add_f32 v[0:1], v[12:13], v[34:35]
	ds_bpermute_b32 v2, v163, v0
	ds_bpermute_b32 v3, v163, v1
	s_and_saveexec_b64 s[48:49], s[46:47]
	s_cbranch_execz .LBB0_197
	s_lshl_b32 s12, s12, 2
	v_lshlrev_b64 v[4:5], 5, v[16:17]
	s_sub_i32 s14, s12, 32
	v_lshl_add_u64 v[4:5], v[4:5], 0, s[14:15]
	v_or_b32_e32 v4, s56, v4
	v_lshl_add_u64 v[4:5], v[4:5], 3, s[20:21]
	s_waitcnt lgkmcnt(0)
	v_pk_add_f32 v[0:1], v[0:1], v[2:3]
	global_store_dwordx2 v[4:5], v[0:1], off

.LBB0_259:
	s_lshl_b32 s18, s31, 3
	s_and_b32 s46, s18, 0xffffff80
	v_add_u32_e32 v76, s46, v83
	v_ashrrev_i32_e32 v77, 31, v76
	s_lshl_b32 s18, s31, 7
	v_lshlrev_b64 v[16:17], 13, v[76:77]
	s_and_b32 s45, s18, 0x780
	v_lshl_add_u64 v[16:17], s[8:9], 0, v[16:17]
	s_lshl_b32 s18, s45, 1
	v_lshl_add_u64 v[16:17], v[16:17], 0, s[18:19]
	v_lshl_add_u64 v[16:17], v[16:17], 0, v[60:61]
	global_load_dwordx2 v[78:79], v[16:17], off
	global_load_dwordx2 v[74:75], v[16:17], off offset:32
	global_load_dwordx2 v[72:73], v[16:17], off offset:64
	global_load_dwordx2 v[70:71], v[16:17], off offset:96
	global_load_dwordx2 v[68:69], v[16:17], off offset:128
	global_load_dwordx2 v[66:67], v[16:17], off offset:160
	global_load_dwordx2 v[64:65], v[16:17], off offset:192
	global_load_dwordx2 v[62:63], v[16:17], off offset:224
	s_cmp_eq_u32 s31, s30
	s_cselect_b64 s[26:27], -1, 0
	s_or_b64 s[26:27], s[20:21], s[26:27]
	s_and_b64 s[48:49], s[4:5], s[26:27]
	s_and_saveexec_b64 s[26:27], s[48:49]
	s_cbranch_execz .LBB0_261
	v_add_u32_e32 v16, s46, v51
	v_ashrrev_i32_e32 v17, 31, v16
	v_lshlrev_b64 v[16:17], 8, v[16:17]
	v_lshl_add_u64 v[80:81], s[16:17], 0, v[16:17]
	global_load_dwordx4 v[16:19], v[80:81], off
	global_load_dwordx4 v[20:23], v[80:81], off offset:16
	global_load_dwordx4 v[24:27], v[80:81], off offset:32
	global_load_dwordx4 v[28:31], v[80:81], off offset:48
	global_load_dwordx4 v[32:35], v[80:81], off offset:64
	global_load_dwordx4 v[36:39], v[80:81], off offset:80
	global_load_dwordx4 v[40:43], v[80:81], off offset:96
	global_load_dwordx4 v[44:47], v[80:81], off offset:112
	global_load_dwordx4 v[90:93], v[80:81], off offset:128
	global_load_dwordx4 v[94:97], v[80:81], off offset:144
	global_load_dwordx4 v[98:101], v[80:81], off offset:160
	global_load_dwordx4 v[102:105], v[80:81], off offset:176
	global_load_dwordx4 v[106:109], v[80:81], off offset:192
	global_load_dwordx4 v[110:113], v[80:81], off offset:208
	global_load_dwordx4 v[114:117], v[80:81], off offset:224
	global_load_dwordx4 v[118:121], v[80:81], off offset:240
	s_waitcnt vmcnt(15)
	v_pk_add_f32 v[16:17], v[16:17], v[18:19]
	s_waitcnt vmcnt(14)
	v_pk_add_f32 v[18:19], v[20:21], v[22:23]
	v_pk_add_f32 v[16:17], v[16:17], 0 op_sel_hi:[1,0]
	s_waitcnt vmcnt(13)
	v_pk_add_f32 v[20:21], v[24:25], v[26:27]
	v_pk_add_f32 v[16:17], v[16:17], v[18:19]
	s_waitcnt vmcnt(12)
	v_pk_add_f32 v[22:23], v[28:29], v[30:31]
	v_pk_add_f32 v[16:17], v[16:17], v[20:21]
	s_waitcnt vmcnt(11)
	v_pk_add_f32 v[24:25], v[32:33], v[34:35]
	v_pk_add_f32 v[16:17], v[16:17], v[22:23]
	s_waitcnt vmcnt(10)
	v_pk_add_f32 v[26:27], v[36:37], v[38:39]
	v_pk_add_f32 v[16:17], v[16:17], v[24:25]
	s_waitcnt vmcnt(9)
	v_pk_add_f32 v[28:29], v[40:41], v[42:43]
	v_pk_add_f32 v[16:17], v[16:17], v[26:27]
	s_waitcnt vmcnt(8)
	v_pk_add_f32 v[30:31], v[44:45], v[46:47]
	v_pk_add_f32 v[16:17], v[16:17], v[28:29]
	s_waitcnt vmcnt(7)
	v_pk_add_f32 v[32:33], v[90:91], v[92:93]
	v_pk_add_f32 v[16:17], v[16:17], v[30:31]
	s_waitcnt vmcnt(6)
	v_pk_add_f32 v[34:35], v[94:95], v[96:97]
	v_pk_add_f32 v[16:17], v[16:17], v[32:33]
	s_waitcnt vmcnt(5)
	v_pk_add_f32 v[36:37], v[98:99], v[100:101]
	v_pk_add_f32 v[16:17], v[16:17], v[34:35]
	s_waitcnt vmcnt(4)
	v_pk_add_f32 v[38:39], v[102:103], v[104:105]
	v_pk_add_f32 v[16:17], v[16:17], v[36:37]
	s_waitcnt vmcnt(3)
	v_pk_add_f32 v[40:41], v[106:107], v[108:109]
	v_pk_add_f32 v[16:17], v[16:17], v[38:39]
	s_waitcnt vmcnt(2)
	v_pk_add_f32 v[42:43], v[110:111], v[112:113]
	v_pk_add_f32 v[16:17], v[16:17], v[40:41]
	s_waitcnt vmcnt(1)
	v_pk_add_f32 v[44:45], v[114:115], v[116:117]
	v_pk_add_f32 v[16:17], v[16:17], v[42:43]
	s_waitcnt vmcnt(0)
	v_pk_add_f32 v[46:47], v[118:119], v[120:121]
	v_pk_add_f32 v[16:17], v[16:17], v[44:45]
	s_nop 0
	v_pk_add_f32 v[16:17], v[16:17], v[46:47]
	s_nop 0
	v_pk_mul_f32 v[16:17], v[16:17], s[22:23] op_sel_hi:[1,0]
	s_nop 0
	v_fma_f32 v17, -v16, v16, v17
	v_add_f32_e32 v17, 0x358637bd, v17
	v_rsq_f32_e32 v17, v17
	s_nop 0
	ds_write_b64 v86, v[16:17] offset:34816

.LBB0_441:
	s_lshl_b32 s23, s36, 8
	s_cmp_eq_u32 s50, 2
	s_cselect_b32 s25, 0x80, 0
	s_or_b32 s23, s23, s25
	v_add_u32_e32 v132, s23, v219
	v_ashrrev_i32_e32 v133, 31, v132
	v_lshlrev_b64 v[2:3], 7, v[132:133]
	v_lshl_add_u64 v[2:3], v[204:205], 0, v[2:3]
	global_load_dwordx4 v[134:137], v[2:3], off
	global_load_dwordx4 v[138:141], v[2:3], off offset:16
	v_and_b32_e32 v133, 64, v225
	v_xor_b32_e32 v1, 16, v225
	v_mov_b32_e32 v145, v118
	v_mov_b32_e32 v118, v127
	v_add_u32_e32 v127, 64, v133
	v_cmp_lt_i32_e32 vcc, v1, v127
	v_mov_b32_e32 v144, v126
	v_xor_b32_e32 v148, 32, v225
	v_cndmask_b32_e32 v1, v225, v1, vcc
	v_lshlrev_b32_e32 v126, 2, v1
	v_cmp_lt_i32_e32 vcc, v148, v127
	v_mov_b32_e32 v142, v128
	v_mov_b32_e32 v143, v120
	v_mov_b32_e32 v120, v129
	v_mov_b32_e32 v128, v130
	v_mov_b32_e32 v129, v122
	v_mov_b32_e32 v122, v131
	v_mov_b32_e32 v130, v124
	v_mov_b32_e32 v131, v116
	v_mov_b32_e32 v116, v125
	v_lshl_or_b32 v2, s51, 7, v221
	v_mov_b64_e32 v[124:125], s[14:15]
	v_ashrrev_i32_e32 v3, 31, v2
	v_lshlrev_b64 v[2:3], 1, v[2:3]
	s_waitcnt vmcnt(0)
	v_mov_b32_e32 v146, v134
	v_mov_b32_e32 v147, v138
	v_mov_b32_e32 v138, v135
	v_mov_b32_e32 v134, v136
	v_mov_b32_e32 v135, v140
	v_mov_b32_e32 v140, v137
	v_pk_add_f32 v[136:137], v[146:147], v[138:139]
	v_pk_add_f32 v[134:135], v[134:135], v[140:141]
	s_nop 0
	v_pk_add_f32 v[134:135], v[136:137], v[134:135]
	v_or_b32_e32 v136, 16, v132
	v_add_f32_e32 v1, 0, v134
	v_add_f32_e32 v133, v1, v135
	ds_bpermute_b32 v134, v126, v133
	v_cndmask_b32_e32 v1, v225, v148, vcc
	v_lshlrev_b32_e32 v1, 2, v1
	v_ashrrev_i32_e32 v137, 31, v136
	v_lshlrev_b64 v[138:139], 7, v[136:137]
	s_waitcnt lgkmcnt(0)
	v_add_f32_e32 v127, v133, v134
	ds_bpermute_b32 v133, v1, v127
	v_mad_i64_i32 v[134:135], s[46:47], v132, s72, v[124:125]
	v_lshl_add_u64 v[134:135], v[134:135], 0, v[2:3]
	v_lshl_add_u64 v[138:139], v[204:205], 0, v[138:139]
	s_waitcnt lgkmcnt(0)
	v_add_f32_e32 v127, v127, v133
	v_fmamk_f32 v127, v127, 0x3a000000, v226
	v_rsq_f32_e32 v140, v127
	s_nop 0
	v_pk_mul_f32 v[118:119], v[118:119], v[140:141] op_sel_hi:[1,0]
	v_pk_mul_f32 v[142:143], v[142:143], v[140:141] op_sel_hi:[1,0]
	v_pk_mul_f32 v[120:121], v[120:121], v[140:141] op_sel_hi:[1,0]
	v_pk_mul_f32 v[128:129], v[128:129], v[140:141] op_sel_hi:[1,0]
	v_pk_mul_f32 v[122:123], v[122:123], v[140:141] op_sel_hi:[1,0]
	v_pk_mul_f32 v[130:131], v[130:131], v[140:141] op_sel_hi:[1,0]
	v_pk_mul_f32 v[116:117], v[116:117], v[140:141] op_sel_hi:[1,0]
	v_pk_mul_f32 v[144:145], v[144:145], v[140:141] op_sel_hi:[1,0]
	v_mul_f32_e32 v148, 0xbfb8aa3b, v119
	v_mul_f32_e32 v127, 0xbfb8aa3b, v143
	v_mul_f32_e32 v133, 0xbfb8aa3b, v121
	v_mul_f32_e32 v137, 0xbfb8aa3b, v129
	v_mul_f32_e32 v140, 0xbfb8aa3b, v123
	v_mul_f32_e32 v141, 0xbfb8aa3b, v131
	v_mul_f32_e32 v146, 0xbfb8aa3b, v117
	v_mul_f32_e32 v147, 0xbfb8aa3b, v145
	v_exp_f32_e32 v148, v148
	v_exp_f32_e32 v127, v127
	v_exp_f32_e32 v133, v133
	v_exp_f32_e32 v137, v137
	v_exp_f32_e32 v140, v140
	v_exp_f32_e32 v141, v141
	v_exp_f32_e32 v146, v146
	v_exp_f32_e32 v147, v147
	v_add_f32_e32 v148, 1.0, v148
	v_add_f32_e32 v127, 1.0, v127
	v_add_f32_e32 v133, 1.0, v133
	v_add_f32_e32 v137, 1.0, v137
	v_add_f32_e32 v140, 1.0, v140
	v_add_f32_e32 v141, 1.0, v141
	v_add_f32_e32 v146, 1.0, v146
	v_add_f32_e32 v147, 1.0, v147
	v_rcp_f32_e32 v148, v148
	v_rcp_f32_e32 v127, v127
	v_rcp_f32_e32 v133, v133
	v_rcp_f32_e32 v137, v137
	v_rcp_f32_e32 v140, v140
	v_rcp_f32_e32 v141, v141
	v_rcp_f32_e32 v146, v146
	v_rcp_f32_e32 v147, v147
	v_mul_f32_e32 v119, v119, v148
	v_mul_f32_e32 v127, v143, v127
	v_mul_f32_e32 v121, v121, v133
	v_mul_f32_e32 v129, v129, v137
	v_mul_f32_e32 v123, v123, v140
	v_mul_f32_e32 v131, v131, v141
	v_mul_f32_e32 v117, v117, v146
	v_mul_f32_e32 v133, v145, v147
	v_mul_f32_e32 v119, v118, v119
	v_mul_f32_e32 v127, v142, v127
	v_mul_f32_e32 v120, v120, v121
	v_mul_f32_e32 v121, v128, v129
	v_mul_f32_e32 v122, v122, v123
	v_mul_f32_e32 v123, v130, v131
	v_mul_f32_e32 v128, v116, v117
	v_mul_f32_e32 v129, v144, v133
	v_cvt_pk_bf16_f32 v116, v127, v120
	v_cvt_pk_bf16_f32 v117, v121, v122
	v_cvt_pk_bf16_f32 v118, v123, v128
	v_cvt_pk_bf16_f32 v119, v129, v119
	global_store_dwordx4 v[134:135], v[116:119], off
	global_load_dwordx4 v[116:119], v[138:139], off
	global_load_dwordx4 v[120:123], v[138:139], off offset:16
	v_mov_b32_e32 v129, v104
	v_mov_b32_e32 v104, v113
	v_mov_b32_e32 v113, v106
	v_mov_b32_e32 v106, v115
	v_mov_b32_e32 v115, v100
	v_mov_b32_e32 v128, v112
	v_mov_b32_e32 v112, v114
	v_mov_b32_e32 v114, v108
	v_mov_b32_e32 v108, v110
	v_or_b32_e32 v110, 32, v132
	s_waitcnt vmcnt(1)
	v_mov_b32_e32 v130, v116
	s_waitcnt vmcnt(0)
	v_mov_b32_e32 v131, v120
	v_mov_b32_e32 v120, v117
	v_mov_b32_e32 v116, v118
	v_mov_b32_e32 v117, v122
	v_mov_b32_e32 v122, v119
	v_pk_add_f32 v[118:119], v[130:131], v[120:121]
	v_pk_add_f32 v[116:117], v[116:117], v[122:123]
	s_nop 0
	v_pk_add_f32 v[116:117], v[118:119], v[116:117]
	s_nop 0
	v_add_f32_e32 v100, 0, v116
	v_add_f32_e32 v116, v100, v117
	ds_bpermute_b32 v117, v126, v116
	v_mov_b32_e32 v100, v109
	v_mov_b32_e32 v109, v102
	v_mov_b32_e32 v102, v111
	v_ashrrev_i32_e32 v111, 31, v110
	s_waitcnt lgkmcnt(0)
	v_add_f32_e32 v118, v116, v117
	ds_bpermute_b32 v119, v1, v118
	v_mad_i64_i32 v[116:117], s[46:47], v136, s72, v[124:125]
	v_lshl_add_u64 v[116:117], v[116:117], 0, v[2:3]
	s_waitcnt lgkmcnt(0)
	v_add_f32_e32 v118, v118, v119
	v_fmamk_f32 v118, v118, 0x3a000000, v226
	v_rsq_f32_e32 v120, v118
	v_lshlrev_b64 v[118:119], 7, v[110:111]
	v_lshl_add_u64 v[118:119], v[204:205], 0, v[118:119]
	v_pk_mul_f32 v[102:103], v[102:103], v[120:121] op_sel_hi:[1,0]
	v_pk_mul_f32 v[122:123], v[128:129], v[120:121] op_sel_hi:[1,0]
	v_pk_mul_f32 v[104:105], v[104:105], v[120:121] op_sel_hi:[1,0]
	v_pk_mul_f32 v[112:113], v[112:113], v[120:121] op_sel_hi:[1,0]
	v_pk_mul_f32 v[106:107], v[106:107], v[120:121] op_sel_hi:[1,0]
	v_pk_mul_f32 v[114:115], v[114:115], v[120:121] op_sel_hi:[1,0]
	v_pk_mul_f32 v[100:101], v[100:101], v[120:121] op_sel_hi:[1,0]
	v_pk_mul_f32 v[108:109], v[108:109], v[120:121] op_sel_hi:[1,0]
	v_mul_f32_e32 v131, 0xbfb8aa3b, v103
	v_mul_f32_e32 v111, 0xbfb8aa3b, v123
	v_mul_f32_e32 v120, 0xbfb8aa3b, v105
	v_mul_f32_e32 v121, 0xbfb8aa3b, v113
	v_mul_f32_e32 v127, 0xbfb8aa3b, v107
	v_mul_f32_e32 v128, 0xbfb8aa3b, v115
	v_mul_f32_e32 v129, 0xbfb8aa3b, v101
	v_mul_f32_e32 v130, 0xbfb8aa3b, v109
	v_exp_f32_e32 v131, v131
	v_exp_f32_e32 v111, v111
	v_exp_f32_e32 v120, v120
	v_exp_f32_e32 v121, v121
	v_exp_f32_e32 v127, v127
	v_exp_f32_e32 v128, v128
	v_exp_f32_e32 v129, v129
	v_exp_f32_e32 v130, v130
	v_add_f32_e32 v131, 1.0, v131
	v_add_f32_e32 v111, 1.0, v111
	v_add_f32_e32 v120, 1.0, v120
	v_add_f32_e32 v121, 1.0, v121
	v_add_f32_e32 v127, 1.0, v127
	v_add_f32_e32 v128, 1.0, v128
	v_add_f32_e32 v129, 1.0, v129
	v_add_f32_e32 v130, 1.0, v130
	v_rcp_f32_e32 v131, v131
	v_rcp_f32_e32 v111, v111
	v_rcp_f32_e32 v120, v120
	v_rcp_f32_e32 v121, v121
	v_rcp_f32_e32 v127, v127
	v_rcp_f32_e32 v128, v128
	v_rcp_f32_e32 v129, v129
	v_rcp_f32_e32 v130, v130
	v_mul_f32_e32 v103, v103, v131
	v_mul_f32_e32 v111, v123, v111
	v_mul_f32_e32 v105, v105, v120
	v_mul_f32_e32 v113, v113, v121
	v_mul_f32_e32 v107, v107, v127
	v_mul_f32_e32 v115, v115, v128
	v_mul_f32_e32 v101, v101, v129
	v_mul_f32_e32 v109, v109, v130
	v_mul_f32_e32 v103, v102, v103
	v_mul_f32_e32 v111, v122, v111
	v_mul_f32_e32 v104, v104, v105
	v_mul_f32_e32 v105, v112, v113
	v_mul_f32_e32 v106, v106, v107
	v_mul_f32_e32 v107, v114, v115
	v_mul_f32_e32 v112, v100, v101
	v_mul_f32_e32 v108, v108, v109
	v_cvt_pk_bf16_f32 v100, v111, v104
	v_cvt_pk_bf16_f32 v101, v105, v106
	v_cvt_pk_bf16_f32 v102, v107, v112
	v_cvt_pk_bf16_f32 v103, v108, v103
	global_store_dwordx4 v[116:117], v[100:103], off
	global_load_dwordx4 v[100:103], v[118:119], off
	global_load_dwordx4 v[104:107], v[118:119], off offset:16
	v_mov_b32_e32 v109, v88
	v_mov_b32_e32 v88, v97
	v_mov_b32_e32 v97, v90
	v_mov_b32_e32 v90, v99
	v_mov_b32_e32 v99, v84
	v_mov_b32_e32 v108, v96
	v_mov_b32_e32 v96, v98
	v_mov_b32_e32 v98, v92
	v_mov_b32_e32 v92, v94
	v_or_b32_e32 v94, 48, v132
	s_waitcnt vmcnt(1)
	v_mov_b32_e32 v112, v100
	s_waitcnt vmcnt(0)
	v_mov_b32_e32 v113, v104
	v_mov_b32_e32 v104, v101
	v_mov_b32_e32 v100, v102
	v_mov_b32_e32 v101, v106
	v_mov_b32_e32 v106, v103
	v_pk_add_f32 v[102:103], v[112:113], v[104:105]
	v_pk_add_f32 v[100:101], v[100:101], v[106:107]
	s_nop 0
	v_pk_add_f32 v[100:101], v[102:103], v[100:101]
	s_nop 0
	v_add_f32_e32 v84, 0, v100
	v_add_f32_e32 v100, v84, v101
	ds_bpermute_b32 v101, v126, v100
	v_mov_b32_e32 v84, v93
	v_mov_b32_e32 v93, v86
	v_mov_b32_e32 v86, v95
	v_ashrrev_i32_e32 v95, 31, v94
	s_waitcnt lgkmcnt(0)
	v_add_f32_e32 v102, v100, v101
	ds_bpermute_b32 v103, v1, v102
	v_mad_i64_i32 v[100:101], s[46:47], v110, s72, v[124:125]
	v_lshl_add_u64 v[100:101], v[100:101], 0, v[2:3]
	s_waitcnt lgkmcnt(0)
	v_add_f32_e32 v102, v102, v103
	v_fmamk_f32 v102, v102, 0x3a000000, v226
	v_rsq_f32_e32 v104, v102
	v_lshlrev_b64 v[102:103], 7, v[94:95]
	v_lshl_add_u64 v[102:103], v[204:205], 0, v[102:103]
	v_pk_mul_f32 v[86:87], v[86:87], v[104:105] op_sel_hi:[1,0]
	v_pk_mul_f32 v[106:107], v[108:109], v[104:105] op_sel_hi:[1,0]
	v_pk_mul_f32 v[88:89], v[88:89], v[104:105] op_sel_hi:[1,0]
	v_pk_mul_f32 v[96:97], v[96:97], v[104:105] op_sel_hi:[1,0]
	v_pk_mul_f32 v[90:91], v[90:91], v[104:105] op_sel_hi:[1,0]
	v_pk_mul_f32 v[98:99], v[98:99], v[104:105] op_sel_hi:[1,0]
	v_pk_mul_f32 v[84:85], v[84:85], v[104:105] op_sel_hi:[1,0]
	v_pk_mul_f32 v[92:93], v[92:93], v[104:105] op_sel_hi:[1,0]
	v_mul_f32_e32 v112, 0xbfb8aa3b, v87
	v_mul_f32_e32 v95, 0xbfb8aa3b, v107
	v_mul_f32_e32 v104, 0xbfb8aa3b, v89
	v_mul_f32_e32 v105, 0xbfb8aa3b, v97
	v_mul_f32_e32 v108, 0xbfb8aa3b, v91
	v_mul_f32_e32 v109, 0xbfb8aa3b, v99
	v_mul_f32_e32 v110, 0xbfb8aa3b, v85
	v_mul_f32_e32 v111, 0xbfb8aa3b, v93
	v_exp_f32_e32 v112, v112
	v_exp_f32_e32 v95, v95
	v_exp_f32_e32 v104, v104
	v_exp_f32_e32 v105, v105
	v_exp_f32_e32 v108, v108
	v_exp_f32_e32 v109, v109
	v_exp_f32_e32 v110, v110
	v_exp_f32_e32 v111, v111
	v_add_f32_e32 v112, 1.0, v112
	v_add_f32_e32 v95, 1.0, v95
	v_add_f32_e32 v104, 1.0, v104
	v_add_f32_e32 v105, 1.0, v105
	v_add_f32_e32 v108, 1.0, v108
	v_add_f32_e32 v109, 1.0, v109
	v_add_f32_e32 v110, 1.0, v110
	v_add_f32_e32 v111, 1.0, v111
	v_rcp_f32_e32 v112, v112
	v_rcp_f32_e32 v95, v95
	v_rcp_f32_e32 v104, v104
	v_rcp_f32_e32 v105, v105
	v_rcp_f32_e32 v108, v108
	v_rcp_f32_e32 v109, v109
	v_rcp_f32_e32 v110, v110
	v_rcp_f32_e32 v111, v111
	v_mul_f32_e32 v87, v87, v112
	v_mul_f32_e32 v95, v107, v95
	v_mul_f32_e32 v89, v89, v104
	v_mul_f32_e32 v97, v97, v105
	v_mul_f32_e32 v91, v91, v108
	v_mul_f32_e32 v99, v99, v109
	v_mul_f32_e32 v85, v85, v110
	v_mul_f32_e32 v93, v93, v111
	v_mul_f32_e32 v87, v86, v87
	v_mul_f32_e32 v95, v106, v95
	v_mul_f32_e32 v88, v88, v89
	v_mul_f32_e32 v89, v96, v97
	v_mul_f32_e32 v90, v90, v91
	v_mul_f32_e32 v91, v98, v99
	v_mul_f32_e32 v96, v84, v85
	v_mul_f32_e32 v92, v92, v93
	v_cvt_pk_bf16_f32 v84, v95, v88
	v_cvt_pk_bf16_f32 v85, v89, v90
	v_cvt_pk_bf16_f32 v86, v91, v96
	v_cvt_pk_bf16_f32 v87, v92, v87
	global_store_dwordx4 v[100:101], v[84:87], off
	global_load_dwordx4 v[84:87], v[102:103], off
	global_load_dwordx4 v[88:91], v[102:103], off offset:16
	v_mov_b32_e32 v93, v76
	v_mov_b32_e32 v76, v81
	v_mov_b32_e32 v92, v80
	v_mov_b32_e32 v80, v82
	v_mov_b32_e32 v82, v68
	v_mov_b32_e32 v68, v70
	s_waitcnt vmcnt(1)
	v_mov_b32_e32 v96, v84
	s_waitcnt vmcnt(0)
	v_mov_b32_e32 v97, v88
	v_mov_b32_e32 v88, v85
	v_mov_b32_e32 v84, v86
	v_mov_b32_e32 v85, v90
	v_mov_b32_e32 v90, v87
	v_pk_add_f32 v[86:87], v[96:97], v[88:89]
	v_pk_add_f32 v[84:85], v[84:85], v[90:91]
	s_nop 0
	v_pk_add_f32 v[84:85], v[86:87], v[84:85]
	s_nop 0
	v_add_f32_e32 v81, 0, v84
	v_add_f32_e32 v84, v81, v85
	ds_bpermute_b32 v85, v126, v84
	v_mov_b32_e32 v81, v78
	v_mov_b32_e32 v78, v83
	v_mov_b32_e32 v83, v72
	v_mov_b32_e32 v72, v69
	s_waitcnt lgkmcnt(0)
	v_add_f32_e32 v84, v84, v85
	ds_bpermute_b32 v85, v1, v84
	v_mov_b32_e32 v69, v74
	v_mov_b32_e32 v74, v71
	s_waitcnt lgkmcnt(0)
	v_add_f32_e32 v70, v84, v85
	v_fmamk_f32 v70, v70, 0x3a000000, v226
	v_mul_f32_e32 v71, 0x4b800000, v70
	v_cmp_gt_f32_e32 vcc, s71, v70
	s_nop 1
	v_cndmask_b32_e32 v70, v70, v71, vcc
	v_rsq_f32_e32 v86, v70
	v_mad_i64_i32 v[70:71], s[46:47], v94, s72, v[124:125]
	v_lshl_add_u64 v[84:85], v[70:71], 0, v[2:3]
	v_mul_f32_e32 v70, 0x45800000, v86
	v_cndmask_b32_e32 v70, v86, v70, vcc
	v_pk_mul_f32 v[86:87], v[92:93], v[70:71] op_sel_hi:[1,0]
	v_pk_mul_f32 v[76:77], v[76:77], v[70:71] op_sel_hi:[1,0]
	v_pk_mul_f32 v[80:81], v[80:81], v[70:71] op_sel_hi:[1,0]
	v_pk_mul_f32 v[78:79], v[78:79], v[70:71] op_sel_hi:[1,0]
	v_pk_mul_f32 v[82:83], v[82:83], v[70:71] op_sel_hi:[1,0]
	v_pk_mul_f32 v[72:73], v[72:73], v[70:71] op_sel_hi:[1,0]
	v_pk_mul_f32 v[68:69], v[68:69], v[70:71] op_sel_hi:[1,0]
	v_pk_mul_f32 v[70:71], v[74:75], v[70:71] op_sel_hi:[1,0]
	v_mul_f32_e32 v74, 0xbfb8aa3b, v87
	v_mul_f32_e32 v93, 0xbfb8aa3b, v71
	v_mul_f32_e32 v75, 0xbfb8aa3b, v77
	v_mul_f32_e32 v88, 0xbfb8aa3b, v81
	v_mul_f32_e32 v89, 0xbfb8aa3b, v79
	v_mul_f32_e32 v90, 0xbfb8aa3b, v83
	v_mul_f32_e32 v91, 0xbfb8aa3b, v73
	v_mul_f32_e32 v92, 0xbfb8aa3b, v69
	v_exp_f32_e32 v93, v93
	v_exp_f32_e32 v74, v74
	v_exp_f32_e32 v75, v75
	v_exp_f32_e32 v88, v88
	v_exp_f32_e32 v89, v89
	v_exp_f32_e32 v90, v90
	v_exp_f32_e32 v91, v91
	v_exp_f32_e32 v92, v92
	v_add_f32_e32 v93, 1.0, v93
	v_add_f32_e32 v74, 1.0, v74
	v_add_f32_e32 v75, 1.0, v75
	v_add_f32_e32 v88, 1.0, v88
	v_add_f32_e32 v89, 1.0, v89
	v_add_f32_e32 v90, 1.0, v90
	v_add_f32_e32 v91, 1.0, v91
	v_add_f32_e32 v92, 1.0, v92
	v_rcp_f32_e32 v93, v93
	v_rcp_f32_e32 v74, v74
	v_rcp_f32_e32 v75, v75
	v_rcp_f32_e32 v88, v88
	v_rcp_f32_e32 v89, v89
	v_rcp_f32_e32 v90, v90
	v_rcp_f32_e32 v91, v91
	v_rcp_f32_e32 v92, v92
	v_mul_f32_e32 v71, v71, v93
	v_mul_f32_e32 v74, v87, v74
	v_mul_f32_e32 v75, v77, v75
	v_mul_f32_e32 v77, v81, v88
	v_mul_f32_e32 v79, v79, v89
	v_mul_f32_e32 v81, v83, v90
	v_mul_f32_e32 v73, v73, v91
	v_mul_f32_e32 v69, v69, v92
	v_mul_f32_e32 v71, v70, v71
	v_mul_f32_e32 v74, v86, v74
	v_mul_f32_e32 v75, v76, v75
	v_mul_f32_e32 v76, v80, v77
	v_mul_f32_e32 v77, v78, v79
	v_mul_f32_e32 v78, v82, v81
	v_mul_f32_e32 v72, v72, v73
	v_mul_f32_e32 v73, v68, v69
	v_cvt_pk_bf16_f32 v68, v74, v75
	v_cvt_pk_bf16_f32 v69, v76, v77
	v_cvt_pk_bf16_f32 v70, v78, v72
	v_cvt_pk_bf16_f32 v71, v73, v71
	global_store_dwordx4 v[84:85], v[68:71], off
	s_and_b64 vcc, exec, s[10:11]
	s_cbranch_vccz .LBB0_443
	s_andn2_b64 vcc, exec, s[26:27]
	s_mov_b64 s[10:11], -1
	s_cbranch_vccnz .LBB0_422
	s_branch .LBB0_444
.LBB0_443:
	v_add_u32_e32 v76, 0x80, v132
	v_ashrrev_i32_e32 v77, 31, v76
	v_lshlrev_b64 v[68:69], 7, v[76:77]
	v_lshl_add_u64 v[72:73], v[204:205], 0, v[68:69]
	global_load_dwordx4 v[68:71], v[72:73], off
	s_nop 0
	global_load_dwordx4 v[72:75], v[72:73], off offset:16
	v_mov_b32_e32 v78, v64
	v_mov_b32_e32 v79, v56
	v_mov_b32_e32 v56, v65
	v_mov_b32_e32 v64, v66
	v_mov_b32_e32 v65, v58
	v_mov_b32_e32 v58, v67
	v_mov_b32_e32 v66, v60
	v_mov_b32_e32 v67, v52
	v_mov_b32_e32 v52, v61
	s_waitcnt vmcnt(1)
	v_mov_b32_e32 v60, v68
	s_waitcnt vmcnt(0)
	v_mov_b32_e32 v61, v72
	v_mov_b32_e32 v72, v69
	v_mov_b32_e32 v68, v70
	v_mov_b32_e32 v69, v74
	v_mov_b32_e32 v74, v71
	v_pk_add_f32 v[60:61], v[60:61], v[72:73]
	v_pk_add_f32 v[68:69], v[68:69], v[74:75]
	s_nop 0
	v_pk_add_f32 v[60:61], v[60:61], v[68:69]
	v_mov_b32_e32 v68, v62
	v_add_f32_e32 v60, 0, v60
	v_add_f32_e32 v70, v60, v61
	ds_bpermute_b32 v71, v126, v70
	v_add_u32_e32 v62, 0x90, v132
	v_mov_b32_e32 v69, v54
	v_mov_b32_e32 v54, v63
	v_ashrrev_i32_e32 v63, 31, v62
	s_waitcnt lgkmcnt(0)
	v_add_f32_e32 v72, v70, v71
	ds_bpermute_b32 v73, v1, v72
	v_mov_b64_e32 v[60:61], s[14:15]
	v_mad_i64_i32 v[70:71], s[10:11], v76, s72, v[60:61]
	v_lshl_add_u64 v[70:71], v[70:71], 0, v[2:3]
	s_waitcnt lgkmcnt(0)
	v_add_f32_e32 v72, v72, v73
	v_fmamk_f32 v72, v72, 0x3a000000, v226
	v_rsq_f32_e32 v74, v72
	v_lshlrev_b64 v[72:73], 7, v[62:63]
	v_lshl_add_u64 v[72:73], v[204:205], 0, v[72:73]
	v_pk_mul_f32 v[54:55], v[54:55], v[74:75] op_sel_hi:[1,0]
	v_pk_mul_f32 v[76:77], v[78:79], v[74:75] op_sel_hi:[1,0]
	v_pk_mul_f32 v[56:57], v[56:57], v[74:75] op_sel_hi:[1,0]
	v_pk_mul_f32 v[64:65], v[64:65], v[74:75] op_sel_hi:[1,0]
	v_pk_mul_f32 v[58:59], v[58:59], v[74:75] op_sel_hi:[1,0]
	v_pk_mul_f32 v[66:67], v[66:67], v[74:75] op_sel_hi:[1,0]
	v_pk_mul_f32 v[52:53], v[52:53], v[74:75] op_sel_hi:[1,0]
	v_pk_mul_f32 v[68:69], v[68:69], v[74:75] op_sel_hi:[1,0]
	v_mul_f32_e32 v82, 0xbfb8aa3b, v55
	v_mul_f32_e32 v63, 0xbfb8aa3b, v77
	v_mul_f32_e32 v74, 0xbfb8aa3b, v57
	v_mul_f32_e32 v75, 0xbfb8aa3b, v65
	v_mul_f32_e32 v78, 0xbfb8aa3b, v59
	v_mul_f32_e32 v79, 0xbfb8aa3b, v67
	v_mul_f32_e32 v80, 0xbfb8aa3b, v53
	v_mul_f32_e32 v81, 0xbfb8aa3b, v69
	v_exp_f32_e32 v82, v82
	v_exp_f32_e32 v63, v63
	v_exp_f32_e32 v74, v74
	v_exp_f32_e32 v75, v75
	v_exp_f32_e32 v78, v78
	v_exp_f32_e32 v79, v79
	v_exp_f32_e32 v80, v80
	v_exp_f32_e32 v81, v81
	v_add_f32_e32 v82, 1.0, v82
	v_add_f32_e32 v63, 1.0, v63
	v_add_f32_e32 v74, 1.0, v74
	v_add_f32_e32 v75, 1.0, v75
	v_add_f32_e32 v78, 1.0, v78
	v_add_f32_e32 v79, 1.0, v79
	v_add_f32_e32 v80, 1.0, v80
	v_add_f32_e32 v81, 1.0, v81
	v_rcp_f32_e32 v82, v82
	v_rcp_f32_e32 v63, v63
	v_rcp_f32_e32 v74, v74
	v_rcp_f32_e32 v75, v75
	v_rcp_f32_e32 v78, v78
	v_rcp_f32_e32 v79, v79
	v_rcp_f32_e32 v80, v80
	v_rcp_f32_e32 v81, v81
	v_mul_f32_e32 v55, v55, v82
	v_mul_f32_e32 v63, v77, v63
	v_mul_f32_e32 v57, v57, v74
	v_mul_f32_e32 v65, v65, v75
	v_mul_f32_e32 v59, v59, v78
	v_mul_f32_e32 v67, v67, v79
	v_mul_f32_e32 v53, v53, v80
	v_mul_f32_e32 v69, v69, v81
	v_mul_f32_e32 v55, v54, v55
	v_mul_f32_e32 v63, v76, v63
	v_mul_f32_e32 v56, v56, v57
	v_mul_f32_e32 v57, v64, v65
	v_mul_f32_e32 v58, v58, v59
	v_mul_f32_e32 v59, v66, v67
	v_mul_f32_e32 v64, v52, v53
	v_mul_f32_e32 v65, v68, v69
	v_cvt_pk_bf16_f32 v52, v63, v56
	v_cvt_pk_bf16_f32 v53, v57, v58
	v_cvt_pk_bf16_f32 v54, v59, v64
	v_cvt_pk_bf16_f32 v55, v65, v55
	global_store_dwordx4 v[70:71], v[52:55], off
	global_load_dwordx4 v[52:55], v[72:73], off
	global_load_dwordx4 v[56:59], v[72:73], off offset:16
	v_mov_b32_e32 v65, v40
	v_mov_b32_e32 v40, v49
	v_mov_b32_e32 v49, v42
	v_mov_b32_e32 v42, v51
	v_mov_b32_e32 v51, v36
	v_mov_b32_e32 v64, v48
	v_mov_b32_e32 v48, v50
	v_mov_b32_e32 v50, v44
	v_mov_b32_e32 v44, v46
	v_add_u32_e32 v46, 0xa0, v132
	s_waitcnt vmcnt(1)
	v_mov_b32_e32 v66, v52
	s_waitcnt vmcnt(0)
	v_mov_b32_e32 v67, v56
	v_mov_b32_e32 v56, v53
	v_mov_b32_e32 v52, v54
	v_mov_b32_e32 v53, v58
	v_mov_b32_e32 v58, v55
	v_pk_add_f32 v[54:55], v[66:67], v[56:57]
	v_pk_add_f32 v[52:53], v[52:53], v[58:59]
	s_nop 0
	v_pk_add_f32 v[52:53], v[54:55], v[52:53]
	s_nop 0
	v_add_f32_e32 v36, 0, v52
	v_add_f32_e32 v52, v36, v53
	ds_bpermute_b32 v53, v126, v52
	v_mov_b32_e32 v36, v45
	v_mov_b32_e32 v45, v38
	v_mov_b32_e32 v38, v47
	v_ashrrev_i32_e32 v47, 31, v46
	s_waitcnt lgkmcnt(0)
	v_add_f32_e32 v54, v52, v53
	ds_bpermute_b32 v55, v1, v54
	v_mad_i64_i32 v[52:53], s[10:11], v62, s72, v[60:61]
	v_lshl_add_u64 v[52:53], v[52:53], 0, v[2:3]
	s_waitcnt lgkmcnt(0)
	v_add_f32_e32 v54, v54, v55
	v_fmamk_f32 v54, v54, 0x3a000000, v226
	v_rsq_f32_e32 v56, v54
	v_lshlrev_b64 v[54:55], 7, v[46:47]
	v_lshl_add_u64 v[54:55], v[204:205], 0, v[54:55]
	v_pk_mul_f32 v[38:39], v[38:39], v[56:57] op_sel_hi:[1,0]
	v_pk_mul_f32 v[58:59], v[64:65], v[56:57] op_sel_hi:[1,0]
	v_pk_mul_f32 v[40:41], v[40:41], v[56:57] op_sel_hi:[1,0]
	v_pk_mul_f32 v[48:49], v[48:49], v[56:57] op_sel_hi:[1,0]
	v_pk_mul_f32 v[42:43], v[42:43], v[56:57] op_sel_hi:[1,0]
	v_pk_mul_f32 v[50:51], v[50:51], v[56:57] op_sel_hi:[1,0]
	v_pk_mul_f32 v[36:37], v[36:37], v[56:57] op_sel_hi:[1,0]
	v_pk_mul_f32 v[44:45], v[44:45], v[56:57] op_sel_hi:[1,0]
	v_mul_f32_e32 v66, 0xbfb8aa3b, v39
	v_mul_f32_e32 v47, 0xbfb8aa3b, v59
	v_mul_f32_e32 v56, 0xbfb8aa3b, v41
	v_mul_f32_e32 v57, 0xbfb8aa3b, v49
	v_mul_f32_e32 v62, 0xbfb8aa3b, v43
	v_mul_f32_e32 v63, 0xbfb8aa3b, v51
	v_mul_f32_e32 v64, 0xbfb8aa3b, v37
	v_mul_f32_e32 v65, 0xbfb8aa3b, v45
	v_exp_f32_e32 v66, v66
	v_exp_f32_e32 v47, v47
	v_exp_f32_e32 v56, v56
	v_exp_f32_e32 v57, v57
	v_exp_f32_e32 v62, v62
	v_exp_f32_e32 v63, v63
	v_exp_f32_e32 v64, v64
	v_exp_f32_e32 v65, v65
	v_add_f32_e32 v66, 1.0, v66
	v_add_f32_e32 v47, 1.0, v47
	v_add_f32_e32 v56, 1.0, v56
	v_add_f32_e32 v57, 1.0, v57
	v_add_f32_e32 v62, 1.0, v62
	v_add_f32_e32 v63, 1.0, v63
	v_add_f32_e32 v64, 1.0, v64
	v_add_f32_e32 v65, 1.0, v65
	v_rcp_f32_e32 v66, v66
	v_rcp_f32_e32 v47, v47
	v_rcp_f32_e32 v56, v56
	v_rcp_f32_e32 v57, v57
	v_rcp_f32_e32 v62, v62
	v_rcp_f32_e32 v63, v63
	v_rcp_f32_e32 v64, v64
	v_rcp_f32_e32 v65, v65
	v_mul_f32_e32 v39, v39, v66
	v_mul_f32_e32 v47, v59, v47
	v_mul_f32_e32 v41, v41, v56
	v_mul_f32_e32 v49, v49, v57
	v_mul_f32_e32 v43, v43, v62
	v_mul_f32_e32 v51, v51, v63
	v_mul_f32_e32 v37, v37, v64
	v_mul_f32_e32 v45, v45, v65
	v_mul_f32_e32 v39, v38, v39
	v_mul_f32_e32 v47, v58, v47
	v_mul_f32_e32 v40, v40, v41
	v_mul_f32_e32 v41, v48, v49
	v_mul_f32_e32 v42, v42, v43
	v_mul_f32_e32 v43, v50, v51
	v_mul_f32_e32 v48, v36, v37
	v_mul_f32_e32 v44, v44, v45
	v_cvt_pk_bf16_f32 v36, v47, v40
	v_cvt_pk_bf16_f32 v37, v41, v42
	v_cvt_pk_bf16_f32 v38, v43, v48
	v_cvt_pk_bf16_f32 v39, v44, v39
	global_store_dwordx4 v[52:53], v[36:39], off
	global_load_dwordx4 v[36:39], v[54:55], off
	global_load_dwordx4 v[40:43], v[54:55], off offset:16
	v_mov_b32_e32 v45, v24
	v_mov_b32_e32 v24, v33
	v_mov_b32_e32 v33, v26
	v_mov_b32_e32 v26, v35
	v_mov_b32_e32 v35, v20
	v_mov_b32_e32 v44, v32
	v_mov_b32_e32 v32, v34
	v_mov_b32_e32 v34, v28
	v_mov_b32_e32 v28, v30
	v_add_u32_e32 v30, 0xb0, v132
	s_waitcnt vmcnt(1)
	v_mov_b32_e32 v48, v36
	s_waitcnt vmcnt(0)
	v_mov_b32_e32 v49, v40
	v_mov_b32_e32 v40, v37
	v_mov_b32_e32 v36, v38
	v_mov_b32_e32 v37, v42
	v_mov_b32_e32 v42, v39
	v_pk_add_f32 v[38:39], v[48:49], v[40:41]
	v_pk_add_f32 v[36:37], v[36:37], v[42:43]
	s_nop 0
	v_pk_add_f32 v[36:37], v[38:39], v[36:37]
	s_nop 0
	v_add_f32_e32 v20, 0, v36
	v_add_f32_e32 v36, v20, v37
	ds_bpermute_b32 v37, v126, v36
	v_mov_b32_e32 v20, v29
	v_mov_b32_e32 v29, v22
	v_mov_b32_e32 v22, v31
	v_ashrrev_i32_e32 v31, 31, v30
	s_waitcnt lgkmcnt(0)
	v_add_f32_e32 v38, v36, v37
	ds_bpermute_b32 v39, v1, v38
	v_mad_i64_i32 v[36:37], s[10:11], v46, s72, v[60:61]
	v_lshl_add_u64 v[36:37], v[36:37], 0, v[2:3]
	s_waitcnt lgkmcnt(0)
	v_add_f32_e32 v38, v38, v39
	v_fmamk_f32 v38, v38, 0x3a000000, v226
	v_rsq_f32_e32 v40, v38
	v_lshlrev_b64 v[38:39], 7, v[30:31]
	v_lshl_add_u64 v[38:39], v[204:205], 0, v[38:39]
	v_pk_mul_f32 v[22:23], v[22:23], v[40:41] op_sel_hi:[1,0]
	v_pk_mul_f32 v[42:43], v[44:45], v[40:41] op_sel_hi:[1,0]
	v_pk_mul_f32 v[24:25], v[24:25], v[40:41] op_sel_hi:[1,0]
	v_pk_mul_f32 v[32:33], v[32:33], v[40:41] op_sel_hi:[1,0]
	v_pk_mul_f32 v[26:27], v[26:27], v[40:41] op_sel_hi:[1,0]
	v_pk_mul_f32 v[34:35], v[34:35], v[40:41] op_sel_hi:[1,0]
	v_pk_mul_f32 v[20:21], v[20:21], v[40:41] op_sel_hi:[1,0]
	v_pk_mul_f32 v[28:29], v[28:29], v[40:41] op_sel_hi:[1,0]
	v_mul_f32_e32 v48, 0xbfb8aa3b, v23
	v_mul_f32_e32 v31, 0xbfb8aa3b, v43
	v_mul_f32_e32 v40, 0xbfb8aa3b, v25
	v_mul_f32_e32 v41, 0xbfb8aa3b, v33
	v_mul_f32_e32 v44, 0xbfb8aa3b, v27
	v_mul_f32_e32 v45, 0xbfb8aa3b, v35
	v_mul_f32_e32 v46, 0xbfb8aa3b, v21
	v_mul_f32_e32 v47, 0xbfb8aa3b, v29
	v_exp_f32_e32 v48, v48
	v_exp_f32_e32 v31, v31
	v_exp_f32_e32 v40, v40
	v_exp_f32_e32 v41, v41
	v_exp_f32_e32 v44, v44
	v_exp_f32_e32 v45, v45
	v_exp_f32_e32 v46, v46
	v_exp_f32_e32 v47, v47
	v_add_f32_e32 v48, 1.0, v48
	v_add_f32_e32 v31, 1.0, v31
	v_add_f32_e32 v40, 1.0, v40
	v_add_f32_e32 v41, 1.0, v41
	v_add_f32_e32 v44, 1.0, v44
	v_add_f32_e32 v45, 1.0, v45
	v_add_f32_e32 v46, 1.0, v46
	v_add_f32_e32 v47, 1.0, v47
	v_rcp_f32_e32 v48, v48
	v_rcp_f32_e32 v31, v31
	v_rcp_f32_e32 v40, v40
	v_rcp_f32_e32 v41, v41
	v_rcp_f32_e32 v44, v44
	v_rcp_f32_e32 v45, v45
	v_rcp_f32_e32 v46, v46
	v_rcp_f32_e32 v47, v47
	v_mul_f32_e32 v23, v23, v48
	v_mul_f32_e32 v31, v43, v31
	v_mul_f32_e32 v25, v25, v40
	v_mul_f32_e32 v33, v33, v41
	v_mul_f32_e32 v27, v27, v44
	v_mul_f32_e32 v35, v35, v45
	v_mul_f32_e32 v21, v21, v46
	v_mul_f32_e32 v29, v29, v47
	v_mul_f32_e32 v23, v22, v23
	v_mul_f32_e32 v31, v42, v31
	v_mul_f32_e32 v24, v24, v25
	v_mul_f32_e32 v25, v32, v33
	v_mul_f32_e32 v26, v26, v27
	v_mul_f32_e32 v27, v34, v35
	v_mul_f32_e32 v32, v20, v21
	v_mul_f32_e32 v28, v28, v29
	v_cvt_pk_bf16_f32 v20, v31, v24
	v_cvt_pk_bf16_f32 v21, v25, v26
	v_cvt_pk_bf16_f32 v22, v27, v32
	v_cvt_pk_bf16_f32 v23, v28, v23
	global_store_dwordx4 v[36:37], v[20:23], off
	global_load_dwordx4 v[20:23], v[38:39], off
	global_load_dwordx4 v[24:27], v[38:39], off offset:16
	v_mov_b32_e32 v28, v16
	v_mov_b32_e32 v29, v8
	v_mov_b32_e32 v8, v17
	s_waitcnt vmcnt(1)
	v_mov_b32_e32 v16, v20
	s_waitcnt vmcnt(0)
	v_mov_b32_e32 v17, v24
	v_mov_b32_e32 v24, v21
	v_mov_b32_e32 v20, v22
	v_mov_b32_e32 v21, v26
	v_mov_b32_e32 v26, v23
	v_pk_add_f32 v[16:17], v[16:17], v[24:25]
	v_pk_add_f32 v[20:21], v[20:21], v[26:27]
	s_nop 0
	v_pk_add_f32 v[16:17], v[16:17], v[20:21]
	s_nop 0
	v_add_f32_e32 v16, 0, v16
	v_add_f32_e32 v20, v16, v17
	ds_bpermute_b32 v21, v126, v20
	v_mov_b32_e32 v17, v10
	v_mov_b32_e32 v10, v19
	v_mov_b32_e32 v19, v4
	v_mov_b32_e32 v4, v13
	s_waitcnt lgkmcnt(0)
	v_add_f32_e32 v20, v20, v21
	ds_bpermute_b32 v1, v1, v20
	v_mov_b32_e32 v13, v6
	v_mov_b32_e32 v16, v18
	v_mov_b32_e32 v18, v12
	v_mov_b32_e32 v12, v14
	s_waitcnt lgkmcnt(0)
	v_add_f32_e32 v1, v20, v1
	v_fmamk_f32 v1, v1, 0x3a000000, v226
	v_rsq_f32_e32 v20, v1
	v_mov_b32_e32 v6, v15
	v_mad_i64_i32 v[14:15], s[10:11], v30, s72, v[60:61]
	v_pk_mul_f32 v[6:7], v[6:7], v[20:21] op_sel_hi:[1,0]
	v_pk_mul_f32 v[22:23], v[28:29], v[20:21] op_sel_hi:[1,0]
	v_pk_mul_f32 v[8:9], v[8:9], v[20:21] op_sel_hi:[1,0]
	v_pk_mul_f32 v[16:17], v[16:17], v[20:21] op_sel_hi:[1,0]
	v_pk_mul_f32 v[10:11], v[10:11], v[20:21] op_sel_hi:[1,0]
	v_pk_mul_f32 v[18:19], v[18:19], v[20:21] op_sel_hi:[1,0]
	v_pk_mul_f32 v[4:5], v[4:5], v[20:21] op_sel_hi:[1,0]
	v_pk_mul_f32 v[12:13], v[12:13], v[20:21] op_sel_hi:[1,0]
	v_mul_f32_e32 v28, 0xbfb8aa3b, v7
	v_mul_f32_e32 v1, 0xbfb8aa3b, v23
	v_mul_f32_e32 v20, 0xbfb8aa3b, v9
	v_mul_f32_e32 v21, 0xbfb8aa3b, v17
	v_mul_f32_e32 v24, 0xbfb8aa3b, v11
	v_mul_f32_e32 v25, 0xbfb8aa3b, v19
	v_mul_f32_e32 v26, 0xbfb8aa3b, v5
	v_mul_f32_e32 v27, 0xbfb8aa3b, v13
	v_exp_f32_e32 v28, v28
	v_exp_f32_e32 v1, v1
	v_exp_f32_e32 v20, v20
	v_exp_f32_e32 v21, v21
	v_exp_f32_e32 v24, v24
	v_exp_f32_e32 v25, v25
	v_exp_f32_e32 v26, v26
	v_exp_f32_e32 v27, v27
	v_add_f32_e32 v28, 1.0, v28
	v_add_f32_e32 v1, 1.0, v1
	v_add_f32_e32 v20, 1.0, v20
	v_add_f32_e32 v21, 1.0, v21
	v_add_f32_e32 v24, 1.0, v24
	v_add_f32_e32 v25, 1.0, v25
	v_add_f32_e32 v26, 1.0, v26
	v_add_f32_e32 v27, 1.0, v27
	v_rcp_f32_e32 v28, v28
	v_rcp_f32_e32 v1, v1
	v_rcp_f32_e32 v20, v20
	v_rcp_f32_e32 v21, v21
	v_rcp_f32_e32 v24, v24
	v_rcp_f32_e32 v25, v25
	v_rcp_f32_e32 v26, v26
	v_rcp_f32_e32 v27, v27
	v_mul_f32_e32 v7, v7, v28
	v_mul_f32_e32 v1, v23, v1
	v_mul_f32_e32 v9, v9, v20
	v_mul_f32_e32 v17, v17, v21
	v_mul_f32_e32 v11, v11, v24
	v_mul_f32_e32 v19, v19, v25
	v_mul_f32_e32 v5, v5, v26
	v_mul_f32_e32 v13, v13, v27
	v_mul_f32_e32 v7, v6, v7
	v_lshl_add_u64 v[2:3], v[14:15], 0, v[2:3]
	v_mul_f32_e32 v1, v22, v1
	v_mul_f32_e32 v8, v8, v9
	v_mul_f32_e32 v9, v16, v17
	v_mul_f32_e32 v10, v10, v11
	v_mul_f32_e32 v11, v18, v19
	v_mul_f32_e32 v16, v4, v5
	v_mul_f32_e32 v12, v12, v13
	v_cvt_pk_bf16_f32 v4, v1, v8
	v_cvt_pk_bf16_f32 v5, v9, v10
	v_cvt_pk_bf16_f32 v6, v11, v16
	v_cvt_pk_bf16_f32 v7, v12, v7
	global_store_dwordx4 v[2:3], v[4:7], off
	s_andn2_b64 vcc, exec, s[26:27]
	s_mov_b64 s[10:11], -1
	s_cbranch_vccnz .LBB0_422

.LBB0_620:
	v_lshl_add_u32 v148, s54, 8, v156
	v_ashrrev_i32_e32 v149, 31, v148
	v_lshlrev_b64 v[150:151], 7, v[148:149]
	v_lshl_add_u64 v[146:147], v[136:137], 0, v[150:151]
	global_load_dwordx4 v[166:169], v[146:147], off
	global_load_dwordx4 v[170:173], v[146:147], off offset:16
	v_lshl_or_b32 v146, s14, 8, v158
	v_ashrrev_i32_e32 v147, 31, v146
	v_lshlrev_b64 v[152:153], 11, v[148:149]
	v_lshl_add_u64 v[152:153], v[152:153], 0, v[146:147]
	v_lshlrev_b64 v[152:153], 1, v[152:153]
	v_lshl_add_u64 v[154:155], s[12:13], 0, v[152:153]
	global_load_dwordx4 v[174:177], v[154:155], off
	v_lshl_add_u64 v[154:155], s[22:23], 0, v[152:153]
	global_load_dwordx4 v[178:181], v[154:155], off
	v_and_b32_e32 v154, 64, v162
	v_xor_b32_e32 v149, 16, v162
	v_add_u32_e32 v154, 64, v154
	v_cmp_lt_i32_e32 vcc, v149, v154
	v_xor_b32_e32 v155, 32, v162
	s_lshl_b32 s54, s14, 2
	v_cndmask_b32_e32 v149, v162, v149, vcc
	v_lshlrev_b32_e32 v164, 2, v149
	v_cmp_lt_i32_e32 vcc, v155, v154
	s_ashr_i32 s55, s54, 31
	s_waitcnt vmcnt(0)
	v_mov_b32_e32 v184, v166
	v_mov_b32_e32 v185, v170
	v_mov_b32_e32 v170, v167
	v_mov_b32_e32 v166, v168
	v_mov_b32_e32 v167, v172
	v_mov_b32_e32 v172, v169
	v_pk_add_f32 v[168:169], v[184:185], v[170:171]
	v_pk_add_f32 v[166:167], v[166:167], v[172:173]
	v_lshlrev_b32_e32 v170, 16, v175
	v_pk_add_f32 v[166:167], v[168:169], v[166:167]
	v_and_b32_e32 v171, 0xffff0000, v175
	v_add_f32_e32 v165, 0, v166
	v_add_f32_e32 v165, v165, v167
	ds_bpermute_b32 v175, v164, v165
	v_cndmask_b32_e32 v154, v162, v155, vcc
	v_lshlrev_b32_e32 v149, 2, v154
	v_lshlrev_b32_e32 v172, 16, v176
	v_and_b32_e32 v173, 0xffff0000, v176
	s_waitcnt lgkmcnt(0)
	v_add_f32_e32 v165, v165, v175
	ds_bpermute_b32 v184, v149, v165
	v_lshlrev_b32_e32 v166, 16, v177
	v_and_b32_e32 v167, 0xffff0000, v177
	v_lshlrev_b32_e32 v176, 16, v179
	v_and_b32_e32 v177, 0xffff0000, v179
	s_waitcnt lgkmcnt(0)
	v_add_f32_e32 v165, v165, v184
	v_fmamk_f32 v165, v165, 0x3a000000, v163
	v_lshl_add_u64 v[154:155], s[18:19], 0, v[152:153]
	v_or_b32_e32 v152, 0x100, v152
	v_rsq_f32_e32 v165, v165
	v_lshlrev_b32_e32 v168, 16, v174
	v_and_b32_e32 v169, 0xffff0000, v174
	v_lshlrev_b32_e32 v174, 16, v178
	v_mul_f32_e32 v126, v126, v165
	v_mul_f32_e32 v127, v127, v165
	v_mul_f32_e32 v122, v122, v165
	v_mul_f32_e32 v123, v123, v165
	v_mul_f32_e32 v124, v124, v165
	v_mul_f32_e32 v125, v125, v165
	v_mul_f32_e32 v120, v120, v165
	v_mul_f32_e32 v121, v121, v165
	v_mul_f32_e32 v126, 0xbfb8aa3b, v126
	v_mul_f32_e32 v127, 0xbfb8aa3b, v127
	v_mul_f32_e32 v122, 0xbfb8aa3b, v122
	v_mul_f32_e32 v123, 0xbfb8aa3b, v123
	v_mul_f32_e32 v124, 0xbfb8aa3b, v124
	v_mul_f32_e32 v125, 0xbfb8aa3b, v125
	v_mul_f32_e32 v120, 0xbfb8aa3b, v120
	v_mul_f32_e32 v121, 0xbfb8aa3b, v121
	v_exp_f32_e32 v126, v126
	v_exp_f32_e32 v127, v127
	v_exp_f32_e32 v122, v122
	v_exp_f32_e32 v123, v123
	v_exp_f32_e32 v124, v124
	v_exp_f32_e32 v125, v125
	v_exp_f32_e32 v120, v120
	v_exp_f32_e32 v121, v121
	v_add_f32_e32 v126, 1.0, v126
	v_add_f32_e32 v127, 1.0, v127
	v_add_f32_e32 v186, 1.0, v122
	v_add_f32_e32 v187, 1.0, v123
	v_add_f32_e32 v124, 1.0, v124
	v_add_f32_e32 v125, 1.0, v125
	v_add_f32_e32 v184, 1.0, v120
	v_add_f32_e32 v185, 1.0, v121
	v_rcp_f32_e32 v122, v126
	v_rcp_f32_e32 v123, v127
	v_rcp_f32_e32 v126, v186
	v_rcp_f32_e32 v127, v187
	v_rcp_f32_e32 v120, v124
	v_rcp_f32_e32 v121, v125
	v_rcp_f32_e32 v124, v184
	v_rcp_f32_e32 v125, v185
	v_and_b32_e32 v175, 0xffff0000, v178
	v_lshlrev_b32_e32 v178, 16, v180
	v_and_b32_e32 v179, 0xffff0000, v180
	v_lshlrev_b32_e32 v180, 16, v181
	v_and_b32_e32 v181, 0xffff0000, v181
	v_lshl_add_u64 v[182:183], s[12:13], 0, v[152:153]
	v_pk_fma_f32 v[170:171], v[122:123], v[176:177], v[170:171]
	v_pk_fma_f32 v[176:177], v[126:127], v[180:181], v[166:167]
	v_lshl_add_u64 v[166:167], s[22:23], 0, v[152:153]
	v_pk_fma_f32 v[174:175], v[120:121], v[174:175], v[168:169]
	v_pk_fma_f32 v[172:173], v[124:125], v[178:179], v[172:173]
	v_cvt_pk_bf16_f32 v120, v174, v175
	v_cvt_pk_bf16_f32 v121, v170, v171
	v_mul_f32_e32 v116, v116, v165
	v_cvt_pk_bf16_f32 v122, v172, v173
	v_cvt_pk_bf16_f32 v123, v176, v177
	global_load_dwordx4 v[124:127], v[182:183], off
	v_mul_f32_e32 v117, v117, v165
	global_load_dwordx4 v[166:169], v[166:167], off
	v_mul_f32_e32 v118, v118, v165
	v_mul_f32_e32 v119, v119, v165
	v_mul_f32_e32 v112, v112, v165
	v_mul_f32_e32 v113, v113, v165
	v_mul_f32_e32 v114, v114, v165
	v_mul_f32_e32 v115, v115, v165
	v_mul_f32_e32 v116, 0xbfb8aa3b, v116
	v_mul_f32_e32 v117, 0xbfb8aa3b, v117
	v_mul_f32_e32 v118, 0xbfb8aa3b, v118
	v_mul_f32_e32 v119, 0xbfb8aa3b, v119
	v_mul_f32_e32 v112, 0xbfb8aa3b, v112
	v_mul_f32_e32 v113, 0xbfb8aa3b, v113
	v_mul_f32_e32 v114, 0xbfb8aa3b, v114
	v_mul_f32_e32 v115, 0xbfb8aa3b, v115
	v_exp_f32_e32 v116, v116
	v_exp_f32_e32 v117, v117
	v_exp_f32_e32 v118, v118
	v_exp_f32_e32 v119, v119
	v_exp_f32_e32 v112, v112
	v_exp_f32_e32 v113, v113
	v_exp_f32_e32 v114, v114
	v_exp_f32_e32 v115, v115
	v_add_f32_e32 v116, 1.0, v116
	v_add_f32_e32 v117, 1.0, v117
	v_add_f32_e32 v118, 1.0, v118
	v_add_f32_e32 v119, 1.0, v119
	v_add_f32_e32 v165, 1.0, v112
	v_add_f32_e32 v178, 1.0, v113
	v_add_f32_e32 v179, 1.0, v114
	v_add_f32_e32 v180, 1.0, v115
	v_rcp_f32_e32 v112, v116
	v_rcp_f32_e32 v113, v117
	v_rcp_f32_e32 v114, v118
	v_rcp_f32_e32 v115, v119
	v_rcp_f32_e32 v116, v165
	v_rcp_f32_e32 v117, v178
	v_rcp_f32_e32 v118, v179
	v_rcp_f32_e32 v119, v180
	v_mul_f32_e32 v165, v175, v175
	v_mul_f32_e32 v171, v171, v171
	v_mul_f32_e32 v173, v173, v173
	v_mul_f32_e32 v175, v177, v177
	v_fmac_f32_e32 v165, v174, v174
	v_fmac_f32_e32 v171, v170, v170
	v_fmac_f32_e32 v173, v172, v172
	v_fmac_f32_e32 v175, v176, v176
	v_add_f32_e32 v165, v165, v171
	v_add_f32_e32 v170, v173, v175
	v_add_f32_e32 v165, v165, v170
	global_store_dwordx4 v[154:155], v[120:123], off
	s_waitcnt vmcnt(2)
	v_lshlrev_b32_e32 v170, 16, v124
	v_and_b32_e32 v171, 0xffff0000, v124
	v_lshlrev_b32_e32 v124, 16, v125
	v_and_b32_e32 v125, 0xffff0000, v125
	v_lshlrev_b32_e32 v172, 16, v126
	v_and_b32_e32 v173, 0xffff0000, v126
	v_lshlrev_b32_e32 v126, 16, v127
	v_and_b32_e32 v127, 0xffff0000, v127
	s_waitcnt vmcnt(1)
	v_lshlrev_b32_e32 v174, 16, v166
	v_and_b32_e32 v175, 0xffff0000, v166
	v_lshlrev_b32_e32 v166, 16, v167
	v_and_b32_e32 v167, 0xffff0000, v167
	v_lshlrev_b32_e32 v176, 16, v168
	v_and_b32_e32 v177, 0xffff0000, v168
	v_lshlrev_b32_e32 v168, 16, v169
	v_and_b32_e32 v169, 0xffff0000, v169
	v_pk_fma_f32 v[124:125], v[114:115], v[166:167], v[124:125]
	v_pk_fma_f32 v[112:113], v[112:113], v[174:175], v[170:171]
	v_pk_fma_f32 v[118:119], v[118:119], v[168:169], v[126:127]
	v_pk_fma_f32 v[116:117], v[116:117], v[176:177], v[172:173]
	v_mul_f32_e32 v114, v113, v113
	v_mul_f32_e32 v115, v125, v125
	v_mul_f32_e32 v126, v117, v117
	v_mul_f32_e32 v127, v119, v119
	v_fmac_f32_e32 v114, v112, v112
	v_fmac_f32_e32 v115, v124, v124
	v_fmac_f32_e32 v126, v116, v116
	v_fmac_f32_e32 v127, v118, v118
	v_add_f32_e32 v114, v114, v115
	v_add_f32_e32 v115, v126, v127
	v_add_f32_e32 v114, v114, v115
	v_add_f32_e32 v126, v165, v114
	ds_bpermute_b32 v127, v164, v126
	v_cvt_pk_bf16_f32 v114, v112, v113
	v_cvt_pk_bf16_f32 v115, v124, v125
	v_cvt_pk_bf16_f32 v116, v116, v117
	v_cvt_pk_bf16_f32 v117, v118, v119
	s_waitcnt lgkmcnt(0)
	v_add_f32_e32 v112, v126, v127
	ds_bpermute_b32 v113, v149, v112
	v_lshl_add_u64 v[118:119], s[18:19], 0, v[152:153]
	global_store_dwordx4 v[118:119], v[114:117], off
	s_and_saveexec_b64 s[56:57], s[8:9]
	s_cbranch_execz .LBB0_622
	s_waitcnt lgkmcnt(0)
	v_add_f32_e32 v114, v112, v113
	v_lshl_add_u64 v[112:113], s[20:21], 0, v[150:151]
	v_lshl_add_u64 v[112:113], s[54:55], 2, v[112:113]
	s_lshl_b32 s14, s63, 2
	v_lshl_add_u64 v[112:113], v[112:113], 0, s[14:15]
	global_store_dword v[112:113], v114, off
.LBB0_622:
	s_or_b64 exec, exec, s[56:57]
	v_or_b32_e32 v114, 16, v148
	v_ashrrev_i32_e32 v115, 31, v114
	s_waitcnt lgkmcnt(0)
	v_lshlrev_b64 v[112:113], 7, v[114:115]
	v_lshl_add_u64 v[116:117], v[136:137], 0, v[112:113]
	global_load_dwordx4 v[118:121], v[116:117], off
	global_load_dwordx4 v[122:125], v[116:117], off offset:16
	v_lshlrev_b64 v[114:115], 11, v[114:115]
	v_lshl_add_u64 v[114:115], v[114:115], 0, v[146:147]
	v_lshlrev_b64 v[114:115], 1, v[114:115]
	v_lshl_add_u64 v[116:117], s[12:13], 0, v[114:115]
	global_load_dwordx4 v[150:153], v[116:117], off
	v_lshl_add_u64 v[116:117], s[22:23], 0, v[114:115]
	global_load_dwordx4 v[166:169], v[116:117], off
	v_lshl_add_u64 v[116:117], s[18:19], 0, v[114:115]
	v_or_b32_e32 v114, 0x100, v114
	v_lshl_add_u64 v[126:127], s[12:13], 0, v[114:115]
	s_waitcnt vmcnt(3)
	v_mov_b32_e32 v154, v118
	s_waitcnt vmcnt(2)
	v_mov_b32_e32 v155, v122
	v_mov_b32_e32 v122, v119
	v_mov_b32_e32 v118, v120
	v_mov_b32_e32 v119, v124
	v_mov_b32_e32 v124, v121
	v_pk_add_f32 v[120:121], v[154:155], v[122:123]
	v_pk_add_f32 v[118:119], v[118:119], v[124:125]
	s_waitcnt vmcnt(1)
	v_lshlrev_b32_e32 v122, 16, v151
	v_pk_add_f32 v[118:119], v[120:121], v[118:119]
	v_and_b32_e32 v123, 0xffff0000, v151
	v_add_f32_e32 v118, 0, v118
	v_add_f32_e32 v151, v118, v119
	ds_bpermute_b32 v154, v164, v151
	v_lshlrev_b32_e32 v120, 16, v150
	v_and_b32_e32 v121, 0xffff0000, v150
	v_lshlrev_b32_e32 v124, 16, v152
	v_and_b32_e32 v125, 0xffff0000, v152
	s_waitcnt lgkmcnt(0)
	v_add_f32_e32 v155, v151, v154
	ds_bpermute_b32 v165, v149, v155
	s_waitcnt vmcnt(0)
	v_lshlrev_b32_e32 v154, 16, v168
	v_lshlrev_b32_e32 v118, 16, v153
	v_and_b32_e32 v119, 0xffff0000, v153
	v_lshlrev_b32_e32 v150, 16, v166
	s_waitcnt lgkmcnt(0)
	v_add_f32_e32 v155, v155, v165
	v_fmamk_f32 v155, v155, 0x3a000000, v163
	v_and_b32_e32 v151, 0xffff0000, v166
	v_lshlrev_b32_e32 v152, 16, v167
	v_rsq_f32_e32 v165, v155
	v_and_b32_e32 v155, 0xffff0000, v168
	v_and_b32_e32 v153, 0xffff0000, v167
	v_lshlrev_b32_e32 v166, 16, v169
	v_mul_f32_e32 v110, v110, v165
	v_mul_f32_e32 v111, v111, v165
	v_mul_f32_e32 v106, v106, v165
	v_mul_f32_e32 v107, v107, v165
	v_mul_f32_e32 v108, v108, v165
	v_mul_f32_e32 v109, v109, v165
	v_mul_f32_e32 v104, v104, v165
	v_mul_f32_e32 v105, v105, v165
	v_mul_f32_e32 v110, 0xbfb8aa3b, v110
	v_mul_f32_e32 v111, 0xbfb8aa3b, v111
	v_mul_f32_e32 v106, 0xbfb8aa3b, v106
	v_mul_f32_e32 v107, 0xbfb8aa3b, v107
	v_mul_f32_e32 v108, 0xbfb8aa3b, v108
	v_mul_f32_e32 v109, 0xbfb8aa3b, v109
	v_mul_f32_e32 v104, 0xbfb8aa3b, v104
	v_mul_f32_e32 v105, 0xbfb8aa3b, v105
	v_exp_f32_e32 v110, v110
	v_exp_f32_e32 v111, v111
	v_exp_f32_e32 v106, v106
	v_exp_f32_e32 v107, v107
	v_exp_f32_e32 v108, v108
	v_exp_f32_e32 v109, v109
	v_exp_f32_e32 v104, v104
	v_exp_f32_e32 v105, v105
	v_add_f32_e32 v110, 1.0, v110
	v_add_f32_e32 v111, 1.0, v111
	v_add_f32_e32 v170, 1.0, v106
	v_add_f32_e32 v171, 1.0, v107
	v_and_b32_e32 v167, 0xffff0000, v169
	v_add_f32_e32 v108, 1.0, v108
	v_add_f32_e32 v109, 1.0, v109
	v_add_f32_e32 v168, 1.0, v104
	v_add_f32_e32 v169, 1.0, v105
	v_rcp_f32_e32 v106, v110
	v_rcp_f32_e32 v107, v111
	v_rcp_f32_e32 v110, v170
	v_rcp_f32_e32 v111, v171
	v_rcp_f32_e32 v104, v108
	v_rcp_f32_e32 v105, v109
	v_rcp_f32_e32 v108, v168
	v_rcp_f32_e32 v109, v169
	v_pk_fma_f32 v[122:123], v[106:107], v[152:153], v[122:123]
	v_pk_fma_f32 v[152:153], v[110:111], v[166:167], v[118:119]
	v_lshl_add_u64 v[118:119], s[22:23], 0, v[114:115]
	v_pk_fma_f32 v[150:151], v[104:105], v[150:151], v[120:121]
	v_pk_fma_f32 v[124:125], v[108:109], v[154:155], v[124:125]
	v_cvt_pk_bf16_f32 v104, v150, v151
	v_cvt_pk_bf16_f32 v105, v122, v123
	v_mul_f32_e32 v100, v100, v165
	v_cvt_pk_bf16_f32 v106, v124, v125
	v_cvt_pk_bf16_f32 v107, v152, v153
	global_load_dwordx4 v[108:111], v[126:127], off
	v_mul_f32_e32 v101, v101, v165
	global_load_dwordx4 v[118:121], v[118:119], off
	v_mul_f32_e32 v102, v102, v165
	v_mul_f32_e32 v103, v103, v165
	v_mul_f32_e32 v96, v96, v165
	v_mul_f32_e32 v97, v97, v165
	v_mul_f32_e32 v98, v98, v165
	v_mul_f32_e32 v99, v99, v165
	v_mul_f32_e32 v100, 0xbfb8aa3b, v100
	v_mul_f32_e32 v101, 0xbfb8aa3b, v101
	v_mul_f32_e32 v102, 0xbfb8aa3b, v102
	v_mul_f32_e32 v103, 0xbfb8aa3b, v103
	v_mul_f32_e32 v96, 0xbfb8aa3b, v96
	v_mul_f32_e32 v97, 0xbfb8aa3b, v97
	v_mul_f32_e32 v98, 0xbfb8aa3b, v98
	v_mul_f32_e32 v99, 0xbfb8aa3b, v99
	v_exp_f32_e32 v100, v100
	v_exp_f32_e32 v101, v101
	v_exp_f32_e32 v102, v102
	v_exp_f32_e32 v103, v103
	v_exp_f32_e32 v96, v96
	v_exp_f32_e32 v97, v97
	v_exp_f32_e32 v98, v98
	v_exp_f32_e32 v99, v99
	v_add_f32_e32 v100, 1.0, v100
	v_add_f32_e32 v101, 1.0, v101
	v_add_f32_e32 v102, 1.0, v102
	v_add_f32_e32 v103, 1.0, v103
	v_add_f32_e32 v126, 1.0, v96
	v_add_f32_e32 v127, 1.0, v97
	v_add_f32_e32 v154, 1.0, v98
	v_add_f32_e32 v155, 1.0, v99
	v_rcp_f32_e32 v96, v100
	v_rcp_f32_e32 v97, v101
	v_rcp_f32_e32 v98, v102
	v_rcp_f32_e32 v99, v103
	v_rcp_f32_e32 v100, v126
	v_rcp_f32_e32 v101, v127
	v_rcp_f32_e32 v102, v154
	v_rcp_f32_e32 v103, v155
	v_mul_f32_e32 v126, v151, v151
	v_mul_f32_e32 v123, v123, v123
	v_mul_f32_e32 v125, v125, v125
	v_mul_f32_e32 v127, v153, v153
	v_fmac_f32_e32 v126, v150, v150
	v_fmac_f32_e32 v123, v122, v122
	v_fmac_f32_e32 v125, v124, v124
	v_fmac_f32_e32 v127, v152, v152
	v_add_f32_e32 v122, v126, v123
	v_add_f32_e32 v123, v125, v127
	v_add_f32_e32 v152, v122, v123
	global_store_dwordx4 v[116:117], v[104:107], off
	s_waitcnt vmcnt(2)
	v_lshlrev_b32_e32 v122, 16, v108
	v_and_b32_e32 v123, 0xffff0000, v108
	v_lshlrev_b32_e32 v108, 16, v109
	v_and_b32_e32 v109, 0xffff0000, v109
	v_lshlrev_b32_e32 v124, 16, v110
	v_and_b32_e32 v125, 0xffff0000, v110
	v_lshlrev_b32_e32 v110, 16, v111
	v_and_b32_e32 v111, 0xffff0000, v111
	s_waitcnt vmcnt(1)
	v_lshlrev_b32_e32 v126, 16, v118
	v_and_b32_e32 v127, 0xffff0000, v118
	v_lshlrev_b32_e32 v118, 16, v119
	v_and_b32_e32 v119, 0xffff0000, v119
	v_lshlrev_b32_e32 v150, 16, v120
	v_and_b32_e32 v151, 0xffff0000, v120
	v_lshlrev_b32_e32 v120, 16, v121
	v_and_b32_e32 v121, 0xffff0000, v121
	v_pk_fma_f32 v[108:109], v[98:99], v[118:119], v[108:109]
	v_pk_fma_f32 v[96:97], v[96:97], v[126:127], v[122:123]
	v_pk_fma_f32 v[102:103], v[102:103], v[120:121], v[110:111]
	v_pk_fma_f32 v[100:101], v[100:101], v[150:151], v[124:125]
	v_mul_f32_e32 v98, v97, v97
	v_mul_f32_e32 v99, v109, v109
	v_mul_f32_e32 v110, v101, v101
	v_mul_f32_e32 v111, v103, v103
	v_fmac_f32_e32 v98, v96, v96
	v_fmac_f32_e32 v99, v108, v108
	v_fmac_f32_e32 v110, v100, v100
	v_fmac_f32_e32 v111, v102, v102
	v_add_f32_e32 v98, v98, v99
	v_add_f32_e32 v99, v110, v111
	v_add_f32_e32 v98, v98, v99
	v_add_f32_e32 v110, v152, v98
	ds_bpermute_b32 v111, v164, v110
	v_cvt_pk_bf16_f32 v98, v96, v97
	v_cvt_pk_bf16_f32 v99, v108, v109
	v_cvt_pk_bf16_f32 v100, v100, v101
	v_cvt_pk_bf16_f32 v101, v102, v103
	s_waitcnt lgkmcnt(0)
	v_add_f32_e32 v96, v110, v111
	ds_bpermute_b32 v97, v149, v96
	v_lshl_add_u64 v[102:103], s[18:19], 0, v[114:115]
	global_store_dwordx4 v[102:103], v[98:101], off
	s_and_saveexec_b64 s[56:57], s[8:9]
	s_cbranch_execz .LBB0_624
	s_waitcnt lgkmcnt(0)
	v_add_f32_e32 v98, v96, v97
	v_lshl_add_u64 v[96:97], s[20:21], 0, v[112:113]
	v_lshl_add_u64 v[96:97], s[54:55], 2, v[96:97]
	s_lshl_b32 s14, s63, 2
	v_lshl_add_u64 v[96:97], v[96:97], 0, s[14:15]
	global_store_dword v[96:97], v98, off
.LBB0_624:
	s_or_b64 exec, exec, s[56:57]
	v_or_b32_e32 v98, 32, v148
	v_ashrrev_i32_e32 v99, 31, v98
	s_waitcnt lgkmcnt(0)
	v_lshlrev_b64 v[96:97], 7, v[98:99]
	v_lshl_add_u64 v[100:101], v[136:137], 0, v[96:97]
	global_load_dwordx4 v[102:105], v[100:101], off
	global_load_dwordx4 v[106:109], v[100:101], off offset:16
	v_lshlrev_b64 v[98:99], 11, v[98:99]
	v_lshl_add_u64 v[98:99], v[98:99], 0, v[146:147]
	v_lshlrev_b64 v[98:99], 1, v[98:99]
	v_lshl_add_u64 v[100:101], s[12:13], 0, v[98:99]
	global_load_dwordx4 v[110:113], v[100:101], off
	v_lshl_add_u64 v[100:101], s[22:23], 0, v[98:99]
	global_load_dwordx4 v[114:117], v[100:101], off
	v_lshl_add_u64 v[100:101], s[18:19], 0, v[98:99]
	v_or_b32_e32 v98, 0x100, v98
	v_lshl_add_u64 v[118:119], s[12:13], 0, v[98:99]
	s_waitcnt vmcnt(3)
	v_mov_b32_e32 v120, v102
	s_waitcnt vmcnt(2)
	v_mov_b32_e32 v121, v106
	v_mov_b32_e32 v106, v103
	v_mov_b32_e32 v102, v104
	v_mov_b32_e32 v103, v108
	v_mov_b32_e32 v108, v105
	v_pk_add_f32 v[104:105], v[120:121], v[106:107]
	v_pk_add_f32 v[102:103], v[102:103], v[108:109]
	s_waitcnt vmcnt(1)
	v_lshlrev_b32_e32 v106, 16, v111
	v_pk_add_f32 v[102:103], v[104:105], v[102:103]
	v_and_b32_e32 v107, 0xffff0000, v111
	v_add_f32_e32 v102, 0, v102
	v_add_f32_e32 v111, v102, v103
	ds_bpermute_b32 v120, v164, v111
	v_lshlrev_b32_e32 v108, 16, v112
	v_and_b32_e32 v109, 0xffff0000, v112
	v_lshlrev_b32_e32 v102, 16, v113
	v_and_b32_e32 v103, 0xffff0000, v113
	s_waitcnt lgkmcnt(0)
	v_add_f32_e32 v120, v111, v120
	ds_bpermute_b32 v121, v149, v120
	s_waitcnt vmcnt(0)
	v_lshlrev_b32_e32 v112, 16, v115
	v_and_b32_e32 v113, 0xffff0000, v115
	v_lshlrev_b32_e32 v104, 16, v110
	v_and_b32_e32 v105, 0xffff0000, v110
	s_waitcnt lgkmcnt(0)
	v_add_f32_e32 v115, v120, v121
	v_fmamk_f32 v115, v115, 0x3a000000, v163
	v_lshlrev_b32_e32 v110, 16, v114
	v_and_b32_e32 v111, 0xffff0000, v114
	v_rsq_f32_e32 v120, v115
	v_lshlrev_b32_e32 v114, 16, v116
	v_and_b32_e32 v115, 0xffff0000, v116
	v_lshlrev_b32_e32 v116, 16, v117
	v_mul_f32_e32 v94, v94, v120
	v_mul_f32_e32 v95, v95, v120
	v_mul_f32_e32 v90, v90, v120
	v_mul_f32_e32 v91, v91, v120
	v_mul_f32_e32 v92, v92, v120
	v_mul_f32_e32 v93, v93, v120
	v_mul_f32_e32 v88, v88, v120
	v_mul_f32_e32 v89, v89, v120
	v_mul_f32_e32 v94, 0xbfb8aa3b, v94
	v_mul_f32_e32 v95, 0xbfb8aa3b, v95
	v_mul_f32_e32 v90, 0xbfb8aa3b, v90
	v_mul_f32_e32 v91, 0xbfb8aa3b, v91
	v_mul_f32_e32 v92, 0xbfb8aa3b, v92
	v_mul_f32_e32 v93, 0xbfb8aa3b, v93
	v_mul_f32_e32 v88, 0xbfb8aa3b, v88
	v_mul_f32_e32 v89, 0xbfb8aa3b, v89
	v_exp_f32_e32 v94, v94
	v_exp_f32_e32 v95, v95
	v_exp_f32_e32 v90, v90
	v_exp_f32_e32 v91, v91
	v_exp_f32_e32 v92, v92
	v_exp_f32_e32 v93, v93
	v_exp_f32_e32 v88, v88
	v_exp_f32_e32 v89, v89
	v_add_f32_e32 v94, 1.0, v94
	v_add_f32_e32 v95, 1.0, v95
	v_add_f32_e32 v123, 1.0, v90
	v_add_f32_e32 v124, 1.0, v91
	v_add_f32_e32 v92, 1.0, v92
	v_add_f32_e32 v93, 1.0, v93
	v_add_f32_e32 v121, 1.0, v88
	v_add_f32_e32 v122, 1.0, v89
	v_rcp_f32_e32 v90, v94
	v_rcp_f32_e32 v91, v95
	v_rcp_f32_e32 v94, v123
	v_rcp_f32_e32 v95, v124
	v_rcp_f32_e32 v88, v92
	v_rcp_f32_e32 v89, v93
	v_rcp_f32_e32 v92, v121
	v_rcp_f32_e32 v93, v122
	v_and_b32_e32 v117, 0xffff0000, v117
	v_pk_fma_f32 v[106:107], v[90:91], v[112:113], v[106:107]
	v_pk_fma_f32 v[112:113], v[94:95], v[116:117], v[102:103]
	v_lshl_add_u64 v[102:103], s[22:23], 0, v[98:99]
	v_pk_fma_f32 v[110:111], v[88:89], v[110:111], v[104:105]
	v_pk_fma_f32 v[108:109], v[92:93], v[114:115], v[108:109]
	v_cvt_pk_bf16_f32 v88, v110, v111
	v_cvt_pk_bf16_f32 v89, v106, v107
	v_mul_f32_e32 v84, v84, v120
	v_cvt_pk_bf16_f32 v90, v108, v109
	v_cvt_pk_bf16_f32 v91, v112, v113
	global_load_dwordx4 v[92:95], v[118:119], off
	v_mul_f32_e32 v85, v85, v120
	global_load_dwordx4 v[102:105], v[102:103], off
	v_mul_f32_e32 v86, v86, v120
	v_mul_f32_e32 v87, v87, v120
	v_mul_f32_e32 v80, v80, v120
	v_mul_f32_e32 v81, v81, v120
	v_mul_f32_e32 v82, v82, v120
	v_mul_f32_e32 v83, v83, v120
	v_mul_f32_e32 v84, 0xbfb8aa3b, v84
	v_mul_f32_e32 v85, 0xbfb8aa3b, v85
	v_mul_f32_e32 v86, 0xbfb8aa3b, v86
	v_mul_f32_e32 v87, 0xbfb8aa3b, v87
	v_mul_f32_e32 v80, 0xbfb8aa3b, v80
	v_mul_f32_e32 v81, 0xbfb8aa3b, v81
	v_mul_f32_e32 v82, 0xbfb8aa3b, v82
	v_mul_f32_e32 v83, 0xbfb8aa3b, v83
	v_exp_f32_e32 v84, v84
	v_exp_f32_e32 v85, v85
	v_exp_f32_e32 v86, v86
	v_exp_f32_e32 v87, v87
	v_exp_f32_e32 v80, v80
	v_exp_f32_e32 v81, v81
	v_exp_f32_e32 v82, v82
	v_exp_f32_e32 v83, v83
	v_add_f32_e32 v84, 1.0, v84
	v_add_f32_e32 v85, 1.0, v85
	v_add_f32_e32 v86, 1.0, v86
	v_add_f32_e32 v87, 1.0, v87
	v_add_f32_e32 v114, 1.0, v80
	v_add_f32_e32 v115, 1.0, v81
	v_add_f32_e32 v116, 1.0, v82
	v_add_f32_e32 v117, 1.0, v83
	v_rcp_f32_e32 v80, v84
	v_rcp_f32_e32 v81, v85
	v_rcp_f32_e32 v82, v86
	v_rcp_f32_e32 v83, v87
	v_rcp_f32_e32 v84, v114
	v_rcp_f32_e32 v85, v115
	v_rcp_f32_e32 v86, v116
	v_rcp_f32_e32 v87, v117
	v_mul_f32_e32 v111, v111, v111
	v_mul_f32_e32 v107, v107, v107
	v_mul_f32_e32 v109, v109, v109
	v_mul_f32_e32 v113, v113, v113
	v_fmac_f32_e32 v111, v110, v110
	v_fmac_f32_e32 v107, v106, v106
	v_fmac_f32_e32 v109, v108, v108
	v_fmac_f32_e32 v113, v112, v112
	v_add_f32_e32 v106, v111, v107
	v_add_f32_e32 v107, v109, v113
	v_add_f32_e32 v114, v106, v107
	global_store_dwordx4 v[100:101], v[88:91], off
	s_waitcnt vmcnt(2)
	v_lshlrev_b32_e32 v106, 16, v92
	v_and_b32_e32 v107, 0xffff0000, v92
	v_lshlrev_b32_e32 v92, 16, v93
	v_and_b32_e32 v93, 0xffff0000, v93
	v_lshlrev_b32_e32 v108, 16, v94
	v_and_b32_e32 v109, 0xffff0000, v94
	v_lshlrev_b32_e32 v94, 16, v95
	v_and_b32_e32 v95, 0xffff0000, v95
	s_waitcnt vmcnt(1)
	v_lshlrev_b32_e32 v110, 16, v102
	v_and_b32_e32 v111, 0xffff0000, v102
	v_lshlrev_b32_e32 v102, 16, v103
	v_and_b32_e32 v103, 0xffff0000, v103
	v_lshlrev_b32_e32 v112, 16, v104
	v_and_b32_e32 v113, 0xffff0000, v104
	v_lshlrev_b32_e32 v104, 16, v105
	v_and_b32_e32 v105, 0xffff0000, v105
	v_pk_fma_f32 v[92:93], v[82:83], v[102:103], v[92:93]
	v_pk_fma_f32 v[80:81], v[80:81], v[110:111], v[106:107]
	v_pk_fma_f32 v[86:87], v[86:87], v[104:105], v[94:95]
	v_pk_fma_f32 v[84:85], v[84:85], v[112:113], v[108:109]
	v_mul_f32_e32 v82, v81, v81
	v_mul_f32_e32 v83, v93, v93
	v_mul_f32_e32 v94, v85, v85
	v_mul_f32_e32 v95, v87, v87
	v_fmac_f32_e32 v82, v80, v80
	v_fmac_f32_e32 v83, v92, v92
	v_fmac_f32_e32 v94, v84, v84
	v_fmac_f32_e32 v95, v86, v86
	v_add_f32_e32 v82, v82, v83
	v_add_f32_e32 v83, v94, v95
	v_add_f32_e32 v82, v82, v83
	v_add_f32_e32 v94, v114, v82
	ds_bpermute_b32 v95, v164, v94
	v_cvt_pk_bf16_f32 v82, v80, v81
	v_cvt_pk_bf16_f32 v83, v92, v93
	v_cvt_pk_bf16_f32 v84, v84, v85
	v_cvt_pk_bf16_f32 v85, v86, v87
	s_waitcnt lgkmcnt(0)
	v_add_f32_e32 v80, v94, v95
	ds_bpermute_b32 v81, v149, v80
	v_lshl_add_u64 v[86:87], s[18:19], 0, v[98:99]
	global_store_dwordx4 v[86:87], v[82:85], off
	s_and_saveexec_b64 s[56:57], s[8:9]
	s_cbranch_execz .LBB0_626
	s_waitcnt lgkmcnt(0)
	v_add_f32_e32 v82, v80, v81
	v_lshl_add_u64 v[80:81], s[20:21], 0, v[96:97]
	v_lshl_add_u64 v[80:81], s[54:55], 2, v[80:81]
	s_lshl_b32 s14, s63, 2
	v_lshl_add_u64 v[80:81], v[80:81], 0, s[14:15]
	global_store_dword v[80:81], v82, off
.LBB0_626:
	s_or_b64 exec, exec, s[56:57]
	v_or_b32_e32 v82, 48, v148
	v_ashrrev_i32_e32 v83, 31, v82
	s_waitcnt lgkmcnt(0)
	v_lshlrev_b64 v[80:81], 7, v[82:83]
	v_lshl_add_u64 v[84:85], v[136:137], 0, v[80:81]
	global_load_dwordx4 v[86:89], v[84:85], off
	global_load_dwordx4 v[90:93], v[84:85], off offset:16
	v_lshlrev_b64 v[82:83], 11, v[82:83]
	v_lshl_add_u64 v[82:83], v[82:83], 0, v[146:147]
	v_lshlrev_b64 v[82:83], 1, v[82:83]
	v_lshl_add_u64 v[84:85], s[12:13], 0, v[82:83]
	global_load_dwordx4 v[94:97], v[84:85], off
	v_lshl_add_u64 v[84:85], s[22:23], 0, v[82:83]
	global_load_dwordx4 v[98:101], v[84:85], off
	v_lshl_add_u64 v[84:85], s[18:19], 0, v[82:83]
	v_or_b32_e32 v82, 0x100, v82
	v_lshl_add_u64 v[102:103], s[12:13], 0, v[82:83]
	s_waitcnt vmcnt(3)
	v_mov_b32_e32 v104, v86
	s_waitcnt vmcnt(2)
	v_mov_b32_e32 v105, v90
	v_mov_b32_e32 v90, v87
	v_mov_b32_e32 v86, v88
	v_mov_b32_e32 v87, v92
	v_mov_b32_e32 v92, v89
	v_pk_add_f32 v[88:89], v[104:105], v[90:91]
	v_pk_add_f32 v[86:87], v[86:87], v[92:93]
	s_waitcnt vmcnt(1)
	v_lshlrev_b32_e32 v90, 16, v95
	v_pk_add_f32 v[86:87], v[88:89], v[86:87]
	v_and_b32_e32 v91, 0xffff0000, v95
	v_add_f32_e32 v86, 0, v86
	v_add_f32_e32 v95, v86, v87
	ds_bpermute_b32 v104, v164, v95
	v_lshlrev_b32_e32 v92, 16, v96
	v_and_b32_e32 v93, 0xffff0000, v96
	v_lshlrev_b32_e32 v86, 16, v97
	v_and_b32_e32 v87, 0xffff0000, v97
	s_waitcnt lgkmcnt(0)
	v_add_f32_e32 v104, v95, v104
	ds_bpermute_b32 v105, v149, v104
	s_waitcnt vmcnt(0)
	v_lshlrev_b32_e32 v96, 16, v99
	v_and_b32_e32 v97, 0xffff0000, v99
	v_lshlrev_b32_e32 v88, 16, v94
	v_and_b32_e32 v89, 0xffff0000, v94
	s_waitcnt lgkmcnt(0)
	v_add_f32_e32 v99, v104, v105
	v_fmamk_f32 v99, v99, 0x3a000000, v163
	v_lshlrev_b32_e32 v94, 16, v98
	v_and_b32_e32 v95, 0xffff0000, v98
	v_rsq_f32_e32 v104, v99
	v_lshlrev_b32_e32 v98, 16, v100
	v_and_b32_e32 v99, 0xffff0000, v100
	v_lshlrev_b32_e32 v100, 16, v101
	v_mul_f32_e32 v78, v78, v104
	v_mul_f32_e32 v79, v79, v104
	v_mul_f32_e32 v74, v74, v104
	v_mul_f32_e32 v75, v75, v104
	v_mul_f32_e32 v76, v76, v104
	v_mul_f32_e32 v77, v77, v104
	v_mul_f32_e32 v72, v72, v104
	v_mul_f32_e32 v73, v73, v104
	v_mul_f32_e32 v78, 0xbfb8aa3b, v78
	v_mul_f32_e32 v79, 0xbfb8aa3b, v79
	v_mul_f32_e32 v74, 0xbfb8aa3b, v74
	v_mul_f32_e32 v75, 0xbfb8aa3b, v75
	v_mul_f32_e32 v76, 0xbfb8aa3b, v76
	v_mul_f32_e32 v77, 0xbfb8aa3b, v77
	v_mul_f32_e32 v72, 0xbfb8aa3b, v72
	v_mul_f32_e32 v73, 0xbfb8aa3b, v73
	v_exp_f32_e32 v78, v78
	v_exp_f32_e32 v79, v79
	v_exp_f32_e32 v74, v74
	v_exp_f32_e32 v75, v75
	v_exp_f32_e32 v76, v76
	v_exp_f32_e32 v77, v77
	v_exp_f32_e32 v72, v72
	v_exp_f32_e32 v73, v73
	v_add_f32_e32 v78, 1.0, v78
	v_add_f32_e32 v79, 1.0, v79
	v_add_f32_e32 v107, 1.0, v74
	v_add_f32_e32 v108, 1.0, v75
	v_add_f32_e32 v76, 1.0, v76
	v_add_f32_e32 v77, 1.0, v77
	v_add_f32_e32 v105, 1.0, v72
	v_add_f32_e32 v106, 1.0, v73
	v_rcp_f32_e32 v74, v78
	v_rcp_f32_e32 v75, v79
	v_rcp_f32_e32 v78, v107
	v_rcp_f32_e32 v79, v108
	v_rcp_f32_e32 v72, v76
	v_rcp_f32_e32 v73, v77
	v_rcp_f32_e32 v76, v105
	v_rcp_f32_e32 v77, v106
	v_and_b32_e32 v101, 0xffff0000, v101
	v_pk_fma_f32 v[90:91], v[74:75], v[96:97], v[90:91]
	v_pk_fma_f32 v[96:97], v[78:79], v[100:101], v[86:87]
	v_lshl_add_u64 v[86:87], s[22:23], 0, v[82:83]
	v_pk_fma_f32 v[94:95], v[72:73], v[94:95], v[88:89]
	v_pk_fma_f32 v[92:93], v[76:77], v[98:99], v[92:93]
	v_cvt_pk_bf16_f32 v72, v94, v95
	v_cvt_pk_bf16_f32 v73, v90, v91
	v_mul_f32_e32 v68, v68, v104
	v_cvt_pk_bf16_f32 v74, v92, v93
	v_cvt_pk_bf16_f32 v75, v96, v97
	global_load_dwordx4 v[76:79], v[102:103], off
	v_mul_f32_e32 v69, v69, v104
	global_load_dwordx4 v[86:89], v[86:87], off
	v_mul_f32_e32 v70, v70, v104
	v_mul_f32_e32 v71, v71, v104
	v_mul_f32_e32 v64, v64, v104
	v_mul_f32_e32 v65, v65, v104
	v_mul_f32_e32 v66, v66, v104
	v_mul_f32_e32 v67, v67, v104
	v_mul_f32_e32 v68, 0xbfb8aa3b, v68
	v_mul_f32_e32 v69, 0xbfb8aa3b, v69
	v_mul_f32_e32 v70, 0xbfb8aa3b, v70
	v_mul_f32_e32 v71, 0xbfb8aa3b, v71
	v_mul_f32_e32 v64, 0xbfb8aa3b, v64
	v_mul_f32_e32 v65, 0xbfb8aa3b, v65
	v_mul_f32_e32 v66, 0xbfb8aa3b, v66
	v_mul_f32_e32 v67, 0xbfb8aa3b, v67
	v_exp_f32_e32 v68, v68
	v_exp_f32_e32 v69, v69
	v_exp_f32_e32 v70, v70
	v_exp_f32_e32 v71, v71
	v_exp_f32_e32 v64, v64
	v_exp_f32_e32 v65, v65
	v_exp_f32_e32 v66, v66
	v_exp_f32_e32 v67, v67
	v_add_f32_e32 v68, 1.0, v68
	v_add_f32_e32 v69, 1.0, v69
	v_add_f32_e32 v70, 1.0, v70
	v_add_f32_e32 v71, 1.0, v71
	v_add_f32_e32 v98, 1.0, v64
	v_add_f32_e32 v99, 1.0, v65
	v_add_f32_e32 v100, 1.0, v66
	v_add_f32_e32 v101, 1.0, v67
	v_rcp_f32_e32 v64, v68
	v_rcp_f32_e32 v65, v69
	v_rcp_f32_e32 v66, v70
	v_rcp_f32_e32 v67, v71
	v_rcp_f32_e32 v68, v98
	v_rcp_f32_e32 v69, v99
	v_rcp_f32_e32 v70, v100
	v_rcp_f32_e32 v71, v101
	v_mul_f32_e32 v95, v95, v95
	v_mul_f32_e32 v91, v91, v91
	v_mul_f32_e32 v93, v93, v93
	v_mul_f32_e32 v97, v97, v97
	v_fmac_f32_e32 v95, v94, v94
	v_fmac_f32_e32 v91, v90, v90
	v_fmac_f32_e32 v93, v92, v92
	v_fmac_f32_e32 v97, v96, v96
	v_add_f32_e32 v90, v95, v91
	v_add_f32_e32 v91, v93, v97
	v_add_f32_e32 v98, v90, v91
	global_store_dwordx4 v[84:85], v[72:75], off
	s_waitcnt vmcnt(2)
	v_lshlrev_b32_e32 v90, 16, v76
	v_and_b32_e32 v91, 0xffff0000, v76
	v_lshlrev_b32_e32 v76, 16, v77
	v_and_b32_e32 v77, 0xffff0000, v77
	v_lshlrev_b32_e32 v92, 16, v78
	v_and_b32_e32 v93, 0xffff0000, v78
	v_lshlrev_b32_e32 v78, 16, v79
	v_and_b32_e32 v79, 0xffff0000, v79
	s_waitcnt vmcnt(1)
	v_lshlrev_b32_e32 v94, 16, v86
	v_and_b32_e32 v95, 0xffff0000, v86
	v_lshlrev_b32_e32 v86, 16, v87
	v_and_b32_e32 v87, 0xffff0000, v87
	v_lshlrev_b32_e32 v96, 16, v88
	v_and_b32_e32 v97, 0xffff0000, v88
	v_lshlrev_b32_e32 v88, 16, v89
	v_and_b32_e32 v89, 0xffff0000, v89
	v_pk_fma_f32 v[76:77], v[66:67], v[86:87], v[76:77]
	v_pk_fma_f32 v[64:65], v[64:65], v[94:95], v[90:91]
	v_pk_fma_f32 v[70:71], v[70:71], v[88:89], v[78:79]
	v_pk_fma_f32 v[68:69], v[68:69], v[96:97], v[92:93]
	v_mul_f32_e32 v66, v65, v65
	v_mul_f32_e32 v67, v77, v77
	v_mul_f32_e32 v78, v69, v69
	v_mul_f32_e32 v79, v71, v71
	v_fmac_f32_e32 v66, v64, v64
	v_fmac_f32_e32 v67, v76, v76
	v_fmac_f32_e32 v78, v68, v68
	v_fmac_f32_e32 v79, v70, v70
	v_add_f32_e32 v66, v66, v67
	v_add_f32_e32 v67, v78, v79
	v_add_f32_e32 v66, v66, v67
	v_add_f32_e32 v78, v98, v66
	ds_bpermute_b32 v79, v164, v78
	v_cvt_pk_bf16_f32 v66, v64, v65
	v_cvt_pk_bf16_f32 v67, v76, v77
	v_cvt_pk_bf16_f32 v68, v68, v69
	v_cvt_pk_bf16_f32 v69, v70, v71
	s_waitcnt lgkmcnt(0)
	v_add_f32_e32 v64, v78, v79
	ds_bpermute_b32 v65, v149, v64
	v_lshl_add_u64 v[70:71], s[18:19], 0, v[82:83]
	global_store_dwordx4 v[70:71], v[66:69], off
	s_and_saveexec_b64 s[56:57], s[8:9]
	s_cbranch_execz .LBB0_628
	s_waitcnt lgkmcnt(0)
	v_add_f32_e32 v66, v64, v65
	v_lshl_add_u64 v[64:65], s[20:21], 0, v[80:81]
	v_lshl_add_u64 v[64:65], s[54:55], 2, v[64:65]
	s_lshl_b32 s14, s63, 2
	v_lshl_add_u64 v[64:65], v[64:65], 0, s[14:15]
	global_store_dword v[64:65], v66, off
.LBB0_628:
	s_or_b64 exec, exec, s[56:57]
	v_add_u32_e32 v66, 0x80, v148
	v_ashrrev_i32_e32 v67, 31, v66
	s_waitcnt lgkmcnt(0)
	v_lshlrev_b64 v[64:65], 7, v[66:67]
	v_lshl_add_u64 v[68:69], v[136:137], 0, v[64:65]
	global_load_dwordx4 v[70:73], v[68:69], off
	global_load_dwordx4 v[74:77], v[68:69], off offset:16
	v_lshlrev_b64 v[66:67], 11, v[66:67]
	v_lshl_add_u64 v[66:67], v[66:67], 0, v[146:147]
	v_lshlrev_b64 v[66:67], 1, v[66:67]
	v_lshl_add_u64 v[68:69], s[12:13], 0, v[66:67]
	global_load_dwordx4 v[78:81], v[68:69], off
	v_lshl_add_u64 v[68:69], s[22:23], 0, v[66:67]
	global_load_dwordx4 v[82:85], v[68:69], off
	v_lshl_add_u64 v[68:69], s[18:19], 0, v[66:67]
	v_or_b32_e32 v66, 0x100, v66
	v_lshl_add_u64 v[86:87], s[12:13], 0, v[66:67]
	s_waitcnt vmcnt(3)
	v_mov_b32_e32 v88, v70
	s_waitcnt vmcnt(2)
	v_mov_b32_e32 v89, v74
	v_mov_b32_e32 v74, v71
	v_mov_b32_e32 v70, v72
	v_mov_b32_e32 v71, v76
	v_mov_b32_e32 v76, v73
	v_pk_add_f32 v[72:73], v[88:89], v[74:75]
	v_pk_add_f32 v[70:71], v[70:71], v[76:77]
	s_waitcnt vmcnt(1)
	v_lshlrev_b32_e32 v74, 16, v79
	v_pk_add_f32 v[70:71], v[72:73], v[70:71]
	v_and_b32_e32 v75, 0xffff0000, v79
	v_add_f32_e32 v70, 0, v70
	v_add_f32_e32 v79, v70, v71
	ds_bpermute_b32 v88, v164, v79
	v_lshlrev_b32_e32 v76, 16, v80
	v_and_b32_e32 v77, 0xffff0000, v80
	v_lshlrev_b32_e32 v70, 16, v81
	v_and_b32_e32 v71, 0xffff0000, v81
	s_waitcnt lgkmcnt(0)
	v_add_f32_e32 v88, v79, v88
	ds_bpermute_b32 v89, v149, v88
	s_waitcnt vmcnt(0)
	v_lshlrev_b32_e32 v80, 16, v83
	v_and_b32_e32 v81, 0xffff0000, v83
	v_lshlrev_b32_e32 v72, 16, v78
	v_and_b32_e32 v73, 0xffff0000, v78
	s_waitcnt lgkmcnt(0)
	v_add_f32_e32 v83, v88, v89
	v_fmamk_f32 v83, v83, 0x3a000000, v163
	v_lshlrev_b32_e32 v78, 16, v82
	v_and_b32_e32 v79, 0xffff0000, v82
	v_rsq_f32_e32 v88, v83
	v_lshlrev_b32_e32 v82, 16, v84
	v_and_b32_e32 v83, 0xffff0000, v84
	v_lshlrev_b32_e32 v84, 16, v85
	v_mul_f32_e32 v62, v62, v88
	v_mul_f32_e32 v63, v63, v88
	v_mul_f32_e32 v58, v58, v88
	v_mul_f32_e32 v59, v59, v88
	v_mul_f32_e32 v60, v60, v88
	v_mul_f32_e32 v61, v61, v88
	v_mul_f32_e32 v56, v56, v88
	v_mul_f32_e32 v57, v57, v88
	v_mul_f32_e32 v62, 0xbfb8aa3b, v62
	v_mul_f32_e32 v63, 0xbfb8aa3b, v63
	v_mul_f32_e32 v58, 0xbfb8aa3b, v58
	v_mul_f32_e32 v59, 0xbfb8aa3b, v59
	v_mul_f32_e32 v60, 0xbfb8aa3b, v60
	v_mul_f32_e32 v61, 0xbfb8aa3b, v61
	v_mul_f32_e32 v56, 0xbfb8aa3b, v56
	v_mul_f32_e32 v57, 0xbfb8aa3b, v57
	v_exp_f32_e32 v62, v62
	v_exp_f32_e32 v63, v63
	v_exp_f32_e32 v58, v58
	v_exp_f32_e32 v59, v59
	v_exp_f32_e32 v60, v60
	v_exp_f32_e32 v61, v61
	v_exp_f32_e32 v56, v56
	v_exp_f32_e32 v57, v57
	v_add_f32_e32 v62, 1.0, v62
	v_add_f32_e32 v63, 1.0, v63
	v_add_f32_e32 v91, 1.0, v58
	v_add_f32_e32 v92, 1.0, v59
	v_add_f32_e32 v60, 1.0, v60
	v_add_f32_e32 v61, 1.0, v61
	v_add_f32_e32 v89, 1.0, v56
	v_add_f32_e32 v90, 1.0, v57
	v_rcp_f32_e32 v58, v62
	v_rcp_f32_e32 v59, v63
	v_rcp_f32_e32 v62, v91
	v_rcp_f32_e32 v63, v92
	v_rcp_f32_e32 v56, v60
	v_rcp_f32_e32 v57, v61
	v_rcp_f32_e32 v60, v89
	v_rcp_f32_e32 v61, v90
	v_and_b32_e32 v85, 0xffff0000, v85
	v_pk_fma_f32 v[74:75], v[58:59], v[80:81], v[74:75]
	v_pk_fma_f32 v[80:81], v[62:63], v[84:85], v[70:71]
	v_lshl_add_u64 v[70:71], s[22:23], 0, v[66:67]
	v_pk_fma_f32 v[78:79], v[56:57], v[78:79], v[72:73]
	v_pk_fma_f32 v[76:77], v[60:61], v[82:83], v[76:77]
	v_cvt_pk_bf16_f32 v56, v78, v79
	v_cvt_pk_bf16_f32 v57, v74, v75
	v_mul_f32_e32 v52, v52, v88
	v_cvt_pk_bf16_f32 v58, v76, v77
	v_cvt_pk_bf16_f32 v59, v80, v81
	global_load_dwordx4 v[60:63], v[86:87], off
	v_mul_f32_e32 v53, v53, v88
	global_load_dwordx4 v[70:73], v[70:71], off
	v_mul_f32_e32 v54, v54, v88
	v_mul_f32_e32 v55, v55, v88
	v_mul_f32_e32 v48, v48, v88
	v_mul_f32_e32 v49, v49, v88
	v_mul_f32_e32 v50, v50, v88
	v_mul_f32_e32 v51, v51, v88
	v_mul_f32_e32 v52, 0xbfb8aa3b, v52
	v_mul_f32_e32 v53, 0xbfb8aa3b, v53
	v_mul_f32_e32 v54, 0xbfb8aa3b, v54
	v_mul_f32_e32 v55, 0xbfb8aa3b, v55
	v_mul_f32_e32 v48, 0xbfb8aa3b, v48
	v_mul_f32_e32 v49, 0xbfb8aa3b, v49
	v_mul_f32_e32 v50, 0xbfb8aa3b, v50
	v_mul_f32_e32 v51, 0xbfb8aa3b, v51
	v_exp_f32_e32 v52, v52
	v_exp_f32_e32 v53, v53
	v_exp_f32_e32 v54, v54
	v_exp_f32_e32 v55, v55
	v_exp_f32_e32 v48, v48
	v_exp_f32_e32 v49, v49
	v_exp_f32_e32 v50, v50
	v_exp_f32_e32 v51, v51
	v_add_f32_e32 v52, 1.0, v52
	v_add_f32_e32 v53, 1.0, v53
	v_add_f32_e32 v54, 1.0, v54
	v_add_f32_e32 v55, 1.0, v55
	v_add_f32_e32 v82, 1.0, v48
	v_add_f32_e32 v83, 1.0, v49
	v_add_f32_e32 v84, 1.0, v50
	v_add_f32_e32 v85, 1.0, v51
	v_rcp_f32_e32 v48, v52
	v_rcp_f32_e32 v49, v53
	v_rcp_f32_e32 v50, v54
	v_rcp_f32_e32 v51, v55
	v_rcp_f32_e32 v52, v82
	v_rcp_f32_e32 v53, v83
	v_rcp_f32_e32 v54, v84
	v_rcp_f32_e32 v55, v85
	v_mul_f32_e32 v79, v79, v79
	v_mul_f32_e32 v75, v75, v75
	v_mul_f32_e32 v77, v77, v77
	v_mul_f32_e32 v81, v81, v81
	v_fmac_f32_e32 v79, v78, v78
	v_fmac_f32_e32 v75, v74, v74
	v_fmac_f32_e32 v77, v76, v76
	v_fmac_f32_e32 v81, v80, v80
	v_add_f32_e32 v74, v79, v75
	v_add_f32_e32 v75, v77, v81
	v_add_f32_e32 v82, v74, v75
	global_store_dwordx4 v[68:69], v[56:59], off
	s_waitcnt vmcnt(2)
	v_lshlrev_b32_e32 v74, 16, v60
	v_and_b32_e32 v75, 0xffff0000, v60
	v_lshlrev_b32_e32 v60, 16, v61
	v_and_b32_e32 v61, 0xffff0000, v61
	v_lshlrev_b32_e32 v76, 16, v62
	v_and_b32_e32 v77, 0xffff0000, v62
	v_lshlrev_b32_e32 v62, 16, v63
	v_and_b32_e32 v63, 0xffff0000, v63
	s_waitcnt vmcnt(1)
	v_lshlrev_b32_e32 v78, 16, v70
	v_and_b32_e32 v79, 0xffff0000, v70
	v_lshlrev_b32_e32 v70, 16, v71
	v_and_b32_e32 v71, 0xffff0000, v71
	v_lshlrev_b32_e32 v80, 16, v72
	v_and_b32_e32 v81, 0xffff0000, v72
	v_lshlrev_b32_e32 v72, 16, v73
	v_and_b32_e32 v73, 0xffff0000, v73
	v_pk_fma_f32 v[60:61], v[50:51], v[70:71], v[60:61]
	v_pk_fma_f32 v[48:49], v[48:49], v[78:79], v[74:75]
	v_pk_fma_f32 v[54:55], v[54:55], v[72:73], v[62:63]
	v_pk_fma_f32 v[52:53], v[52:53], v[80:81], v[76:77]
	v_mul_f32_e32 v50, v49, v49
	v_mul_f32_e32 v51, v61, v61
	v_mul_f32_e32 v62, v53, v53
	v_mul_f32_e32 v63, v55, v55
	v_fmac_f32_e32 v50, v48, v48
	v_fmac_f32_e32 v51, v60, v60
	v_fmac_f32_e32 v62, v52, v52
	v_fmac_f32_e32 v63, v54, v54
	v_add_f32_e32 v50, v50, v51
	v_add_f32_e32 v51, v62, v63
	v_add_f32_e32 v50, v50, v51
	v_add_f32_e32 v62, v82, v50
	ds_bpermute_b32 v63, v164, v62
	v_cvt_pk_bf16_f32 v50, v48, v49
	v_cvt_pk_bf16_f32 v51, v60, v61
	v_cvt_pk_bf16_f32 v52, v52, v53
	v_cvt_pk_bf16_f32 v53, v54, v55
	s_waitcnt lgkmcnt(0)
	v_add_f32_e32 v48, v62, v63
	ds_bpermute_b32 v49, v149, v48
	v_lshl_add_u64 v[54:55], s[18:19], 0, v[66:67]
	global_store_dwordx4 v[54:55], v[50:53], off
	s_and_saveexec_b64 s[56:57], s[8:9]
	s_cbranch_execz .LBB0_630
	s_waitcnt lgkmcnt(0)
	v_add_f32_e32 v50, v48, v49
	v_lshl_add_u64 v[48:49], s[20:21], 0, v[64:65]
	v_lshl_add_u64 v[48:49], s[54:55], 2, v[48:49]
	s_lshl_b32 s14, s63, 2
	v_lshl_add_u64 v[48:49], v[48:49], 0, s[14:15]
	global_store_dword v[48:49], v50, off
.LBB0_630:
	s_or_b64 exec, exec, s[56:57]
	v_add_u32_e32 v50, 0x90, v148
	v_ashrrev_i32_e32 v51, 31, v50
	s_waitcnt lgkmcnt(0)
	v_lshlrev_b64 v[48:49], 7, v[50:51]
	v_lshl_add_u64 v[52:53], v[136:137], 0, v[48:49]
	global_load_dwordx4 v[54:57], v[52:53], off
	global_load_dwordx4 v[58:61], v[52:53], off offset:16
	v_lshlrev_b64 v[50:51], 11, v[50:51]
	v_lshl_add_u64 v[50:51], v[50:51], 0, v[146:147]
	v_lshlrev_b64 v[50:51], 1, v[50:51]
	v_lshl_add_u64 v[52:53], s[12:13], 0, v[50:51]
	global_load_dwordx4 v[62:65], v[52:53], off
	v_lshl_add_u64 v[52:53], s[22:23], 0, v[50:51]
	global_load_dwordx4 v[66:69], v[52:53], off
	v_lshl_add_u64 v[52:53], s[18:19], 0, v[50:51]
	v_or_b32_e32 v50, 0x100, v50
	v_lshl_add_u64 v[70:71], s[12:13], 0, v[50:51]
	s_waitcnt vmcnt(3)
	v_mov_b32_e32 v72, v54
	s_waitcnt vmcnt(2)
	v_mov_b32_e32 v73, v58
	v_mov_b32_e32 v58, v55
	v_mov_b32_e32 v54, v56
	v_mov_b32_e32 v55, v60
	v_mov_b32_e32 v60, v57
	v_pk_add_f32 v[56:57], v[72:73], v[58:59]
	v_pk_add_f32 v[54:55], v[54:55], v[60:61]
	s_waitcnt vmcnt(1)
	v_lshlrev_b32_e32 v58, 16, v63
	v_pk_add_f32 v[54:55], v[56:57], v[54:55]
	v_and_b32_e32 v59, 0xffff0000, v63
	v_add_f32_e32 v54, 0, v54
	v_add_f32_e32 v63, v54, v55
	ds_bpermute_b32 v72, v164, v63
	v_lshlrev_b32_e32 v60, 16, v64
	v_and_b32_e32 v61, 0xffff0000, v64
	v_lshlrev_b32_e32 v54, 16, v65
	v_and_b32_e32 v55, 0xffff0000, v65
	s_waitcnt lgkmcnt(0)
	v_add_f32_e32 v72, v63, v72
	ds_bpermute_b32 v73, v149, v72
	s_waitcnt vmcnt(0)
	v_lshlrev_b32_e32 v64, 16, v67
	v_and_b32_e32 v65, 0xffff0000, v67
	v_lshlrev_b32_e32 v56, 16, v62
	v_and_b32_e32 v57, 0xffff0000, v62
	s_waitcnt lgkmcnt(0)
	v_add_f32_e32 v67, v72, v73
	v_fmamk_f32 v67, v67, 0x3a000000, v163
	v_lshlrev_b32_e32 v62, 16, v66
	v_and_b32_e32 v63, 0xffff0000, v66
	v_rsq_f32_e32 v72, v67
	v_lshlrev_b32_e32 v66, 16, v68
	v_and_b32_e32 v67, 0xffff0000, v68
	v_lshlrev_b32_e32 v68, 16, v69
	v_mul_f32_e32 v46, v46, v72
	v_mul_f32_e32 v47, v47, v72
	v_mul_f32_e32 v42, v42, v72
	v_mul_f32_e32 v43, v43, v72
	v_mul_f32_e32 v44, v44, v72
	v_mul_f32_e32 v45, v45, v72
	v_mul_f32_e32 v40, v40, v72
	v_mul_f32_e32 v41, v41, v72
	v_mul_f32_e32 v46, 0xbfb8aa3b, v46
	v_mul_f32_e32 v47, 0xbfb8aa3b, v47
	v_mul_f32_e32 v42, 0xbfb8aa3b, v42
	v_mul_f32_e32 v43, 0xbfb8aa3b, v43
	v_mul_f32_e32 v44, 0xbfb8aa3b, v44
	v_mul_f32_e32 v45, 0xbfb8aa3b, v45
	v_mul_f32_e32 v40, 0xbfb8aa3b, v40
	v_mul_f32_e32 v41, 0xbfb8aa3b, v41
	v_exp_f32_e32 v46, v46
	v_exp_f32_e32 v47, v47
	v_exp_f32_e32 v42, v42
	v_exp_f32_e32 v43, v43
	v_exp_f32_e32 v44, v44
	v_exp_f32_e32 v45, v45
	v_exp_f32_e32 v40, v40
	v_exp_f32_e32 v41, v41
	v_add_f32_e32 v46, 1.0, v46
	v_add_f32_e32 v47, 1.0, v47
	v_add_f32_e32 v75, 1.0, v42
	v_add_f32_e32 v76, 1.0, v43
	v_add_f32_e32 v44, 1.0, v44
	v_add_f32_e32 v45, 1.0, v45
	v_add_f32_e32 v73, 1.0, v40
	v_add_f32_e32 v74, 1.0, v41
	v_rcp_f32_e32 v42, v46
	v_rcp_f32_e32 v43, v47
	v_rcp_f32_e32 v46, v75
	v_rcp_f32_e32 v47, v76
	v_rcp_f32_e32 v40, v44
	v_rcp_f32_e32 v41, v45
	v_rcp_f32_e32 v44, v73
	v_rcp_f32_e32 v45, v74
	v_and_b32_e32 v69, 0xffff0000, v69
	v_pk_fma_f32 v[58:59], v[42:43], v[64:65], v[58:59]
	v_pk_fma_f32 v[64:65], v[46:47], v[68:69], v[54:55]
	v_lshl_add_u64 v[54:55], s[22:23], 0, v[50:51]
	v_pk_fma_f32 v[62:63], v[40:41], v[62:63], v[56:57]
	v_pk_fma_f32 v[60:61], v[44:45], v[66:67], v[60:61]
	v_cvt_pk_bf16_f32 v40, v62, v63
	v_cvt_pk_bf16_f32 v41, v58, v59
	v_mul_f32_e32 v36, v36, v72
	v_cvt_pk_bf16_f32 v42, v60, v61
	v_cvt_pk_bf16_f32 v43, v64, v65
	global_load_dwordx4 v[44:47], v[70:71], off
	v_mul_f32_e32 v37, v37, v72
	global_load_dwordx4 v[54:57], v[54:55], off
	v_mul_f32_e32 v38, v38, v72
	v_mul_f32_e32 v39, v39, v72
	v_mul_f32_e32 v32, v32, v72
	v_mul_f32_e32 v33, v33, v72
	v_mul_f32_e32 v34, v34, v72
	v_mul_f32_e32 v35, v35, v72
	v_mul_f32_e32 v36, 0xbfb8aa3b, v36
	v_mul_f32_e32 v37, 0xbfb8aa3b, v37
	v_mul_f32_e32 v38, 0xbfb8aa3b, v38
	v_mul_f32_e32 v39, 0xbfb8aa3b, v39
	v_mul_f32_e32 v32, 0xbfb8aa3b, v32
	v_mul_f32_e32 v33, 0xbfb8aa3b, v33
	v_mul_f32_e32 v34, 0xbfb8aa3b, v34
	v_mul_f32_e32 v35, 0xbfb8aa3b, v35
	v_exp_f32_e32 v36, v36
	v_exp_f32_e32 v37, v37
	v_exp_f32_e32 v38, v38
	v_exp_f32_e32 v39, v39
	v_exp_f32_e32 v32, v32
	v_exp_f32_e32 v33, v33
	v_exp_f32_e32 v34, v34
	v_exp_f32_e32 v35, v35
	v_add_f32_e32 v36, 1.0, v36
	v_add_f32_e32 v37, 1.0, v37
	v_add_f32_e32 v38, 1.0, v38
	v_add_f32_e32 v39, 1.0, v39
	v_add_f32_e32 v66, 1.0, v32
	v_add_f32_e32 v67, 1.0, v33
	v_add_f32_e32 v68, 1.0, v34
	v_add_f32_e32 v69, 1.0, v35
	v_rcp_f32_e32 v32, v36
	v_rcp_f32_e32 v33, v37
	v_rcp_f32_e32 v34, v38
	v_rcp_f32_e32 v35, v39
	v_rcp_f32_e32 v36, v66
	v_rcp_f32_e32 v37, v67
	v_rcp_f32_e32 v38, v68
	v_rcp_f32_e32 v39, v69
	v_mul_f32_e32 v63, v63, v63
	v_mul_f32_e32 v59, v59, v59
	v_mul_f32_e32 v61, v61, v61
	v_mul_f32_e32 v65, v65, v65
	v_fmac_f32_e32 v63, v62, v62
	v_fmac_f32_e32 v59, v58, v58
	v_fmac_f32_e32 v61, v60, v60
	v_fmac_f32_e32 v65, v64, v64
	v_add_f32_e32 v58, v63, v59
	v_add_f32_e32 v59, v61, v65
	v_add_f32_e32 v66, v58, v59
	global_store_dwordx4 v[52:53], v[40:43], off
	s_waitcnt vmcnt(2)
	v_lshlrev_b32_e32 v58, 16, v44
	v_and_b32_e32 v59, 0xffff0000, v44
	v_lshlrev_b32_e32 v44, 16, v45
	v_and_b32_e32 v45, 0xffff0000, v45
	v_lshlrev_b32_e32 v60, 16, v46
	v_and_b32_e32 v61, 0xffff0000, v46
	v_lshlrev_b32_e32 v46, 16, v47
	v_and_b32_e32 v47, 0xffff0000, v47
	s_waitcnt vmcnt(1)
	v_lshlrev_b32_e32 v62, 16, v54
	v_and_b32_e32 v63, 0xffff0000, v54
	v_lshlrev_b32_e32 v54, 16, v55
	v_and_b32_e32 v55, 0xffff0000, v55
	v_lshlrev_b32_e32 v64, 16, v56
	v_and_b32_e32 v65, 0xffff0000, v56
	v_lshlrev_b32_e32 v56, 16, v57
	v_and_b32_e32 v57, 0xffff0000, v57
	v_pk_fma_f32 v[44:45], v[34:35], v[54:55], v[44:45]
	v_pk_fma_f32 v[32:33], v[32:33], v[62:63], v[58:59]
	v_pk_fma_f32 v[38:39], v[38:39], v[56:57], v[46:47]
	v_pk_fma_f32 v[36:37], v[36:37], v[64:65], v[60:61]
	v_mul_f32_e32 v34, v33, v33
	v_mul_f32_e32 v35, v45, v45
	v_mul_f32_e32 v46, v37, v37
	v_mul_f32_e32 v47, v39, v39
	v_fmac_f32_e32 v34, v32, v32
	v_fmac_f32_e32 v35, v44, v44
	v_fmac_f32_e32 v46, v36, v36
	v_fmac_f32_e32 v47, v38, v38
	v_add_f32_e32 v34, v34, v35
	v_add_f32_e32 v35, v46, v47
	v_add_f32_e32 v34, v34, v35
	v_add_f32_e32 v46, v66, v34
	ds_bpermute_b32 v47, v164, v46
	v_cvt_pk_bf16_f32 v34, v32, v33
	v_cvt_pk_bf16_f32 v35, v44, v45
	v_cvt_pk_bf16_f32 v36, v36, v37
	v_cvt_pk_bf16_f32 v37, v38, v39
	s_waitcnt lgkmcnt(0)
	v_add_f32_e32 v32, v46, v47
	ds_bpermute_b32 v33, v149, v32
	v_lshl_add_u64 v[38:39], s[18:19], 0, v[50:51]
	global_store_dwordx4 v[38:39], v[34:37], off
	s_and_saveexec_b64 s[56:57], s[8:9]
	s_cbranch_execz .LBB0_632
	s_waitcnt lgkmcnt(0)
	v_add_f32_e32 v34, v32, v33
	v_lshl_add_u64 v[32:33], s[20:21], 0, v[48:49]
	v_lshl_add_u64 v[32:33], s[54:55], 2, v[32:33]
	s_lshl_b32 s14, s63, 2
	v_lshl_add_u64 v[32:33], v[32:33], 0, s[14:15]
	global_store_dword v[32:33], v34, off
.LBB0_632:
	s_or_b64 exec, exec, s[56:57]
	v_add_u32_e32 v34, 0xa0, v148
	v_ashrrev_i32_e32 v35, 31, v34
	s_waitcnt lgkmcnt(0)
	v_lshlrev_b64 v[32:33], 7, v[34:35]
	v_lshl_add_u64 v[36:37], v[136:137], 0, v[32:33]
	global_load_dwordx4 v[38:41], v[36:37], off
	global_load_dwordx4 v[42:45], v[36:37], off offset:16
	v_lshlrev_b64 v[34:35], 11, v[34:35]
	v_lshl_add_u64 v[34:35], v[34:35], 0, v[146:147]
	v_lshlrev_b64 v[34:35], 1, v[34:35]
	v_lshl_add_u64 v[36:37], s[12:13], 0, v[34:35]
	global_load_dwordx4 v[46:49], v[36:37], off
	v_lshl_add_u64 v[36:37], s[22:23], 0, v[34:35]
	global_load_dwordx4 v[50:53], v[36:37], off
	v_lshl_add_u64 v[36:37], s[18:19], 0, v[34:35]
	v_or_b32_e32 v34, 0x100, v34
	v_lshl_add_u64 v[54:55], s[12:13], 0, v[34:35]
	s_waitcnt vmcnt(3)
	v_mov_b32_e32 v56, v38
	s_waitcnt vmcnt(2)
	v_mov_b32_e32 v57, v42
	v_mov_b32_e32 v42, v39
	v_mov_b32_e32 v38, v40
	v_mov_b32_e32 v39, v44
	v_mov_b32_e32 v44, v41
	v_pk_add_f32 v[40:41], v[56:57], v[42:43]
	v_pk_add_f32 v[38:39], v[38:39], v[44:45]
	s_waitcnt vmcnt(1)
	v_lshlrev_b32_e32 v42, 16, v47
	v_pk_add_f32 v[38:39], v[40:41], v[38:39]
	v_and_b32_e32 v43, 0xffff0000, v47
	v_add_f32_e32 v38, 0, v38
	v_add_f32_e32 v47, v38, v39
	ds_bpermute_b32 v56, v164, v47
	v_lshlrev_b32_e32 v44, 16, v48
	v_and_b32_e32 v45, 0xffff0000, v48
	v_lshlrev_b32_e32 v38, 16, v49
	v_and_b32_e32 v39, 0xffff0000, v49
	s_waitcnt lgkmcnt(0)
	v_add_f32_e32 v56, v47, v56
	ds_bpermute_b32 v57, v149, v56
	s_waitcnt vmcnt(0)
	v_lshlrev_b32_e32 v48, 16, v51
	v_and_b32_e32 v49, 0xffff0000, v51
	v_lshlrev_b32_e32 v40, 16, v46
	v_and_b32_e32 v41, 0xffff0000, v46
	s_waitcnt lgkmcnt(0)
	v_add_f32_e32 v51, v56, v57
	v_fmamk_f32 v51, v51, 0x3a000000, v163
	v_lshlrev_b32_e32 v46, 16, v50
	v_and_b32_e32 v47, 0xffff0000, v50
	v_rsq_f32_e32 v56, v51
	v_lshlrev_b32_e32 v50, 16, v52
	v_and_b32_e32 v51, 0xffff0000, v52
	v_lshlrev_b32_e32 v52, 16, v53
	v_mul_f32_e32 v30, v30, v56
	v_mul_f32_e32 v31, v31, v56
	v_mul_f32_e32 v26, v26, v56
	v_mul_f32_e32 v27, v27, v56
	v_mul_f32_e32 v28, v28, v56
	v_mul_f32_e32 v29, v29, v56
	v_mul_f32_e32 v24, v24, v56
	v_mul_f32_e32 v25, v25, v56
	v_mul_f32_e32 v30, 0xbfb8aa3b, v30
	v_mul_f32_e32 v31, 0xbfb8aa3b, v31
	v_mul_f32_e32 v26, 0xbfb8aa3b, v26
	v_mul_f32_e32 v27, 0xbfb8aa3b, v27
	v_mul_f32_e32 v28, 0xbfb8aa3b, v28
	v_mul_f32_e32 v29, 0xbfb8aa3b, v29
	v_mul_f32_e32 v24, 0xbfb8aa3b, v24
	v_mul_f32_e32 v25, 0xbfb8aa3b, v25
	v_exp_f32_e32 v30, v30
	v_exp_f32_e32 v31, v31
	v_exp_f32_e32 v26, v26
	v_exp_f32_e32 v27, v27
	v_exp_f32_e32 v28, v28
	v_exp_f32_e32 v29, v29
	v_exp_f32_e32 v24, v24
	v_exp_f32_e32 v25, v25
	v_add_f32_e32 v30, 1.0, v30
	v_add_f32_e32 v31, 1.0, v31
	v_add_f32_e32 v59, 1.0, v26
	v_add_f32_e32 v60, 1.0, v27
	v_add_f32_e32 v28, 1.0, v28
	v_add_f32_e32 v29, 1.0, v29
	v_add_f32_e32 v57, 1.0, v24
	v_add_f32_e32 v58, 1.0, v25
	v_rcp_f32_e32 v26, v30
	v_rcp_f32_e32 v27, v31
	v_rcp_f32_e32 v30, v59
	v_rcp_f32_e32 v31, v60
	v_rcp_f32_e32 v24, v28
	v_rcp_f32_e32 v25, v29
	v_rcp_f32_e32 v28, v57
	v_rcp_f32_e32 v29, v58
	v_and_b32_e32 v53, 0xffff0000, v53
	v_pk_fma_f32 v[42:43], v[26:27], v[48:49], v[42:43]
	v_pk_fma_f32 v[48:49], v[30:31], v[52:53], v[38:39]
	v_lshl_add_u64 v[38:39], s[22:23], 0, v[34:35]
	v_pk_fma_f32 v[46:47], v[24:25], v[46:47], v[40:41]
	v_pk_fma_f32 v[44:45], v[28:29], v[50:51], v[44:45]
	v_cvt_pk_bf16_f32 v24, v46, v47
	v_cvt_pk_bf16_f32 v25, v42, v43
	v_mul_f32_e32 v20, v20, v56
	v_cvt_pk_bf16_f32 v26, v44, v45
	v_cvt_pk_bf16_f32 v27, v48, v49
	global_load_dwordx4 v[28:31], v[54:55], off
	v_mul_f32_e32 v21, v21, v56
	global_load_dwordx4 v[38:41], v[38:39], off
	v_mul_f32_e32 v22, v22, v56
	v_mul_f32_e32 v23, v23, v56
	v_mul_f32_e32 v16, v16, v56
	v_mul_f32_e32 v17, v17, v56
	v_mul_f32_e32 v18, v18, v56
	v_mul_f32_e32 v19, v19, v56
	v_mul_f32_e32 v20, 0xbfb8aa3b, v20
	v_mul_f32_e32 v21, 0xbfb8aa3b, v21
	v_mul_f32_e32 v22, 0xbfb8aa3b, v22
	v_mul_f32_e32 v23, 0xbfb8aa3b, v23
	v_mul_f32_e32 v16, 0xbfb8aa3b, v16
	v_mul_f32_e32 v17, 0xbfb8aa3b, v17
	v_mul_f32_e32 v18, 0xbfb8aa3b, v18
	v_mul_f32_e32 v19, 0xbfb8aa3b, v19
	v_exp_f32_e32 v20, v20
	v_exp_f32_e32 v21, v21
	v_exp_f32_e32 v22, v22
	v_exp_f32_e32 v23, v23
	v_exp_f32_e32 v16, v16
	v_exp_f32_e32 v17, v17
	v_exp_f32_e32 v18, v18
	v_exp_f32_e32 v19, v19
	v_add_f32_e32 v20, 1.0, v20
	v_add_f32_e32 v21, 1.0, v21
	v_add_f32_e32 v22, 1.0, v22
	v_add_f32_e32 v23, 1.0, v23
	v_add_f32_e32 v50, 1.0, v16
	v_add_f32_e32 v51, 1.0, v17
	v_add_f32_e32 v52, 1.0, v18
	v_add_f32_e32 v53, 1.0, v19
	v_rcp_f32_e32 v16, v20
	v_rcp_f32_e32 v17, v21
	v_rcp_f32_e32 v18, v22
	v_rcp_f32_e32 v19, v23
	v_rcp_f32_e32 v20, v50
	v_rcp_f32_e32 v21, v51
	v_rcp_f32_e32 v22, v52
	v_rcp_f32_e32 v23, v53
	v_mul_f32_e32 v47, v47, v47
	v_mul_f32_e32 v43, v43, v43
	v_mul_f32_e32 v45, v45, v45
	v_mul_f32_e32 v49, v49, v49
	v_fmac_f32_e32 v47, v46, v46
	v_fmac_f32_e32 v43, v42, v42
	v_fmac_f32_e32 v45, v44, v44
	v_fmac_f32_e32 v49, v48, v48
	v_add_f32_e32 v42, v47, v43
	v_add_f32_e32 v43, v45, v49
	v_add_f32_e32 v50, v42, v43
	global_store_dwordx4 v[36:37], v[24:27], off
	s_waitcnt vmcnt(2)
	v_lshlrev_b32_e32 v42, 16, v28
	v_and_b32_e32 v43, 0xffff0000, v28
	v_lshlrev_b32_e32 v28, 16, v29
	v_and_b32_e32 v29, 0xffff0000, v29
	v_lshlrev_b32_e32 v44, 16, v30
	v_and_b32_e32 v45, 0xffff0000, v30
	v_lshlrev_b32_e32 v30, 16, v31
	v_and_b32_e32 v31, 0xffff0000, v31
	s_waitcnt vmcnt(1)
	v_lshlrev_b32_e32 v46, 16, v38
	v_and_b32_e32 v47, 0xffff0000, v38
	v_lshlrev_b32_e32 v38, 16, v39
	v_and_b32_e32 v39, 0xffff0000, v39
	v_lshlrev_b32_e32 v48, 16, v40
	v_and_b32_e32 v49, 0xffff0000, v40
	v_lshlrev_b32_e32 v40, 16, v41
	v_and_b32_e32 v41, 0xffff0000, v41
	v_pk_fma_f32 v[28:29], v[18:19], v[38:39], v[28:29]
	v_pk_fma_f32 v[16:17], v[16:17], v[46:47], v[42:43]
	v_pk_fma_f32 v[22:23], v[22:23], v[40:41], v[30:31]
	v_pk_fma_f32 v[20:21], v[20:21], v[48:49], v[44:45]
	v_mul_f32_e32 v18, v17, v17
	v_mul_f32_e32 v19, v29, v29
	v_mul_f32_e32 v30, v21, v21
	v_mul_f32_e32 v31, v23, v23
	v_fmac_f32_e32 v18, v16, v16
	v_fmac_f32_e32 v19, v28, v28
	v_fmac_f32_e32 v30, v20, v20
	v_fmac_f32_e32 v31, v22, v22
	v_add_f32_e32 v18, v18, v19
	v_add_f32_e32 v19, v30, v31
	v_add_f32_e32 v18, v18, v19
	v_add_f32_e32 v30, v50, v18
	ds_bpermute_b32 v31, v164, v30
	v_cvt_pk_bf16_f32 v18, v16, v17
	v_cvt_pk_bf16_f32 v19, v28, v29
	v_cvt_pk_bf16_f32 v20, v20, v21
	v_cvt_pk_bf16_f32 v21, v22, v23
	s_waitcnt lgkmcnt(0)
	v_add_f32_e32 v16, v30, v31
	ds_bpermute_b32 v17, v149, v16
	v_lshl_add_u64 v[22:23], s[18:19], 0, v[34:35]
	global_store_dwordx4 v[22:23], v[18:21], off
	s_and_saveexec_b64 s[56:57], s[8:9]
	s_cbranch_execz .LBB0_634
	s_waitcnt lgkmcnt(0)
	v_add_f32_e32 v18, v16, v17
	v_lshl_add_u64 v[16:17], s[20:21], 0, v[32:33]
	v_lshl_add_u64 v[16:17], s[54:55], 2, v[16:17]
	s_lshl_b32 s14, s63, 2
	v_lshl_add_u64 v[16:17], v[16:17], 0, s[14:15]
	global_store_dword v[16:17], v18, off
.LBB0_634:
	s_or_b64 exec, exec, s[56:57]
	v_add_u32_e32 v18, 0xb0, v148
	v_ashrrev_i32_e32 v19, 31, v18
	s_waitcnt lgkmcnt(0)
	v_lshlrev_b64 v[16:17], 7, v[18:19]
	v_lshl_add_u64 v[20:21], v[136:137], 0, v[16:17]
	global_load_dwordx4 v[22:25], v[20:21], off
	global_load_dwordx4 v[26:29], v[20:21], off offset:16
	v_lshlrev_b64 v[18:19], 11, v[18:19]
	v_lshl_add_u64 v[18:19], v[18:19], 0, v[146:147]
	v_lshlrev_b64 v[18:19], 1, v[18:19]
	v_lshl_add_u64 v[20:21], s[12:13], 0, v[18:19]
	global_load_dwordx4 v[30:33], v[20:21], off
	v_lshl_add_u64 v[20:21], s[22:23], 0, v[18:19]
	global_load_dwordx4 v[34:37], v[20:21], off
	v_lshl_add_u64 v[20:21], s[18:19], 0, v[18:19]
	v_or_b32_e32 v18, 0x100, v18
	v_lshl_add_u64 v[38:39], s[12:13], 0, v[18:19]
	s_waitcnt vmcnt(3)
	v_mov_b32_e32 v40, v22
	s_waitcnt vmcnt(2)
	v_mov_b32_e32 v41, v26
	v_mov_b32_e32 v26, v23
	v_mov_b32_e32 v22, v24
	v_mov_b32_e32 v23, v28
	v_mov_b32_e32 v28, v25
	v_pk_add_f32 v[24:25], v[40:41], v[26:27]
	v_pk_add_f32 v[22:23], v[22:23], v[28:29]
	s_waitcnt vmcnt(1)
	v_lshlrev_b32_e32 v26, 16, v31
	v_pk_add_f32 v[22:23], v[24:25], v[22:23]
	v_and_b32_e32 v27, 0xffff0000, v31
	v_add_f32_e32 v22, 0, v22
	v_add_f32_e32 v31, v22, v23
	ds_bpermute_b32 v40, v164, v31
	v_lshlrev_b32_e32 v28, 16, v32
	v_and_b32_e32 v29, 0xffff0000, v32
	v_lshlrev_b32_e32 v22, 16, v33
	v_and_b32_e32 v23, 0xffff0000, v33
	s_waitcnt lgkmcnt(0)
	v_add_f32_e32 v40, v31, v40
	ds_bpermute_b32 v41, v149, v40
	s_waitcnt vmcnt(0)
	v_lshlrev_b32_e32 v32, 16, v35
	v_and_b32_e32 v33, 0xffff0000, v35
	v_lshlrev_b32_e32 v24, 16, v30
	v_and_b32_e32 v25, 0xffff0000, v30
	s_waitcnt lgkmcnt(0)
	v_add_f32_e32 v35, v40, v41
	v_fmamk_f32 v35, v35, 0x3a000000, v163
	v_lshlrev_b32_e32 v30, 16, v34
	v_and_b32_e32 v31, 0xffff0000, v34
	v_rsq_f32_e32 v40, v35
	v_lshlrev_b32_e32 v34, 16, v36
	v_and_b32_e32 v35, 0xffff0000, v36
	v_lshlrev_b32_e32 v36, 16, v37
	v_mul_f32_e32 v14, v14, v40
	v_mul_f32_e32 v15, v15, v40
	v_mul_f32_e32 v10, v10, v40
	v_mul_f32_e32 v11, v11, v40
	v_mul_f32_e32 v12, v12, v40
	v_mul_f32_e32 v13, v13, v40
	v_mul_f32_e32 v8, v8, v40
	v_mul_f32_e32 v9, v9, v40
	v_mul_f32_e32 v14, 0xbfb8aa3b, v14
	v_mul_f32_e32 v15, 0xbfb8aa3b, v15
	v_mul_f32_e32 v10, 0xbfb8aa3b, v10
	v_mul_f32_e32 v11, 0xbfb8aa3b, v11
	v_mul_f32_e32 v12, 0xbfb8aa3b, v12
	v_mul_f32_e32 v13, 0xbfb8aa3b, v13
	v_mul_f32_e32 v8, 0xbfb8aa3b, v8
	v_mul_f32_e32 v9, 0xbfb8aa3b, v9
	v_exp_f32_e32 v14, v14
	v_exp_f32_e32 v15, v15
	v_exp_f32_e32 v10, v10
	v_exp_f32_e32 v11, v11
	v_exp_f32_e32 v12, v12
	v_exp_f32_e32 v13, v13
	v_exp_f32_e32 v8, v8
	v_exp_f32_e32 v9, v9
	v_add_f32_e32 v14, 1.0, v14
	v_add_f32_e32 v15, 1.0, v15
	v_add_f32_e32 v43, 1.0, v10
	v_add_f32_e32 v44, 1.0, v11
	v_add_f32_e32 v12, 1.0, v12
	v_add_f32_e32 v13, 1.0, v13
	v_add_f32_e32 v41, 1.0, v8
	v_add_f32_e32 v42, 1.0, v9
	v_rcp_f32_e32 v10, v14
	v_rcp_f32_e32 v11, v15
	v_rcp_f32_e32 v14, v43
	v_rcp_f32_e32 v15, v44
	v_rcp_f32_e32 v8, v12
	v_rcp_f32_e32 v9, v13
	v_rcp_f32_e32 v12, v41
	v_rcp_f32_e32 v13, v42
	v_and_b32_e32 v37, 0xffff0000, v37
	v_pk_fma_f32 v[26:27], v[10:11], v[32:33], v[26:27]
	v_pk_fma_f32 v[32:33], v[14:15], v[36:37], v[22:23]
	v_lshl_add_u64 v[22:23], s[22:23], 0, v[18:19]
	v_pk_fma_f32 v[30:31], v[8:9], v[30:31], v[24:25]
	v_pk_fma_f32 v[28:29], v[12:13], v[34:35], v[28:29]
	v_cvt_pk_bf16_f32 v8, v30, v31
	v_cvt_pk_bf16_f32 v9, v26, v27
	v_mul_f32_e32 v4, v4, v40
	v_cvt_pk_bf16_f32 v10, v28, v29
	v_cvt_pk_bf16_f32 v11, v32, v33
	global_load_dwordx4 v[12:15], v[38:39], off
	v_mul_f32_e32 v5, v5, v40
	global_load_dwordx4 v[22:25], v[22:23], off
	v_mul_f32_e32 v6, v6, v40
	v_mul_f32_e32 v7, v7, v40
	v_mul_f32_e32 v0, v0, v40
	v_mul_f32_e32 v1, v1, v40
	v_mul_f32_e32 v2, v2, v40
	v_mul_f32_e32 v3, v3, v40
	v_mul_f32_e32 v4, 0xbfb8aa3b, v4
	v_mul_f32_e32 v5, 0xbfb8aa3b, v5
	v_mul_f32_e32 v6, 0xbfb8aa3b, v6
	v_mul_f32_e32 v7, 0xbfb8aa3b, v7
	v_mul_f32_e32 v0, 0xbfb8aa3b, v0
	v_mul_f32_e32 v1, 0xbfb8aa3b, v1
	v_mul_f32_e32 v2, 0xbfb8aa3b, v2
	v_mul_f32_e32 v3, 0xbfb8aa3b, v3
	v_exp_f32_e32 v4, v4
	v_exp_f32_e32 v5, v5
	v_exp_f32_e32 v6, v6
	v_exp_f32_e32 v7, v7
	v_exp_f32_e32 v0, v0
	v_exp_f32_e32 v1, v1
	v_exp_f32_e32 v2, v2
	v_exp_f32_e32 v3, v3
	v_add_f32_e32 v4, 1.0, v4
	v_add_f32_e32 v5, 1.0, v5
	v_add_f32_e32 v6, 1.0, v6
	v_add_f32_e32 v7, 1.0, v7
	v_add_f32_e32 v34, 1.0, v0
	v_add_f32_e32 v35, 1.0, v1
	v_add_f32_e32 v36, 1.0, v2
	v_add_f32_e32 v37, 1.0, v3
	v_rcp_f32_e32 v0, v4
	v_rcp_f32_e32 v1, v5
	v_rcp_f32_e32 v2, v6
	v_rcp_f32_e32 v3, v7
	v_rcp_f32_e32 v4, v34
	v_rcp_f32_e32 v5, v35
	v_rcp_f32_e32 v6, v36
	v_rcp_f32_e32 v7, v37
	v_mul_f32_e32 v31, v31, v31
	v_mul_f32_e32 v27, v27, v27
	v_mul_f32_e32 v29, v29, v29
	v_mul_f32_e32 v33, v33, v33
	v_fmac_f32_e32 v31, v30, v30
	v_fmac_f32_e32 v27, v26, v26
	v_fmac_f32_e32 v29, v28, v28
	v_fmac_f32_e32 v33, v32, v32
	v_add_f32_e32 v26, v31, v27
	v_add_f32_e32 v27, v29, v33
	v_add_f32_e32 v34, v26, v27
	global_store_dwordx4 v[20:21], v[8:11], off
	s_waitcnt vmcnt(2)
	v_lshlrev_b32_e32 v26, 16, v12
	v_and_b32_e32 v27, 0xffff0000, v12
	v_lshlrev_b32_e32 v12, 16, v13
	v_and_b32_e32 v13, 0xffff0000, v13
	v_lshlrev_b32_e32 v28, 16, v14
	v_and_b32_e32 v29, 0xffff0000, v14
	v_lshlrev_b32_e32 v14, 16, v15
	v_and_b32_e32 v15, 0xffff0000, v15
	s_waitcnt vmcnt(1)
	v_lshlrev_b32_e32 v30, 16, v22
	v_and_b32_e32 v31, 0xffff0000, v22
	v_lshlrev_b32_e32 v22, 16, v23
	v_and_b32_e32 v23, 0xffff0000, v23
	v_lshlrev_b32_e32 v32, 16, v24
	v_and_b32_e32 v33, 0xffff0000, v24
	v_lshlrev_b32_e32 v24, 16, v25
	v_and_b32_e32 v25, 0xffff0000, v25
	v_pk_fma_f32 v[12:13], v[2:3], v[22:23], v[12:13]
	v_pk_fma_f32 v[0:1], v[0:1], v[30:31], v[26:27]
	v_pk_fma_f32 v[6:7], v[6:7], v[24:25], v[14:15]
	v_pk_fma_f32 v[4:5], v[4:5], v[32:33], v[28:29]
	v_mul_f32_e32 v2, v1, v1
	v_mul_f32_e32 v3, v13, v13
	v_mul_f32_e32 v14, v5, v5
	v_mul_f32_e32 v15, v7, v7
	v_fmac_f32_e32 v2, v0, v0
	v_fmac_f32_e32 v3, v12, v12
	v_fmac_f32_e32 v14, v4, v4
	v_fmac_f32_e32 v15, v6, v6
	v_add_f32_e32 v2, v2, v3
	v_add_f32_e32 v3, v14, v15
	v_add_f32_e32 v2, v2, v3
	v_add_f32_e32 v14, v34, v2
	ds_bpermute_b32 v15, v164, v14
	v_cvt_pk_bf16_f32 v2, v0, v1
	v_cvt_pk_bf16_f32 v3, v12, v13
	v_cvt_pk_bf16_f32 v4, v4, v5
	v_cvt_pk_bf16_f32 v5, v6, v7
	s_waitcnt lgkmcnt(0)
	v_add_f32_e32 v0, v14, v15
	ds_bpermute_b32 v1, v149, v0
	v_lshl_add_u64 v[6:7], s[18:19], 0, v[18:19]
	global_store_dwordx4 v[6:7], v[2:5], off
	s_and_saveexec_b64 s[56:57], s[8:9]
	s_cbranch_execz .LBB0_636
	s_waitcnt lgkmcnt(0)
	v_add_f32_e32 v2, v0, v1
	v_lshl_add_u64 v[0:1], s[20:21], 0, v[16:17]
	v_lshl_add_u64 v[0:1], s[54:55], 2, v[0:1]
	s_lshl_b32 s14, s63, 2
	v_lshl_add_u64 v[0:1], v[0:1], 0, s[14:15]
	global_store_dword v[0:1], v2, off

.LBB0_734:
	v_lshl_add_u32 v146, s26, 8, v150
	v_ashrrev_i32_e32 v147, 31, v146
	v_lshlrev_b64 v[148:149], 7, v[146:147]
	v_lshl_add_u64 v[148:149], v[136:137], 0, v[148:149]
	global_load_dwordx4 v[160:163], v[148:149], off
	global_load_dwordx4 v[164:167], v[148:149], off offset:16
	v_and_b32_e32 v149, 64, v156
	v_xor_b32_e32 v158, 16, v156
	v_add_u32_e32 v170, 64, v149
	v_cmp_lt_i32_e32 vcc, v158, v170
	v_xor_b32_e32 v159, 32, v156
	v_lshl_or_b32 v148, s58, 8, v152
	v_cndmask_b32_e32 v158, v156, v158, vcc
	v_lshlrev_b32_e32 v158, 2, v158
	v_cmp_lt_i32_e32 vcc, v159, v170
	v_ashrrev_i32_e32 v149, 31, v148
	v_lshlrev_b64 v[148:149], 1, v[148:149]
	v_cndmask_b32_e32 v159, v156, v159, vcc
	v_lshlrev_b32_e32 v159, 2, v159
	s_waitcnt vmcnt(0)
	v_mov_b32_e32 v168, v160
	v_mov_b32_e32 v169, v164
	v_mov_b32_e32 v164, v161
	v_mov_b32_e32 v160, v162
	v_mov_b32_e32 v161, v166
	v_mov_b32_e32 v166, v163
	v_pk_add_f32 v[162:163], v[168:169], v[164:165]
	v_pk_add_f32 v[160:161], v[160:161], v[166:167]
	s_nop 0
	v_pk_add_f32 v[160:161], v[162:163], v[160:161]
	s_nop 0
	v_add_f32_e32 v160, 0, v160
	v_add_f32_e32 v161, v160, v161
	ds_bpermute_b32 v162, v158, v161
	v_or_b32_e32 v160, 16, v146
	s_waitcnt lgkmcnt(0)
	v_add_f32_e32 v164, v161, v162
	ds_bpermute_b32 v165, v159, v164
	v_lshlrev_b64 v[162:163], 12, v[146:147]
	v_lshl_add_u64 v[162:163], s[12:13], 0, v[162:163]
	v_ashrrev_i32_e32 v161, 31, v160
	v_lshl_add_u64 v[162:163], v[162:163], 0, v[148:149]
	s_waitcnt lgkmcnt(0)
	v_add_f32_e32 v147, v164, v165
	v_fmamk_f32 v147, v147, 0x3a000000, v157
	v_rsq_f32_e32 v166, v147
	v_lshlrev_b64 v[164:165], 7, v[160:161]
	v_lshl_add_u64 v[164:165], v[136:137], 0, v[164:165]
	v_pk_mul_f32 v[126:127], v[126:127], v[166:167] op_sel_hi:[1,0]
	v_pk_mul_f32 v[124:125], v[124:125], v[166:167] op_sel_hi:[1,0]
	v_pk_mul_f32 v[122:123], v[122:123], v[166:167] op_sel_hi:[1,0]
	v_pk_mul_f32 v[120:121], v[120:121], v[166:167] op_sel_hi:[1,0]
	v_pk_mul_f32 v[118:119], v[118:119], v[166:167] op_sel_hi:[1,0]
	v_pk_mul_f32 v[116:117], v[116:117], v[166:167] op_sel_hi:[1,0]
	v_pk_mul_f32 v[168:169], v[114:115], v[166:167] op_sel_hi:[1,0]
	v_pk_mul_f32 v[166:167], v[112:113], v[166:167] op_sel_hi:[1,0]
	v_cvt_pk_bf16_f32 v112, v124, v125
	v_cvt_pk_bf16_f32 v113, v126, v127
	v_cvt_pk_bf16_f32 v114, v120, v121
	v_cvt_pk_bf16_f32 v115, v122, v123
	global_store_dwordx4 v[162:163], v[112:115], off
	s_nop 1
	v_cvt_pk_bf16_f32 v112, v116, v117
	v_cvt_pk_bf16_f32 v113, v118, v119
	v_cvt_pk_bf16_f32 v114, v166, v167
	v_cvt_pk_bf16_f32 v115, v168, v169
	global_store_dwordx4 v[162:163], v[112:115], off offset:256
	global_load_dwordx4 v[112:115], v[164:165], off
	global_load_dwordx4 v[116:119], v[164:165], off offset:16
	s_waitcnt vmcnt(1)
	v_mov_b32_e32 v120, v112
	s_waitcnt vmcnt(0)
	v_mov_b32_e32 v121, v116
	v_mov_b32_e32 v116, v113
	v_mov_b32_e32 v112, v114
	v_mov_b32_e32 v113, v118
	v_mov_b32_e32 v118, v115
	v_pk_add_f32 v[114:115], v[120:121], v[116:117]
	v_pk_add_f32 v[112:113], v[112:113], v[118:119]
	s_nop 0
	v_pk_add_f32 v[112:113], v[114:115], v[112:113]
	v_lshlrev_b64 v[114:115], 12, v[160:161]
	v_add_f32_e32 v112, 0, v112
	v_add_f32_e32 v112, v112, v113
	ds_bpermute_b32 v113, v158, v112
	v_lshl_add_u64 v[114:115], s[12:13], 0, v[114:115]
	v_lshl_add_u64 v[114:115], v[114:115], 0, v[148:149]
	s_waitcnt lgkmcnt(0)
	v_add_f32_e32 v118, v112, v113
	ds_bpermute_b32 v119, v159, v118
	v_or_b32_e32 v112, 32, v146
	v_ashrrev_i32_e32 v113, 31, v112
	v_lshlrev_b64 v[116:117], 7, v[112:113]
	v_lshl_add_u64 v[116:117], v[136:137], 0, v[116:117]
	s_waitcnt lgkmcnt(0)
	v_add_f32_e32 v118, v118, v119
	v_fmamk_f32 v118, v118, 0x3a000000, v157
	v_rsq_f32_e32 v118, v118
	s_nop 0
	v_pk_mul_f32 v[110:111], v[110:111], v[118:119] op_sel_hi:[1,0]
	v_pk_mul_f32 v[108:109], v[108:109], v[118:119] op_sel_hi:[1,0]
	v_pk_mul_f32 v[106:107], v[106:107], v[118:119] op_sel_hi:[1,0]
	v_pk_mul_f32 v[104:105], v[104:105], v[118:119] op_sel_hi:[1,0]
	v_pk_mul_f32 v[102:103], v[102:103], v[118:119] op_sel_hi:[1,0]
	v_pk_mul_f32 v[100:101], v[100:101], v[118:119] op_sel_hi:[1,0]
	v_pk_mul_f32 v[120:121], v[98:99], v[118:119] op_sel_hi:[1,0]
	v_pk_mul_f32 v[118:119], v[96:97], v[118:119] op_sel_hi:[1,0]
	v_cvt_pk_bf16_f32 v96, v108, v109
	v_cvt_pk_bf16_f32 v97, v110, v111
	v_cvt_pk_bf16_f32 v98, v104, v105
	v_cvt_pk_bf16_f32 v99, v106, v107
	global_store_dwordx4 v[114:115], v[96:99], off
	s_nop 1
	v_cvt_pk_bf16_f32 v96, v100, v101
	v_cvt_pk_bf16_f32 v97, v102, v103
	v_cvt_pk_bf16_f32 v98, v118, v119
	v_cvt_pk_bf16_f32 v99, v120, v121
	global_store_dwordx4 v[114:115], v[96:99], off offset:256
	global_load_dwordx4 v[96:99], v[116:117], off
	global_load_dwordx4 v[100:103], v[116:117], off offset:16
	s_waitcnt vmcnt(1)
	v_mov_b32_e32 v104, v96
	s_waitcnt vmcnt(0)
	v_mov_b32_e32 v105, v100
	v_mov_b32_e32 v100, v97
	v_mov_b32_e32 v96, v98
	v_mov_b32_e32 v97, v102
	v_mov_b32_e32 v102, v99
	v_pk_add_f32 v[98:99], v[104:105], v[100:101]
	v_pk_add_f32 v[96:97], v[96:97], v[102:103]
	s_nop 0
	v_pk_add_f32 v[96:97], v[98:99], v[96:97]
	v_lshlrev_b64 v[98:99], 12, v[112:113]
	v_add_f32_e32 v96, 0, v96
	v_add_f32_e32 v96, v96, v97
	ds_bpermute_b32 v97, v158, v96
	v_lshl_add_u64 v[98:99], s[12:13], 0, v[98:99]
	v_lshl_add_u64 v[98:99], v[98:99], 0, v[148:149]
	s_waitcnt lgkmcnt(0)
	v_add_f32_e32 v102, v96, v97
	ds_bpermute_b32 v103, v159, v102
	v_or_b32_e32 v96, 48, v146
	v_ashrrev_i32_e32 v97, 31, v96
	v_lshlrev_b64 v[100:101], 7, v[96:97]
	v_lshl_add_u64 v[100:101], v[136:137], 0, v[100:101]
	s_waitcnt lgkmcnt(0)
	v_add_f32_e32 v102, v102, v103
	v_fmamk_f32 v102, v102, 0x3a000000, v157
	v_rsq_f32_e32 v102, v102
	s_nop 0
	v_pk_mul_f32 v[94:95], v[94:95], v[102:103] op_sel_hi:[1,0]
	v_pk_mul_f32 v[92:93], v[92:93], v[102:103] op_sel_hi:[1,0]
	v_pk_mul_f32 v[90:91], v[90:91], v[102:103] op_sel_hi:[1,0]
	v_pk_mul_f32 v[88:89], v[88:89], v[102:103] op_sel_hi:[1,0]
	v_pk_mul_f32 v[86:87], v[86:87], v[102:103] op_sel_hi:[1,0]
	v_pk_mul_f32 v[84:85], v[84:85], v[102:103] op_sel_hi:[1,0]
	v_pk_mul_f32 v[104:105], v[82:83], v[102:103] op_sel_hi:[1,0]
	v_pk_mul_f32 v[102:103], v[80:81], v[102:103] op_sel_hi:[1,0]
	v_cvt_pk_bf16_f32 v80, v92, v93
	v_cvt_pk_bf16_f32 v81, v94, v95
	v_cvt_pk_bf16_f32 v82, v88, v89
	v_cvt_pk_bf16_f32 v83, v90, v91
	global_store_dwordx4 v[98:99], v[80:83], off
	s_nop 1
	v_cvt_pk_bf16_f32 v80, v84, v85
	v_cvt_pk_bf16_f32 v81, v86, v87
	v_cvt_pk_bf16_f32 v82, v102, v103
	v_cvt_pk_bf16_f32 v83, v104, v105
	global_store_dwordx4 v[98:99], v[80:83], off offset:256
	global_load_dwordx4 v[80:83], v[100:101], off
	global_load_dwordx4 v[84:87], v[100:101], off offset:16
	s_waitcnt vmcnt(1)
	v_mov_b32_e32 v88, v80
	s_waitcnt vmcnt(0)
	v_mov_b32_e32 v89, v84
	v_mov_b32_e32 v84, v81
	v_mov_b32_e32 v80, v82
	v_mov_b32_e32 v81, v86
	v_mov_b32_e32 v86, v83
	v_pk_add_f32 v[82:83], v[88:89], v[84:85]
	v_pk_add_f32 v[80:81], v[80:81], v[86:87]
	s_nop 0
	v_pk_add_f32 v[80:81], v[82:83], v[80:81]
	v_lshlrev_b64 v[82:83], 12, v[96:97]
	v_add_f32_e32 v80, 0, v80
	v_add_f32_e32 v80, v80, v81
	ds_bpermute_b32 v81, v158, v80
	v_lshl_add_u64 v[82:83], s[12:13], 0, v[82:83]
	v_lshl_add_u64 v[82:83], v[82:83], 0, v[148:149]
	s_waitcnt lgkmcnt(0)
	v_add_f32_e32 v86, v80, v81
	ds_bpermute_b32 v87, v159, v86
	v_add_u32_e32 v80, 0x80, v146
	v_ashrrev_i32_e32 v81, 31, v80
	v_lshlrev_b64 v[84:85], 7, v[80:81]
	v_lshl_add_u64 v[84:85], v[136:137], 0, v[84:85]
	s_waitcnt lgkmcnt(0)
	v_add_f32_e32 v86, v86, v87
	v_fmamk_f32 v86, v86, 0x3a000000, v157
	v_rsq_f32_e32 v86, v86
	s_nop 0
	v_pk_mul_f32 v[78:79], v[78:79], v[86:87] op_sel_hi:[1,0]
	v_pk_mul_f32 v[76:77], v[76:77], v[86:87] op_sel_hi:[1,0]
	v_pk_mul_f32 v[74:75], v[74:75], v[86:87] op_sel_hi:[1,0]
	v_pk_mul_f32 v[72:73], v[72:73], v[86:87] op_sel_hi:[1,0]
	v_pk_mul_f32 v[70:71], v[70:71], v[86:87] op_sel_hi:[1,0]
	v_pk_mul_f32 v[68:69], v[68:69], v[86:87] op_sel_hi:[1,0]
	v_pk_mul_f32 v[88:89], v[66:67], v[86:87] op_sel_hi:[1,0]
	v_pk_mul_f32 v[86:87], v[64:65], v[86:87] op_sel_hi:[1,0]
	v_cvt_pk_bf16_f32 v64, v76, v77
	v_cvt_pk_bf16_f32 v65, v78, v79
	v_cvt_pk_bf16_f32 v66, v72, v73
	v_cvt_pk_bf16_f32 v67, v74, v75
	global_store_dwordx4 v[82:83], v[64:67], off
	s_nop 1
	v_cvt_pk_bf16_f32 v64, v68, v69
	v_cvt_pk_bf16_f32 v65, v70, v71
	v_cvt_pk_bf16_f32 v66, v86, v87
	v_cvt_pk_bf16_f32 v67, v88, v89
	global_store_dwordx4 v[82:83], v[64:67], off offset:256
	global_load_dwordx4 v[64:67], v[84:85], off
	global_load_dwordx4 v[68:71], v[84:85], off offset:16
	s_waitcnt vmcnt(1)
	v_mov_b32_e32 v72, v64
	s_waitcnt vmcnt(0)
	v_mov_b32_e32 v73, v68
	v_mov_b32_e32 v68, v65
	v_mov_b32_e32 v64, v66
	v_mov_b32_e32 v65, v70
	v_mov_b32_e32 v70, v67
	v_pk_add_f32 v[66:67], v[72:73], v[68:69]
	v_pk_add_f32 v[64:65], v[64:65], v[70:71]
	s_nop 0
	v_pk_add_f32 v[64:65], v[66:67], v[64:65]
	v_lshlrev_b64 v[66:67], 12, v[80:81]
	v_add_f32_e32 v64, 0, v64
	v_add_f32_e32 v64, v64, v65
	ds_bpermute_b32 v65, v158, v64
	v_lshl_add_u64 v[66:67], s[12:13], 0, v[66:67]
	v_lshl_add_u64 v[66:67], v[66:67], 0, v[148:149]
	s_waitcnt lgkmcnt(0)
	v_add_f32_e32 v70, v64, v65
	ds_bpermute_b32 v71, v159, v70
	v_add_u32_e32 v64, 0x90, v146
	v_ashrrev_i32_e32 v65, 31, v64
	v_lshlrev_b64 v[68:69], 7, v[64:65]
	v_lshl_add_u64 v[68:69], v[136:137], 0, v[68:69]
	s_waitcnt lgkmcnt(0)
	v_add_f32_e32 v70, v70, v71
	v_fmamk_f32 v70, v70, 0x3a000000, v157
	v_rsq_f32_e32 v70, v70
	s_nop 0
	v_pk_mul_f32 v[62:63], v[62:63], v[70:71] op_sel_hi:[1,0]
	v_pk_mul_f32 v[60:61], v[60:61], v[70:71] op_sel_hi:[1,0]
	v_pk_mul_f32 v[58:59], v[58:59], v[70:71] op_sel_hi:[1,0]
	v_pk_mul_f32 v[56:57], v[56:57], v[70:71] op_sel_hi:[1,0]
	v_pk_mul_f32 v[54:55], v[54:55], v[70:71] op_sel_hi:[1,0]
	v_pk_mul_f32 v[52:53], v[52:53], v[70:71] op_sel_hi:[1,0]
	v_pk_mul_f32 v[72:73], v[50:51], v[70:71] op_sel_hi:[1,0]
	v_pk_mul_f32 v[70:71], v[48:49], v[70:71] op_sel_hi:[1,0]
	v_cvt_pk_bf16_f32 v48, v60, v61
	v_cvt_pk_bf16_f32 v49, v62, v63
	v_cvt_pk_bf16_f32 v50, v56, v57
	v_cvt_pk_bf16_f32 v51, v58, v59
	global_store_dwordx4 v[66:67], v[48:51], off
	s_nop 1
	v_cvt_pk_bf16_f32 v48, v52, v53
	v_cvt_pk_bf16_f32 v49, v54, v55
	v_cvt_pk_bf16_f32 v50, v70, v71
	v_cvt_pk_bf16_f32 v51, v72, v73
	global_store_dwordx4 v[66:67], v[48:51], off offset:256
	global_load_dwordx4 v[48:51], v[68:69], off
	global_load_dwordx4 v[52:55], v[68:69], off offset:16
	s_waitcnt vmcnt(1)
	v_mov_b32_e32 v56, v48
	s_waitcnt vmcnt(0)
	v_mov_b32_e32 v57, v52
	v_mov_b32_e32 v52, v49
	v_mov_b32_e32 v48, v50
	v_mov_b32_e32 v49, v54
	v_mov_b32_e32 v54, v51
	v_pk_add_f32 v[50:51], v[56:57], v[52:53]
	v_pk_add_f32 v[48:49], v[48:49], v[54:55]
	s_nop 0
	v_pk_add_f32 v[48:49], v[50:51], v[48:49]
	v_lshlrev_b64 v[50:51], 12, v[64:65]
	v_add_f32_e32 v48, 0, v48
	v_add_f32_e32 v48, v48, v49
	ds_bpermute_b32 v49, v158, v48
	v_lshl_add_u64 v[50:51], s[12:13], 0, v[50:51]
	v_lshl_add_u64 v[50:51], v[50:51], 0, v[148:149]
	s_waitcnt lgkmcnt(0)
	v_add_f32_e32 v54, v48, v49
	ds_bpermute_b32 v55, v159, v54
	v_add_u32_e32 v48, 0xa0, v146
	v_ashrrev_i32_e32 v49, 31, v48
	v_lshlrev_b64 v[52:53], 7, v[48:49]
	v_lshl_add_u64 v[52:53], v[136:137], 0, v[52:53]
	s_waitcnt lgkmcnt(0)
	v_add_f32_e32 v54, v54, v55
	v_fmamk_f32 v54, v54, 0x3a000000, v157
	v_rsq_f32_e32 v54, v54
	s_nop 0
	v_pk_mul_f32 v[46:47], v[46:47], v[54:55] op_sel_hi:[1,0]
	v_pk_mul_f32 v[44:45], v[44:45], v[54:55] op_sel_hi:[1,0]
	v_pk_mul_f32 v[42:43], v[42:43], v[54:55] op_sel_hi:[1,0]
	v_pk_mul_f32 v[40:41], v[40:41], v[54:55] op_sel_hi:[1,0]
	v_pk_mul_f32 v[38:39], v[38:39], v[54:55] op_sel_hi:[1,0]
	v_pk_mul_f32 v[36:37], v[36:37], v[54:55] op_sel_hi:[1,0]
	v_pk_mul_f32 v[56:57], v[34:35], v[54:55] op_sel_hi:[1,0]
	v_pk_mul_f32 v[54:55], v[32:33], v[54:55] op_sel_hi:[1,0]
	v_cvt_pk_bf16_f32 v32, v44, v45
	v_cvt_pk_bf16_f32 v33, v46, v47
	v_cvt_pk_bf16_f32 v34, v40, v41
	v_cvt_pk_bf16_f32 v35, v42, v43
	global_store_dwordx4 v[50:51], v[32:35], off
	s_nop 1
	v_cvt_pk_bf16_f32 v32, v36, v37
	v_cvt_pk_bf16_f32 v33, v38, v39
	v_cvt_pk_bf16_f32 v34, v54, v55
	v_cvt_pk_bf16_f32 v35, v56, v57
	global_store_dwordx4 v[50:51], v[32:35], off offset:256
	global_load_dwordx4 v[32:35], v[52:53], off
	global_load_dwordx4 v[36:39], v[52:53], off offset:16
	s_waitcnt vmcnt(1)
	v_mov_b32_e32 v40, v32
	s_waitcnt vmcnt(0)
	v_mov_b32_e32 v41, v36
	v_mov_b32_e32 v36, v33
	v_mov_b32_e32 v32, v34
	v_mov_b32_e32 v33, v38
	v_mov_b32_e32 v38, v35
	v_pk_add_f32 v[34:35], v[40:41], v[36:37]
	v_pk_add_f32 v[32:33], v[32:33], v[38:39]
	s_nop 0
	v_pk_add_f32 v[32:33], v[34:35], v[32:33]
	v_lshlrev_b64 v[34:35], 12, v[48:49]
	v_add_f32_e32 v32, 0, v32
	v_add_f32_e32 v32, v32, v33
	ds_bpermute_b32 v33, v158, v32
	v_lshl_add_u64 v[34:35], s[12:13], 0, v[34:35]
	v_lshl_add_u64 v[34:35], v[34:35], 0, v[148:149]
	s_waitcnt lgkmcnt(0)
	v_add_f32_e32 v38, v32, v33
	ds_bpermute_b32 v39, v159, v38
	v_add_u32_e32 v32, 0xb0, v146
	v_ashrrev_i32_e32 v33, 31, v32
	v_lshlrev_b64 v[36:37], 7, v[32:33]
	v_lshl_add_u64 v[36:37], v[136:137], 0, v[36:37]
	s_waitcnt lgkmcnt(0)
	v_add_f32_e32 v38, v38, v39
	v_fmamk_f32 v38, v38, 0x3a000000, v157
	v_rsq_f32_e32 v38, v38
	s_nop 0
	v_pk_mul_f32 v[30:31], v[30:31], v[38:39] op_sel_hi:[1,0]
	v_pk_mul_f32 v[28:29], v[28:29], v[38:39] op_sel_hi:[1,0]
	v_pk_mul_f32 v[26:27], v[26:27], v[38:39] op_sel_hi:[1,0]
	v_pk_mul_f32 v[24:25], v[24:25], v[38:39] op_sel_hi:[1,0]
	v_pk_mul_f32 v[22:23], v[22:23], v[38:39] op_sel_hi:[1,0]
	v_pk_mul_f32 v[20:21], v[20:21], v[38:39] op_sel_hi:[1,0]
	v_pk_mul_f32 v[40:41], v[18:19], v[38:39] op_sel_hi:[1,0]
	v_pk_mul_f32 v[38:39], v[16:17], v[38:39] op_sel_hi:[1,0]
	v_cvt_pk_bf16_f32 v16, v28, v29
	v_cvt_pk_bf16_f32 v17, v30, v31
	v_cvt_pk_bf16_f32 v18, v24, v25
	v_cvt_pk_bf16_f32 v19, v26, v27
	global_store_dwordx4 v[34:35], v[16:19], off
	s_nop 1
	v_cvt_pk_bf16_f32 v16, v20, v21
	v_cvt_pk_bf16_f32 v17, v22, v23
	v_cvt_pk_bf16_f32 v18, v38, v39
	v_cvt_pk_bf16_f32 v19, v40, v41
	global_store_dwordx4 v[34:35], v[16:19], off offset:256
	global_load_dwordx4 v[16:19], v[36:37], off
	global_load_dwordx4 v[20:23], v[36:37], off offset:16
	s_waitcnt vmcnt(1)
	v_mov_b32_e32 v24, v16
	s_waitcnt vmcnt(0)
	v_mov_b32_e32 v25, v20
	v_mov_b32_e32 v20, v17
	v_mov_b32_e32 v16, v18
	v_mov_b32_e32 v17, v22
	v_mov_b32_e32 v22, v19
	v_pk_add_f32 v[18:19], v[24:25], v[20:21]
	v_pk_add_f32 v[16:17], v[16:17], v[22:23]
	s_nop 0
	v_pk_add_f32 v[16:17], v[18:19], v[16:17]
	s_nop 0
	v_add_f32_e32 v16, 0, v16
	v_add_f32_e32 v16, v16, v17
	ds_bpermute_b32 v17, v158, v16
	s_waitcnt lgkmcnt(0)
	v_add_f32_e32 v16, v16, v17
	ds_bpermute_b32 v17, v159, v16
	s_waitcnt lgkmcnt(0)
	v_add_f32_e32 v16, v16, v17
	v_fmamk_f32 v16, v16, 0x3a000000, v157
	v_rsq_f32_e32 v18, v16
	v_lshlrev_b64 v[16:17], 12, v[32:33]
	v_lshl_add_u64 v[16:17], s[12:13], 0, v[16:17]
	v_lshl_add_u64 v[16:17], v[16:17], 0, v[148:149]
	v_pk_mul_f32 v[14:15], v[14:15], v[18:19] op_sel_hi:[1,0]
	v_pk_mul_f32 v[12:13], v[12:13], v[18:19] op_sel_hi:[1,0]
	v_pk_mul_f32 v[10:11], v[10:11], v[18:19] op_sel_hi:[1,0]
	v_pk_mul_f32 v[8:9], v[8:9], v[18:19] op_sel_hi:[1,0]
	v_pk_mul_f32 v[6:7], v[6:7], v[18:19] op_sel_hi:[1,0]
	v_pk_mul_f32 v[4:5], v[4:5], v[18:19] op_sel_hi:[1,0]
	v_pk_mul_f32 v[20:21], v[2:3], v[18:19] op_sel_hi:[1,0]
	v_pk_mul_f32 v[18:19], v[0:1], v[18:19] op_sel_hi:[1,0]
	v_cvt_pk_bf16_f32 v0, v12, v13
	v_cvt_pk_bf16_f32 v1, v14, v15
	v_cvt_pk_bf16_f32 v2, v8, v9
	v_cvt_pk_bf16_f32 v3, v10, v11
	global_store_dwordx4 v[16:17], v[0:3], off
	s_andn2_b64 vcc, exec, s[8:9]
	s_mov_b64 s[8:9], -1
	v_cvt_pk_bf16_f32 v0, v4, v5
	v_cvt_pk_bf16_f32 v1, v6, v7
	v_cvt_pk_bf16_f32 v2, v18, v19
	v_cvt_pk_bf16_f32 v3, v20, v21
	global_store_dwordx4 v[16:17], v[0:3], off offset:256
	s_cbranch_vccnz .LBB0_723
	s_andn2_b64 vcc, exec, s[10:11]
	s_cbranch_vccnz .LBB0_722
	s_barrier
	s_branch .LBB0_722

.LBB0_1055:
	s_lshl_b32 s21, s34, 8
	s_cmp_eq_u32 s71, 2
	s_cselect_b32 s23, 0x80, 0
	s_or_b32 s21, s21, s23
	v_add_u32_e32 v132, s21, v219
	v_ashrrev_i32_e32 v133, 31, v132
	v_lshlrev_b64 v[2:3], 8, v[132:133]
	v_lshl_add_u64 v[2:3], v[204:205], 0, v[2:3]
	global_load_dwordx4 v[134:137], v[2:3], off
	global_load_dwordx4 v[138:141], v[2:3], off offset:16
	global_load_dwordx4 v[142:145], v[2:3], off offset:32
	global_load_dwordx4 v[146:149], v[2:3], off offset:48
	v_mov_b32_e32 v150, v128
	v_mov_b32_e32 v151, v124
	v_mov_b32_e32 v124, v129
	v_mov_b32_e32 v152, v130
	v_mov_b32_e32 v153, v126
	v_mov_b32_e32 v126, v131
	v_and_b32_e32 v3, 64, v225
	v_xor_b32_e32 v1, 16, v225
	v_add_u32_e32 v3, 64, v3
	v_cmp_lt_i32_e32 vcc, v1, v3
	v_xor_b32_e32 v133, 32, v225
	v_lshl_or_b32 v2, s72, 7, v221
	v_cndmask_b32_e32 v1, v225, v1, vcc
	v_lshlrev_b32_e32 v1, 2, v1
	v_cmp_lt_i32_e32 vcc, v133, v3
	s_waitcnt vmcnt(0)
	v_mov_b32_e32 v128, v135
	v_mov_b32_e32 v129, v136
	v_mov_b32_e32 v135, v137
	v_mov_b32_e32 v130, v139
	v_mov_b32_e32 v131, v140
	v_mov_b32_e32 v139, v141
	v_add_f32_e32 v136, v142, v143
	v_add_f32_e32 v140, v144, v145
	v_mov_b32_e32 v137, v148
	v_mov_b32_e32 v141, v149
	v_pk_add_f32 v[128:129], v[128:129], v[134:135]
	v_pk_add_f32 v[130:131], v[130:131], v[138:139]
	v_pk_add_f32 v[134:135], v[136:137], v[140:141]
	v_add_f32_e32 v136, v128, v129
	v_pk_add_f32 v[128:129], v[130:131], v[130:131] op_sel:[0,1] op_sel_hi:[1,0]
	v_mov_b32_e32 v143, v146
	v_add_f32_e32 v142, 0, v136
	v_mov_b32_e32 v129, v147
	v_pk_add_f32 v[128:129], v[142:143], v[128:129]
	v_cndmask_b32_e32 v3, v225, v133, vcc
	v_pk_add_f32 v[128:129], v[128:129], v[134:135]
	v_mov_b32_e32 v130, v116
	v_add_f32_e32 v129, v128, v129
	ds_bpermute_b32 v131, v1, v129
	v_lshlrev_b32_e32 v128, 2, v3
	v_mov_b32_e32 v134, v118
	v_mov_b32_e32 v135, v122
	v_mov_b32_e32 v122, v119
	s_waitcnt lgkmcnt(0)
	v_add_f32_e32 v3, v129, v131
	ds_bpermute_b32 v116, v128, v3
	v_mov_b32_e32 v131, v120
	v_mov_b32_e32 v120, v117
	s_waitcnt lgkmcnt(0)
	v_add_f32_e32 v3, v3, v116
	v_fmamk_f32 v3, v3, 0x3a000000, v226
	v_rsq_f32_e32 v118, v3
	v_mov_b64_e32 v[116:117], s[12:13]
	v_ashrrev_i32_e32 v3, 31, v2
	v_lshlrev_b64 v[2:3], 1, v[2:3]
	v_pk_mul_f32 v[136:137], v[150:151], v[118:119] op_sel_hi:[1,0]
	v_pk_mul_f32 v[124:125], v[124:125], v[118:119] op_sel_hi:[1,0]
	v_pk_mul_f32 v[138:139], v[152:153], v[118:119] op_sel_hi:[1,0]
	v_pk_mul_f32 v[126:127], v[126:127], v[118:119] op_sel_hi:[1,0]
	v_pk_mul_f32 v[130:131], v[130:131], v[118:119] op_sel_hi:[1,0]
	v_pk_mul_f32 v[120:121], v[120:121], v[118:119] op_sel_hi:[1,0]
	v_pk_mul_f32 v[134:135], v[134:135], v[118:119] op_sel_hi:[1,0]
	v_pk_mul_f32 v[118:119], v[122:123], v[118:119] op_sel_hi:[1,0]
	v_mul_f32_e32 v122, 0xbfb8aa3b, v137
	v_mul_f32_e32 v123, 0xbfb8aa3b, v125
	v_mul_f32_e32 v129, 0xbfb8aa3b, v139
	v_mul_f32_e32 v133, 0xbfb8aa3b, v127
	v_mul_f32_e32 v140, 0xbfb8aa3b, v131
	v_mul_f32_e32 v141, 0xbfb8aa3b, v121
	v_mul_f32_e32 v142, 0xbfb8aa3b, v135
	v_mul_f32_e32 v143, 0xbfb8aa3b, v119
	v_exp_f32_e32 v122, v122
	v_exp_f32_e32 v123, v123
	v_exp_f32_e32 v129, v129
	v_exp_f32_e32 v133, v133
	v_exp_f32_e32 v140, v140
	v_exp_f32_e32 v141, v141
	v_exp_f32_e32 v142, v142
	v_exp_f32_e32 v143, v143
	v_add_f32_e32 v122, 1.0, v122
	v_add_f32_e32 v123, 1.0, v123
	v_add_f32_e32 v129, 1.0, v129
	v_add_f32_e32 v133, 1.0, v133
	v_add_f32_e32 v140, 1.0, v140
	v_add_f32_e32 v141, 1.0, v141
	v_add_f32_e32 v142, 1.0, v142
	v_add_f32_e32 v143, 1.0, v143
	v_rcp_f32_e32 v122, v122
	v_rcp_f32_e32 v123, v123
	v_rcp_f32_e32 v129, v129
	v_rcp_f32_e32 v133, v133
	v_rcp_f32_e32 v140, v140
	v_rcp_f32_e32 v141, v141
	v_rcp_f32_e32 v142, v142
	v_rcp_f32_e32 v143, v143
	v_mul_f32_e32 v122, v137, v122
	v_mul_f32_e32 v123, v125, v123
	v_mul_f32_e32 v125, v139, v129
	v_mul_f32_e32 v127, v127, v133
	v_mul_f32_e32 v129, v131, v140
	v_mul_f32_e32 v121, v121, v141
	v_mul_f32_e32 v131, v135, v142
	v_mul_f32_e32 v119, v119, v143
	v_mul_f32_e32 v122, v136, v122
	v_mul_f32_e32 v123, v124, v123
	v_mul_f32_e32 v124, v138, v125
	v_mul_f32_e32 v125, v126, v127
	v_mul_f32_e32 v126, v130, v129
	v_mul_f32_e32 v120, v120, v121
	v_mul_f32_e32 v121, v134, v131
	v_mul_f32_e32 v127, v118, v119
	v_cvt_pk_bf16_f32 v118, v122, v123
	v_cvt_pk_bf16_f32 v119, v124, v125
	v_cvt_pk_bf16_f32 v120, v126, v120
	v_mad_i64_i32 v[122:123], s[36:37], v132, s68, v[116:117]
	v_or_b32_e32 v126, 16, v132
	v_cvt_pk_bf16_f32 v121, v121, v127
	v_lshl_add_u64 v[122:123], v[122:123], 0, v[2:3]
	v_ashrrev_i32_e32 v127, 31, v126
	global_store_dwordx4 v[122:123], v[118:121], off
	s_nop 1
	v_lshlrev_b64 v[118:119], 8, v[126:127]
	v_lshl_add_u64 v[130:131], v[204:205], 0, v[118:119]
	global_load_dwordx4 v[118:121], v[130:131], off
	global_load_dwordx4 v[122:125], v[130:131], off offset:16
	global_load_dwordx4 v[134:137], v[130:131], off offset:32
	global_load_dwordx4 v[138:141], v[130:131], off offset:48
	v_mov_b32_e32 v131, v104
	v_mov_b32_e32 v104, v113
	v_mov_b32_e32 v113, v106
	v_mov_b32_e32 v106, v115
	v_mov_b32_e32 v115, v100
	v_mov_b32_e32 v130, v112
	v_mov_b32_e32 v112, v114
	v_mov_b32_e32 v114, v108
	v_mov_b32_e32 v108, v110
	s_waitcnt vmcnt(3)
	v_mov_b32_e32 v142, v119
	v_mov_b32_e32 v143, v120
	v_mov_b32_e32 v119, v121
	s_waitcnt vmcnt(2)
	v_mov_b32_e32 v120, v123
	v_mov_b32_e32 v121, v124
	v_mov_b32_e32 v123, v125
	v_pk_add_f32 v[118:119], v[142:143], v[118:119]
	v_pk_add_f32 v[120:121], v[120:121], v[122:123]
	v_add_f32_e32 v100, v118, v119
	v_pk_add_f32 v[118:119], v[120:121], v[120:121] op_sel:[0,1] op_sel_hi:[1,0]
	s_waitcnt vmcnt(1)
	v_add_f32_e32 v124, v134, v135
	v_add_f32_e32 v134, v136, v137
	s_waitcnt vmcnt(0)
	v_mov_b32_e32 v137, v138
	v_mov_b32_e32 v125, v140
	v_mov_b32_e32 v135, v141
	v_add_f32_e32 v136, 0, v100
	v_mov_b32_e32 v119, v139
	v_pk_add_f32 v[122:123], v[124:125], v[134:135]
	v_pk_add_f32 v[118:119], v[136:137], v[118:119]
	v_mov_b32_e32 v100, v109
	v_pk_add_f32 v[118:119], v[118:119], v[122:123]
	v_mov_b32_e32 v109, v102
	v_add_f32_e32 v118, v118, v119
	ds_bpermute_b32 v119, v1, v118
	v_mov_b32_e32 v102, v111
	v_mad_i64_i32 v[110:111], s[36:37], v126, s68, v[116:117]
	v_lshl_add_u64 v[110:111], v[110:111], 0, v[2:3]
	s_waitcnt lgkmcnt(0)
	v_add_f32_e32 v120, v118, v119
	ds_bpermute_b32 v121, v128, v120
	v_or_b32_e32 v118, 32, v132
	v_ashrrev_i32_e32 v119, 31, v118
	s_waitcnt lgkmcnt(0)
	v_add_f32_e32 v120, v120, v121
	v_fmamk_f32 v120, v120, 0x3a000000, v226
	v_rsq_f32_e32 v122, v120
	v_lshlrev_b64 v[120:121], 8, v[118:119]
	v_lshl_add_u64 v[120:121], v[204:205], 0, v[120:121]
	v_pk_mul_f32 v[102:103], v[102:103], v[122:123] op_sel_hi:[1,0]
	v_pk_mul_f32 v[124:125], v[130:131], v[122:123] op_sel_hi:[1,0]
	v_pk_mul_f32 v[104:105], v[104:105], v[122:123] op_sel_hi:[1,0]
	v_pk_mul_f32 v[112:113], v[112:113], v[122:123] op_sel_hi:[1,0]
	v_pk_mul_f32 v[106:107], v[106:107], v[122:123] op_sel_hi:[1,0]
	v_pk_mul_f32 v[114:115], v[114:115], v[122:123] op_sel_hi:[1,0]
	v_pk_mul_f32 v[100:101], v[100:101], v[122:123] op_sel_hi:[1,0]
	v_pk_mul_f32 v[108:109], v[108:109], v[122:123] op_sel_hi:[1,0]
	v_mul_f32_e32 v131, 0xbfb8aa3b, v103
	v_mul_f32_e32 v119, 0xbfb8aa3b, v125
	v_mul_f32_e32 v122, 0xbfb8aa3b, v105
	v_mul_f32_e32 v123, 0xbfb8aa3b, v113
	v_mul_f32_e32 v126, 0xbfb8aa3b, v107
	v_mul_f32_e32 v127, 0xbfb8aa3b, v115
	v_mul_f32_e32 v129, 0xbfb8aa3b, v101
	v_mul_f32_e32 v130, 0xbfb8aa3b, v109
	v_exp_f32_e32 v131, v131
	v_exp_f32_e32 v119, v119
	v_exp_f32_e32 v122, v122
	v_exp_f32_e32 v123, v123
	v_exp_f32_e32 v126, v126
	v_exp_f32_e32 v127, v127
	v_exp_f32_e32 v129, v129
	v_exp_f32_e32 v130, v130
	v_add_f32_e32 v131, 1.0, v131
	v_add_f32_e32 v119, 1.0, v119
	v_add_f32_e32 v122, 1.0, v122
	v_add_f32_e32 v123, 1.0, v123
	v_add_f32_e32 v126, 1.0, v126
	v_add_f32_e32 v127, 1.0, v127
	v_add_f32_e32 v129, 1.0, v129
	v_add_f32_e32 v130, 1.0, v130
	v_rcp_f32_e32 v131, v131
	v_rcp_f32_e32 v119, v119
	v_rcp_f32_e32 v122, v122
	v_rcp_f32_e32 v123, v123
	v_rcp_f32_e32 v126, v126
	v_rcp_f32_e32 v127, v127
	v_rcp_f32_e32 v129, v129
	v_rcp_f32_e32 v130, v130
	v_mul_f32_e32 v103, v103, v131
	v_mul_f32_e32 v119, v125, v119
	v_mul_f32_e32 v105, v105, v122
	v_mul_f32_e32 v113, v113, v123
	v_mul_f32_e32 v107, v107, v126
	v_mul_f32_e32 v115, v115, v127
	v_mul_f32_e32 v101, v101, v129
	v_mul_f32_e32 v109, v109, v130
	v_mul_f32_e32 v103, v102, v103
	v_mul_f32_e32 v119, v124, v119
	v_mul_f32_e32 v104, v104, v105
	v_mul_f32_e32 v105, v112, v113
	v_mul_f32_e32 v106, v106, v107
	v_mul_f32_e32 v107, v114, v115
	v_mul_f32_e32 v112, v100, v101
	v_mul_f32_e32 v108, v108, v109
	v_cvt_pk_bf16_f32 v100, v119, v104
	v_cvt_pk_bf16_f32 v101, v105, v106
	v_cvt_pk_bf16_f32 v102, v107, v112
	v_cvt_pk_bf16_f32 v103, v108, v103
	global_store_dwordx4 v[110:111], v[100:103], off
	global_load_dwordx4 v[100:103], v[120:121], off
	global_load_dwordx4 v[104:107], v[120:121], off offset:16
	global_load_dwordx4 v[108:111], v[120:121], off offset:32
	global_load_dwordx4 v[112:115], v[120:121], off offset:48
	v_mov_b32_e32 v121, v88
	v_mov_b32_e32 v88, v97
	v_mov_b32_e32 v97, v90
	v_mov_b32_e32 v90, v99
	v_mov_b32_e32 v99, v84
	v_mov_b32_e32 v120, v96
	v_mov_b32_e32 v96, v98
	v_mov_b32_e32 v98, v92
	v_mov_b32_e32 v92, v94
	s_waitcnt vmcnt(3)
	v_mov_b32_e32 v122, v101
	v_mov_b32_e32 v123, v102
	v_mov_b32_e32 v101, v103
	s_waitcnt vmcnt(2)
	v_mov_b32_e32 v102, v105
	v_mov_b32_e32 v103, v106
	v_mov_b32_e32 v105, v107
	v_pk_add_f32 v[100:101], v[122:123], v[100:101]
	v_pk_add_f32 v[102:103], v[102:103], v[104:105]
	v_add_f32_e32 v84, v100, v101
	v_pk_add_f32 v[100:101], v[102:103], v[102:103] op_sel:[0,1] op_sel_hi:[1,0]
	s_waitcnt vmcnt(1)
	v_add_f32_e32 v106, v108, v109
	v_add_f32_e32 v108, v110, v111
	s_waitcnt vmcnt(0)
	v_mov_b32_e32 v111, v112
	v_mov_b32_e32 v107, v114
	v_mov_b32_e32 v109, v115
	v_add_f32_e32 v110, 0, v84
	v_mov_b32_e32 v101, v113
	v_pk_add_f32 v[104:105], v[106:107], v[108:109]
	v_pk_add_f32 v[100:101], v[110:111], v[100:101]
	v_mov_b32_e32 v84, v93
	v_pk_add_f32 v[100:101], v[100:101], v[104:105]
	v_mov_b32_e32 v93, v86
	v_add_f32_e32 v100, v100, v101
	ds_bpermute_b32 v101, v1, v100
	v_mov_b32_e32 v86, v95
	v_mad_i64_i32 v[94:95], s[36:37], v118, s68, v[116:117]
	v_lshl_add_u64 v[94:95], v[94:95], 0, v[2:3]
	s_waitcnt lgkmcnt(0)
	v_add_f32_e32 v102, v100, v101
	ds_bpermute_b32 v103, v128, v102
	v_or_b32_e32 v100, 48, v132
	v_ashrrev_i32_e32 v101, 31, v100
	s_waitcnt lgkmcnt(0)
	v_add_f32_e32 v102, v102, v103
	v_fmamk_f32 v102, v102, 0x3a000000, v226
	v_rsq_f32_e32 v104, v102
	v_lshlrev_b64 v[102:103], 8, v[100:101]
	v_lshl_add_u64 v[102:103], v[204:205], 0, v[102:103]
	v_pk_mul_f32 v[86:87], v[86:87], v[104:105] op_sel_hi:[1,0]
	v_pk_mul_f32 v[106:107], v[120:121], v[104:105] op_sel_hi:[1,0]
	v_pk_mul_f32 v[88:89], v[88:89], v[104:105] op_sel_hi:[1,0]
	v_pk_mul_f32 v[96:97], v[96:97], v[104:105] op_sel_hi:[1,0]
	v_pk_mul_f32 v[90:91], v[90:91], v[104:105] op_sel_hi:[1,0]
	v_pk_mul_f32 v[98:99], v[98:99], v[104:105] op_sel_hi:[1,0]
	v_pk_mul_f32 v[84:85], v[84:85], v[104:105] op_sel_hi:[1,0]
	v_pk_mul_f32 v[92:93], v[92:93], v[104:105] op_sel_hi:[1,0]
	v_mul_f32_e32 v112, 0xbfb8aa3b, v87
	v_mul_f32_e32 v101, 0xbfb8aa3b, v107
	v_mul_f32_e32 v104, 0xbfb8aa3b, v89
	v_mul_f32_e32 v105, 0xbfb8aa3b, v97
	v_mul_f32_e32 v108, 0xbfb8aa3b, v91
	v_mul_f32_e32 v109, 0xbfb8aa3b, v99
	v_mul_f32_e32 v110, 0xbfb8aa3b, v85
	v_mul_f32_e32 v111, 0xbfb8aa3b, v93
	v_exp_f32_e32 v112, v112
	v_exp_f32_e32 v101, v101
	v_exp_f32_e32 v104, v104
	v_exp_f32_e32 v105, v105
	v_exp_f32_e32 v108, v108
	v_exp_f32_e32 v109, v109
	v_exp_f32_e32 v110, v110
	v_exp_f32_e32 v111, v111
	v_add_f32_e32 v112, 1.0, v112
	v_add_f32_e32 v101, 1.0, v101
	v_add_f32_e32 v104, 1.0, v104
	v_add_f32_e32 v105, 1.0, v105
	v_add_f32_e32 v108, 1.0, v108
	v_add_f32_e32 v109, 1.0, v109
	v_add_f32_e32 v110, 1.0, v110
	v_add_f32_e32 v111, 1.0, v111
	v_rcp_f32_e32 v112, v112
	v_rcp_f32_e32 v101, v101
	v_rcp_f32_e32 v104, v104
	v_rcp_f32_e32 v105, v105
	v_rcp_f32_e32 v108, v108
	v_rcp_f32_e32 v109, v109
	v_rcp_f32_e32 v110, v110
	v_rcp_f32_e32 v111, v111
	v_mul_f32_e32 v87, v87, v112
	v_mul_f32_e32 v101, v107, v101
	v_mul_f32_e32 v89, v89, v104
	v_mul_f32_e32 v97, v97, v105
	v_mul_f32_e32 v91, v91, v108
	v_mul_f32_e32 v99, v99, v109
	v_mul_f32_e32 v85, v85, v110
	v_mul_f32_e32 v93, v93, v111
	v_mul_f32_e32 v87, v86, v87
	v_mul_f32_e32 v101, v106, v101
	v_mul_f32_e32 v88, v88, v89
	v_mul_f32_e32 v89, v96, v97
	v_mul_f32_e32 v90, v90, v91
	v_mul_f32_e32 v91, v98, v99
	v_mul_f32_e32 v96, v84, v85
	v_mul_f32_e32 v92, v92, v93
	v_cvt_pk_bf16_f32 v84, v101, v88
	v_cvt_pk_bf16_f32 v85, v89, v90
	v_cvt_pk_bf16_f32 v86, v91, v96
	v_cvt_pk_bf16_f32 v87, v92, v87
	global_store_dwordx4 v[94:95], v[84:87], off
	global_load_dwordx4 v[84:87], v[102:103], off
	global_load_dwordx4 v[88:91], v[102:103], off offset:16
	global_load_dwordx4 v[92:95], v[102:103], off offset:32
	global_load_dwordx4 v[96:99], v[102:103], off offset:48
	v_mov_b32_e32 v103, v76
	v_mov_b32_e32 v76, v81
	v_mov_b32_e32 v102, v80
	v_mov_b32_e32 v80, v82
	v_mov_b32_e32 v82, v68
	v_mov_b32_e32 v68, v70
	s_waitcnt vmcnt(3)
	v_mov_b32_e32 v104, v85
	v_mov_b32_e32 v105, v86
	v_mov_b32_e32 v85, v87
	s_waitcnt vmcnt(2)
	v_mov_b32_e32 v86, v89
	v_mov_b32_e32 v87, v90
	v_mov_b32_e32 v89, v91
	v_pk_add_f32 v[84:85], v[104:105], v[84:85]
	v_pk_add_f32 v[86:87], v[86:87], v[88:89]
	v_add_f32_e32 v81, v84, v85
	v_pk_add_f32 v[84:85], v[86:87], v[86:87] op_sel:[0,1] op_sel_hi:[1,0]
	s_waitcnt vmcnt(1)
	v_add_f32_e32 v90, v92, v93
	v_add_f32_e32 v92, v94, v95
	s_waitcnt vmcnt(0)
	v_mov_b32_e32 v95, v96
	v_mov_b32_e32 v91, v98
	v_mov_b32_e32 v93, v99
	v_add_f32_e32 v94, 0, v81
	v_mov_b32_e32 v85, v97
	v_pk_add_f32 v[88:89], v[90:91], v[92:93]
	v_pk_add_f32 v[84:85], v[94:95], v[84:85]
	v_mov_b32_e32 v81, v78
	v_pk_add_f32 v[84:85], v[84:85], v[88:89]
	v_mov_b32_e32 v78, v83
	v_add_f32_e32 v84, v84, v85
	ds_bpermute_b32 v85, v1, v84
	v_mov_b32_e32 v83, v72
	v_mov_b32_e32 v72, v69
	v_mov_b32_e32 v69, v74
	v_mov_b32_e32 v74, v71
	s_waitcnt lgkmcnt(0)
	v_add_f32_e32 v84, v84, v85
	ds_bpermute_b32 v85, v128, v84
	s_waitcnt lgkmcnt(0)
	v_add_f32_e32 v70, v84, v85
	v_fmamk_f32 v70, v70, 0x3a000000, v226
	v_mul_f32_e32 v71, 0x4b800000, v70
	v_cmp_gt_f32_e32 vcc, s67, v70
	s_nop 1
	v_cndmask_b32_e32 v70, v70, v71, vcc
	v_rsq_f32_e32 v86, v70
	v_mad_i64_i32 v[70:71], s[36:37], v100, s68, v[116:117]
	v_lshl_add_u64 v[84:85], v[70:71], 0, v[2:3]
	v_mul_f32_e32 v70, 0x45800000, v86
	v_cndmask_b32_e32 v70, v86, v70, vcc
	v_pk_mul_f32 v[86:87], v[102:103], v[70:71] op_sel_hi:[1,0]
	v_pk_mul_f32 v[76:77], v[76:77], v[70:71] op_sel_hi:[1,0]
	v_pk_mul_f32 v[80:81], v[80:81], v[70:71] op_sel_hi:[1,0]
	v_pk_mul_f32 v[78:79], v[78:79], v[70:71] op_sel_hi:[1,0]
	v_pk_mul_f32 v[82:83], v[82:83], v[70:71] op_sel_hi:[1,0]
	v_pk_mul_f32 v[72:73], v[72:73], v[70:71] op_sel_hi:[1,0]
	v_pk_mul_f32 v[68:69], v[68:69], v[70:71] op_sel_hi:[1,0]
	v_pk_mul_f32 v[70:71], v[74:75], v[70:71] op_sel_hi:[1,0]
	v_mul_f32_e32 v74, 0xbfb8aa3b, v87
	v_mul_f32_e32 v93, 0xbfb8aa3b, v71
	v_mul_f32_e32 v75, 0xbfb8aa3b, v77
	v_mul_f32_e32 v88, 0xbfb8aa3b, v81
	v_mul_f32_e32 v89, 0xbfb8aa3b, v79
	v_mul_f32_e32 v90, 0xbfb8aa3b, v83
	v_mul_f32_e32 v91, 0xbfb8aa3b, v73
	v_mul_f32_e32 v92, 0xbfb8aa3b, v69
	v_exp_f32_e32 v93, v93
	v_exp_f32_e32 v74, v74
	v_exp_f32_e32 v75, v75
	v_exp_f32_e32 v88, v88
	v_exp_f32_e32 v89, v89
	v_exp_f32_e32 v90, v90
	v_exp_f32_e32 v91, v91
	v_exp_f32_e32 v92, v92
	v_add_f32_e32 v93, 1.0, v93
	v_add_f32_e32 v74, 1.0, v74
	v_add_f32_e32 v75, 1.0, v75
	v_add_f32_e32 v88, 1.0, v88
	v_add_f32_e32 v89, 1.0, v89
	v_add_f32_e32 v90, 1.0, v90
	v_add_f32_e32 v91, 1.0, v91
	v_add_f32_e32 v92, 1.0, v92
	v_rcp_f32_e32 v93, v93
	v_rcp_f32_e32 v74, v74
	v_rcp_f32_e32 v75, v75
	v_rcp_f32_e32 v88, v88
	v_rcp_f32_e32 v89, v89
	v_rcp_f32_e32 v90, v90
	v_rcp_f32_e32 v91, v91
	v_rcp_f32_e32 v92, v92
	v_mul_f32_e32 v71, v71, v93
	v_mul_f32_e32 v74, v87, v74
	v_mul_f32_e32 v75, v77, v75
	v_mul_f32_e32 v77, v81, v88
	v_mul_f32_e32 v79, v79, v89
	v_mul_f32_e32 v81, v83, v90
	v_mul_f32_e32 v73, v73, v91
	v_mul_f32_e32 v69, v69, v92
	v_mul_f32_e32 v71, v70, v71
	v_mul_f32_e32 v74, v86, v74
	v_mul_f32_e32 v75, v76, v75
	v_mul_f32_e32 v76, v80, v77
	v_mul_f32_e32 v77, v78, v79
	v_mul_f32_e32 v78, v82, v81
	v_mul_f32_e32 v72, v72, v73
	v_mul_f32_e32 v73, v68, v69
	v_cvt_pk_bf16_f32 v68, v74, v75
	v_cvt_pk_bf16_f32 v69, v76, v77
	v_cvt_pk_bf16_f32 v70, v78, v72
	v_cvt_pk_bf16_f32 v71, v73, v71
	global_store_dwordx4 v[84:85], v[68:71], off
	s_and_b64 vcc, exec, s[8:9]
	s_cbranch_vccz .LBB0_1057
	s_andn2_b64 vcc, exec, s[24:25]
	s_mov_b64 s[8:9], -1
	s_cbranch_vccnz .LBB0_1036
	s_branch .LBB0_1058
.LBB0_1057:
	v_add_u32_e32 v84, 0x80, v132
	v_ashrrev_i32_e32 v85, 31, v84
	v_lshlrev_b64 v[68:69], 8, v[84:85]
	v_lshl_add_u64 v[80:81], v[204:205], 0, v[68:69]
	global_load_dwordx4 v[68:71], v[80:81], off
	global_load_dwordx4 v[72:75], v[80:81], off offset:16
	global_load_dwordx4 v[76:79], v[80:81], off offset:32
	s_nop 0
	global_load_dwordx4 v[80:83], v[80:81], off offset:48
	v_mov_b32_e32 v86, v64
	v_mov_b32_e32 v87, v56
	v_mov_b32_e32 v56, v65
	v_mov_b32_e32 v64, v66
	v_mov_b32_e32 v65, v58
	v_mov_b32_e32 v58, v67
	v_mov_b32_e32 v66, v60
	v_mov_b32_e32 v67, v52
	v_mov_b32_e32 v52, v61
	s_waitcnt vmcnt(3)
	v_mov_b32_e32 v60, v69
	v_mov_b32_e32 v61, v70
	v_mov_b32_e32 v69, v71
	s_waitcnt vmcnt(2)
	v_mov_b32_e32 v70, v73
	v_mov_b32_e32 v71, v74
	v_mov_b32_e32 v73, v75
	v_pk_add_f32 v[60:61], v[60:61], v[68:69]
	v_pk_add_f32 v[68:69], v[70:71], v[72:73]
	v_add_f32_e32 v72, v60, v61
	v_pk_add_f32 v[60:61], v[68:69], v[68:69] op_sel:[0,1] op_sel_hi:[1,0]
	s_waitcnt vmcnt(1)
	v_add_f32_e32 v74, v76, v77
	v_add_f32_e32 v76, v78, v79
	s_waitcnt vmcnt(0)
	v_mov_b32_e32 v79, v80
	v_mov_b32_e32 v75, v82
	v_mov_b32_e32 v77, v83
	v_add_f32_e32 v78, 0, v72
	v_mov_b32_e32 v61, v81
	v_pk_add_f32 v[70:71], v[74:75], v[76:77]
	v_pk_add_f32 v[60:61], v[78:79], v[60:61]
	v_mov_b32_e32 v69, v54
	v_pk_add_f32 v[60:61], v[60:61], v[70:71]
	v_mov_b32_e32 v54, v63
	v_add_f32_e32 v70, v60, v61
	ds_bpermute_b32 v71, v1, v70
	v_mov_b32_e32 v68, v62
	v_mov_b64_e32 v[60:61], s[12:13]
	v_mad_i64_i32 v[62:63], s[8:9], v84, s68, v[60:61]
	s_waitcnt lgkmcnt(0)
	v_add_f32_e32 v72, v70, v71
	ds_bpermute_b32 v73, v128, v72
	v_add_u32_e32 v70, 0x90, v132
	v_ashrrev_i32_e32 v71, 31, v70
	v_lshl_add_u64 v[62:63], v[62:63], 0, v[2:3]
	s_waitcnt lgkmcnt(0)
	v_add_f32_e32 v72, v72, v73
	v_fmamk_f32 v72, v72, 0x3a000000, v226
	v_rsq_f32_e32 v74, v72
	v_lshlrev_b64 v[72:73], 8, v[70:71]
	v_lshl_add_u64 v[72:73], v[204:205], 0, v[72:73]
	v_pk_mul_f32 v[54:55], v[54:55], v[74:75] op_sel_hi:[1,0]
	v_pk_mul_f32 v[76:77], v[86:87], v[74:75] op_sel_hi:[1,0]
	v_pk_mul_f32 v[56:57], v[56:57], v[74:75] op_sel_hi:[1,0]
	v_pk_mul_f32 v[64:65], v[64:65], v[74:75] op_sel_hi:[1,0]
	v_pk_mul_f32 v[58:59], v[58:59], v[74:75] op_sel_hi:[1,0]
	v_pk_mul_f32 v[66:67], v[66:67], v[74:75] op_sel_hi:[1,0]
	v_pk_mul_f32 v[52:53], v[52:53], v[74:75] op_sel_hi:[1,0]
	v_pk_mul_f32 v[68:69], v[68:69], v[74:75] op_sel_hi:[1,0]
	v_mul_f32_e32 v82, 0xbfb8aa3b, v55
	v_mul_f32_e32 v71, 0xbfb8aa3b, v77
	v_mul_f32_e32 v74, 0xbfb8aa3b, v57
	v_mul_f32_e32 v75, 0xbfb8aa3b, v65
	v_mul_f32_e32 v78, 0xbfb8aa3b, v59
	v_mul_f32_e32 v79, 0xbfb8aa3b, v67
	v_mul_f32_e32 v80, 0xbfb8aa3b, v53
	v_mul_f32_e32 v81, 0xbfb8aa3b, v69
	v_exp_f32_e32 v82, v82
	v_exp_f32_e32 v71, v71
	v_exp_f32_e32 v74, v74
	v_exp_f32_e32 v75, v75
	v_exp_f32_e32 v78, v78
	v_exp_f32_e32 v79, v79
	v_exp_f32_e32 v80, v80
	v_exp_f32_e32 v81, v81
	v_add_f32_e32 v82, 1.0, v82
	v_add_f32_e32 v71, 1.0, v71
	v_add_f32_e32 v74, 1.0, v74
	v_add_f32_e32 v75, 1.0, v75
	v_add_f32_e32 v78, 1.0, v78
	v_add_f32_e32 v79, 1.0, v79
	v_add_f32_e32 v80, 1.0, v80
	v_add_f32_e32 v81, 1.0, v81
	v_rcp_f32_e32 v82, v82
	v_rcp_f32_e32 v71, v71
	v_rcp_f32_e32 v74, v74
	v_rcp_f32_e32 v75, v75
	v_rcp_f32_e32 v78, v78
	v_rcp_f32_e32 v79, v79
	v_rcp_f32_e32 v80, v80
	v_rcp_f32_e32 v81, v81
	v_mul_f32_e32 v55, v55, v82
	v_mul_f32_e32 v71, v77, v71
	v_mul_f32_e32 v57, v57, v74
	v_mul_f32_e32 v65, v65, v75
	v_mul_f32_e32 v59, v59, v78
	v_mul_f32_e32 v67, v67, v79
	v_mul_f32_e32 v53, v53, v80
	v_mul_f32_e32 v69, v69, v81
	v_mul_f32_e32 v55, v54, v55
	v_mul_f32_e32 v71, v76, v71
	v_mul_f32_e32 v56, v56, v57
	v_mul_f32_e32 v57, v64, v65
	v_mul_f32_e32 v58, v58, v59
	v_mul_f32_e32 v59, v66, v67
	v_mul_f32_e32 v64, v52, v53
	v_mul_f32_e32 v65, v68, v69
	v_cvt_pk_bf16_f32 v52, v71, v56
	v_cvt_pk_bf16_f32 v53, v57, v58
	v_cvt_pk_bf16_f32 v54, v59, v64
	v_cvt_pk_bf16_f32 v55, v65, v55
	global_store_dwordx4 v[62:63], v[52:55], off
	global_load_dwordx4 v[52:55], v[72:73], off
	global_load_dwordx4 v[56:59], v[72:73], off offset:16
	global_load_dwordx4 v[62:65], v[72:73], off offset:32
	global_load_dwordx4 v[66:69], v[72:73], off offset:48
	v_mov_b32_e32 v73, v40
	v_mov_b32_e32 v40, v49
	v_mov_b32_e32 v49, v42
	v_mov_b32_e32 v42, v51
	v_mov_b32_e32 v51, v36
	v_mov_b32_e32 v72, v48
	v_mov_b32_e32 v48, v50
	v_mov_b32_e32 v50, v44
	v_mov_b32_e32 v44, v46
	s_waitcnt vmcnt(3)
	v_mov_b32_e32 v74, v53
	v_mov_b32_e32 v75, v54
	v_mov_b32_e32 v53, v55
	s_waitcnt vmcnt(2)
	v_mov_b32_e32 v54, v57
	v_mov_b32_e32 v55, v58
	v_mov_b32_e32 v57, v59
	v_pk_add_f32 v[52:53], v[74:75], v[52:53]
	v_pk_add_f32 v[54:55], v[54:55], v[56:57]
	v_add_f32_e32 v36, v52, v53
	v_pk_add_f32 v[52:53], v[54:55], v[54:55] op_sel:[0,1] op_sel_hi:[1,0]
	s_waitcnt vmcnt(1)
	v_add_f32_e32 v58, v62, v63
	v_add_f32_e32 v62, v64, v65
	s_waitcnt vmcnt(0)
	v_mov_b32_e32 v65, v66
	v_mov_b32_e32 v59, v68
	v_mov_b32_e32 v63, v69
	v_add_f32_e32 v64, 0, v36
	v_mov_b32_e32 v53, v67
	v_pk_add_f32 v[56:57], v[58:59], v[62:63]
	v_pk_add_f32 v[52:53], v[64:65], v[52:53]
	v_mov_b32_e32 v36, v45
	v_pk_add_f32 v[52:53], v[52:53], v[56:57]
	v_mov_b32_e32 v45, v38
	v_add_f32_e32 v52, v52, v53
	ds_bpermute_b32 v53, v1, v52
	v_mov_b32_e32 v38, v47
	v_mad_i64_i32 v[46:47], s[8:9], v70, s68, v[60:61]
	v_lshl_add_u64 v[46:47], v[46:47], 0, v[2:3]
	s_waitcnt lgkmcnt(0)
	v_add_f32_e32 v54, v52, v53
	ds_bpermute_b32 v55, v128, v54
	v_add_u32_e32 v52, 0xa0, v132
	v_ashrrev_i32_e32 v53, 31, v52
	s_waitcnt lgkmcnt(0)
	v_add_f32_e32 v54, v54, v55
	v_fmamk_f32 v54, v54, 0x3a000000, v226
	v_rsq_f32_e32 v56, v54
	v_lshlrev_b64 v[54:55], 8, v[52:53]
	v_lshl_add_u64 v[54:55], v[204:205], 0, v[54:55]
	v_pk_mul_f32 v[38:39], v[38:39], v[56:57] op_sel_hi:[1,0]
	v_pk_mul_f32 v[58:59], v[72:73], v[56:57] op_sel_hi:[1,0]
	v_pk_mul_f32 v[40:41], v[40:41], v[56:57] op_sel_hi:[1,0]
	v_pk_mul_f32 v[48:49], v[48:49], v[56:57] op_sel_hi:[1,0]
	v_pk_mul_f32 v[42:43], v[42:43], v[56:57] op_sel_hi:[1,0]
	v_pk_mul_f32 v[50:51], v[50:51], v[56:57] op_sel_hi:[1,0]
	v_pk_mul_f32 v[36:37], v[36:37], v[56:57] op_sel_hi:[1,0]
	v_pk_mul_f32 v[44:45], v[44:45], v[56:57] op_sel_hi:[1,0]
	v_mul_f32_e32 v66, 0xbfb8aa3b, v39
	v_mul_f32_e32 v53, 0xbfb8aa3b, v59
	v_mul_f32_e32 v56, 0xbfb8aa3b, v41
	v_mul_f32_e32 v57, 0xbfb8aa3b, v49
	v_mul_f32_e32 v62, 0xbfb8aa3b, v43
	v_mul_f32_e32 v63, 0xbfb8aa3b, v51
	v_mul_f32_e32 v64, 0xbfb8aa3b, v37
	v_mul_f32_e32 v65, 0xbfb8aa3b, v45
	v_exp_f32_e32 v66, v66
	v_exp_f32_e32 v53, v53
	v_exp_f32_e32 v56, v56
	v_exp_f32_e32 v57, v57
	v_exp_f32_e32 v62, v62
	v_exp_f32_e32 v63, v63
	v_exp_f32_e32 v64, v64
	v_exp_f32_e32 v65, v65
	v_add_f32_e32 v66, 1.0, v66
	v_add_f32_e32 v53, 1.0, v53
	v_add_f32_e32 v56, 1.0, v56
	v_add_f32_e32 v57, 1.0, v57
	v_add_f32_e32 v62, 1.0, v62
	v_add_f32_e32 v63, 1.0, v63
	v_add_f32_e32 v64, 1.0, v64
	v_add_f32_e32 v65, 1.0, v65
	v_rcp_f32_e32 v66, v66
	v_rcp_f32_e32 v53, v53
	v_rcp_f32_e32 v56, v56
	v_rcp_f32_e32 v57, v57
	v_rcp_f32_e32 v62, v62
	v_rcp_f32_e32 v63, v63
	v_rcp_f32_e32 v64, v64
	v_rcp_f32_e32 v65, v65
	v_mul_f32_e32 v39, v39, v66
	v_mul_f32_e32 v53, v59, v53
	v_mul_f32_e32 v41, v41, v56
	v_mul_f32_e32 v49, v49, v57
	v_mul_f32_e32 v43, v43, v62
	v_mul_f32_e32 v51, v51, v63
	v_mul_f32_e32 v37, v37, v64
	v_mul_f32_e32 v45, v45, v65
	v_mul_f32_e32 v39, v38, v39
	v_mul_f32_e32 v53, v58, v53
	v_mul_f32_e32 v40, v40, v41
	v_mul_f32_e32 v41, v48, v49
	v_mul_f32_e32 v42, v42, v43
	v_mul_f32_e32 v43, v50, v51
	v_mul_f32_e32 v48, v36, v37
	v_mul_f32_e32 v44, v44, v45
	v_cvt_pk_bf16_f32 v36, v53, v40
	v_cvt_pk_bf16_f32 v37, v41, v42
	v_cvt_pk_bf16_f32 v38, v43, v48
	v_cvt_pk_bf16_f32 v39, v44, v39
	global_store_dwordx4 v[46:47], v[36:39], off
	global_load_dwordx4 v[36:39], v[54:55], off
	global_load_dwordx4 v[40:43], v[54:55], off offset:16
	global_load_dwordx4 v[44:47], v[54:55], off offset:32
	global_load_dwordx4 v[48:51], v[54:55], off offset:48
	v_mov_b32_e32 v55, v24
	v_mov_b32_e32 v24, v33
	v_mov_b32_e32 v33, v26
	v_mov_b32_e32 v26, v35
	v_mov_b32_e32 v35, v20
	v_mov_b32_e32 v54, v32
	v_mov_b32_e32 v32, v34
	v_mov_b32_e32 v34, v28
	v_mov_b32_e32 v28, v30
	s_waitcnt vmcnt(3)
	v_mov_b32_e32 v56, v37
	v_mov_b32_e32 v57, v38
	v_mov_b32_e32 v37, v39
	s_waitcnt vmcnt(2)
	v_mov_b32_e32 v38, v41
	v_mov_b32_e32 v39, v42
	v_mov_b32_e32 v41, v43
	v_pk_add_f32 v[36:37], v[56:57], v[36:37]
	v_pk_add_f32 v[38:39], v[38:39], v[40:41]
	v_add_f32_e32 v20, v36, v37
	v_pk_add_f32 v[36:37], v[38:39], v[38:39] op_sel:[0,1] op_sel_hi:[1,0]
	s_waitcnt vmcnt(1)
	v_add_f32_e32 v42, v44, v45
	v_add_f32_e32 v44, v46, v47
	s_waitcnt vmcnt(0)
	v_mov_b32_e32 v47, v48
	v_mov_b32_e32 v43, v50
	v_mov_b32_e32 v45, v51
	v_add_f32_e32 v46, 0, v20
	v_mov_b32_e32 v37, v49
	v_pk_add_f32 v[40:41], v[42:43], v[44:45]
	v_pk_add_f32 v[36:37], v[46:47], v[36:37]
	v_mov_b32_e32 v20, v29
	v_pk_add_f32 v[36:37], v[36:37], v[40:41]
	v_mov_b32_e32 v29, v22
	v_add_f32_e32 v36, v36, v37
	ds_bpermute_b32 v37, v1, v36
	v_mov_b32_e32 v22, v31
	v_mad_i64_i32 v[30:31], s[8:9], v52, s68, v[60:61]
	v_lshl_add_u64 v[30:31], v[30:31], 0, v[2:3]
	s_waitcnt lgkmcnt(0)
	v_add_f32_e32 v38, v36, v37
	ds_bpermute_b32 v39, v128, v38
	v_add_u32_e32 v36, 0xb0, v132
	v_ashrrev_i32_e32 v37, 31, v36
	s_waitcnt lgkmcnt(0)
	v_add_f32_e32 v38, v38, v39
	v_fmamk_f32 v38, v38, 0x3a000000, v226
	v_rsq_f32_e32 v40, v38
	v_lshlrev_b64 v[38:39], 8, v[36:37]
	v_lshl_add_u64 v[38:39], v[204:205], 0, v[38:39]
	v_pk_mul_f32 v[22:23], v[22:23], v[40:41] op_sel_hi:[1,0]
	v_pk_mul_f32 v[42:43], v[54:55], v[40:41] op_sel_hi:[1,0]
	v_pk_mul_f32 v[24:25], v[24:25], v[40:41] op_sel_hi:[1,0]
	v_pk_mul_f32 v[32:33], v[32:33], v[40:41] op_sel_hi:[1,0]
	v_pk_mul_f32 v[26:27], v[26:27], v[40:41] op_sel_hi:[1,0]
	v_pk_mul_f32 v[34:35], v[34:35], v[40:41] op_sel_hi:[1,0]
	v_pk_mul_f32 v[20:21], v[20:21], v[40:41] op_sel_hi:[1,0]
	v_pk_mul_f32 v[28:29], v[28:29], v[40:41] op_sel_hi:[1,0]
	v_mul_f32_e32 v48, 0xbfb8aa3b, v23
	v_mul_f32_e32 v37, 0xbfb8aa3b, v43
	v_mul_f32_e32 v40, 0xbfb8aa3b, v25
	v_mul_f32_e32 v41, 0xbfb8aa3b, v33
	v_mul_f32_e32 v44, 0xbfb8aa3b, v27
	v_mul_f32_e32 v45, 0xbfb8aa3b, v35
	v_mul_f32_e32 v46, 0xbfb8aa3b, v21
	v_mul_f32_e32 v47, 0xbfb8aa3b, v29
	v_exp_f32_e32 v48, v48
	v_exp_f32_e32 v37, v37
	v_exp_f32_e32 v40, v40
	v_exp_f32_e32 v41, v41
	v_exp_f32_e32 v44, v44
	v_exp_f32_e32 v45, v45
	v_exp_f32_e32 v46, v46
	v_exp_f32_e32 v47, v47
	v_add_f32_e32 v48, 1.0, v48
	v_add_f32_e32 v37, 1.0, v37
	v_add_f32_e32 v40, 1.0, v40
	v_add_f32_e32 v41, 1.0, v41
	v_add_f32_e32 v44, 1.0, v44
	v_add_f32_e32 v45, 1.0, v45
	v_add_f32_e32 v46, 1.0, v46
	v_add_f32_e32 v47, 1.0, v47
	v_rcp_f32_e32 v48, v48
	v_rcp_f32_e32 v37, v37
	v_rcp_f32_e32 v40, v40
	v_rcp_f32_e32 v41, v41
	v_rcp_f32_e32 v44, v44
	v_rcp_f32_e32 v45, v45
	v_rcp_f32_e32 v46, v46
	v_rcp_f32_e32 v47, v47
	v_mul_f32_e32 v23, v23, v48
	v_mul_f32_e32 v37, v43, v37
	v_mul_f32_e32 v25, v25, v40
	v_mul_f32_e32 v33, v33, v41
	v_mul_f32_e32 v27, v27, v44
	v_mul_f32_e32 v35, v35, v45
	v_mul_f32_e32 v21, v21, v46
	v_mul_f32_e32 v29, v29, v47
	v_mul_f32_e32 v23, v22, v23
	v_mul_f32_e32 v37, v42, v37
	v_mul_f32_e32 v24, v24, v25
	v_mul_f32_e32 v25, v32, v33
	v_mul_f32_e32 v26, v26, v27
	v_mul_f32_e32 v27, v34, v35
	v_mul_f32_e32 v32, v20, v21
	v_mul_f32_e32 v28, v28, v29
	v_cvt_pk_bf16_f32 v20, v37, v24
	v_cvt_pk_bf16_f32 v21, v25, v26
	v_cvt_pk_bf16_f32 v22, v27, v32
	v_cvt_pk_bf16_f32 v23, v28, v23
	global_store_dwordx4 v[30:31], v[20:23], off
	global_load_dwordx4 v[20:23], v[38:39], off
	global_load_dwordx4 v[24:27], v[38:39], off offset:16
	global_load_dwordx4 v[28:31], v[38:39], off offset:32
	global_load_dwordx4 v[32:35], v[38:39], off offset:48
	v_mov_b32_e32 v38, v16
	v_mov_b32_e32 v39, v8
	v_mov_b32_e32 v8, v17
	s_waitcnt vmcnt(3)
	v_mov_b32_e32 v16, v21
	v_mov_b32_e32 v17, v22
	v_mov_b32_e32 v21, v23
	s_waitcnt vmcnt(2)
	v_mov_b32_e32 v22, v25
	v_mov_b32_e32 v23, v26
	v_mov_b32_e32 v25, v27
	v_pk_add_f32 v[16:17], v[16:17], v[20:21]
	v_pk_add_f32 v[20:21], v[22:23], v[24:25]
	v_add_f32_e32 v24, v16, v17
	v_pk_add_f32 v[16:17], v[20:21], v[20:21] op_sel:[0,1] op_sel_hi:[1,0]
	s_waitcnt vmcnt(1)
	v_add_f32_e32 v26, v28, v29
	v_add_f32_e32 v28, v30, v31
	s_waitcnt vmcnt(0)
	v_mov_b32_e32 v31, v32
	v_mov_b32_e32 v27, v34
	v_mov_b32_e32 v29, v35
	v_add_f32_e32 v30, 0, v24
	v_mov_b32_e32 v17, v33
	v_pk_add_f32 v[22:23], v[26:27], v[28:29]
	v_pk_add_f32 v[16:17], v[30:31], v[16:17]
	s_nop 0
	v_pk_add_f32 v[16:17], v[16:17], v[22:23]
	s_nop 0
	v_add_f32_e32 v20, v16, v17
	ds_bpermute_b32 v1, v1, v20
	v_mov_b32_e32 v17, v10
	v_mov_b32_e32 v10, v19
	v_mov_b32_e32 v19, v4
	v_mov_b32_e32 v4, v13
	s_waitcnt lgkmcnt(0)
	v_add_f32_e32 v1, v20, v1
	ds_bpermute_b32 v20, v128, v1
	v_mov_b32_e32 v13, v6
	v_mov_b32_e32 v16, v18
	v_mov_b32_e32 v18, v12
	v_mov_b32_e32 v12, v14
	s_waitcnt lgkmcnt(0)
	v_add_f32_e32 v1, v1, v20
	v_fmamk_f32 v1, v1, 0x3a000000, v226
	v_rsq_f32_e32 v20, v1
	v_mov_b32_e32 v6, v15
	v_mad_i64_i32 v[14:15], s[8:9], v36, s68, v[60:61]
	v_pk_mul_f32 v[6:7], v[6:7], v[20:21] op_sel_hi:[1,0]
	v_pk_mul_f32 v[22:23], v[38:39], v[20:21] op_sel_hi:[1,0]
	v_pk_mul_f32 v[8:9], v[8:9], v[20:21] op_sel_hi:[1,0]
	v_pk_mul_f32 v[16:17], v[16:17], v[20:21] op_sel_hi:[1,0]
	v_pk_mul_f32 v[10:11], v[10:11], v[20:21] op_sel_hi:[1,0]
	v_pk_mul_f32 v[18:19], v[18:19], v[20:21] op_sel_hi:[1,0]
	v_pk_mul_f32 v[4:5], v[4:5], v[20:21] op_sel_hi:[1,0]
	v_pk_mul_f32 v[12:13], v[12:13], v[20:21] op_sel_hi:[1,0]
	v_mul_f32_e32 v28, 0xbfb8aa3b, v7
	v_mul_f32_e32 v1, 0xbfb8aa3b, v23
	v_mul_f32_e32 v20, 0xbfb8aa3b, v9
	v_mul_f32_e32 v21, 0xbfb8aa3b, v17
	v_mul_f32_e32 v24, 0xbfb8aa3b, v11
	v_mul_f32_e32 v25, 0xbfb8aa3b, v19
	v_mul_f32_e32 v26, 0xbfb8aa3b, v5
	v_mul_f32_e32 v27, 0xbfb8aa3b, v13
	v_exp_f32_e32 v28, v28
	v_exp_f32_e32 v1, v1
	v_exp_f32_e32 v20, v20
	v_exp_f32_e32 v21, v21
	v_exp_f32_e32 v24, v24
	v_exp_f32_e32 v25, v25
	v_exp_f32_e32 v26, v26
	v_exp_f32_e32 v27, v27
	v_add_f32_e32 v28, 1.0, v28
	v_add_f32_e32 v1, 1.0, v1
	v_add_f32_e32 v20, 1.0, v20
	v_add_f32_e32 v21, 1.0, v21
	v_add_f32_e32 v24, 1.0, v24
	v_add_f32_e32 v25, 1.0, v25
	v_add_f32_e32 v26, 1.0, v26
	v_add_f32_e32 v27, 1.0, v27
	v_rcp_f32_e32 v28, v28
	v_rcp_f32_e32 v1, v1
	v_rcp_f32_e32 v20, v20
	v_rcp_f32_e32 v21, v21
	v_rcp_f32_e32 v24, v24
	v_rcp_f32_e32 v25, v25
	v_rcp_f32_e32 v26, v26
	v_rcp_f32_e32 v27, v27
	v_mul_f32_e32 v7, v7, v28
	v_mul_f32_e32 v1, v23, v1
	v_mul_f32_e32 v9, v9, v20
	v_mul_f32_e32 v17, v17, v21
	v_mul_f32_e32 v11, v11, v24
	v_mul_f32_e32 v19, v19, v25
	v_mul_f32_e32 v5, v5, v26
	v_mul_f32_e32 v13, v13, v27
	v_mul_f32_e32 v7, v6, v7
	v_lshl_add_u64 v[2:3], v[14:15], 0, v[2:3]
	v_mul_f32_e32 v1, v22, v1
	v_mul_f32_e32 v8, v8, v9
	v_mul_f32_e32 v9, v16, v17
	v_mul_f32_e32 v10, v10, v11
	v_mul_f32_e32 v11, v18, v19
	v_mul_f32_e32 v16, v4, v5
	v_mul_f32_e32 v12, v12, v13
	v_cvt_pk_bf16_f32 v4, v1, v8
	v_cvt_pk_bf16_f32 v5, v9, v10
	v_cvt_pk_bf16_f32 v6, v11, v16
	v_cvt_pk_bf16_f32 v7, v12, v7
	global_store_dwordx4 v[2:3], v[4:7], off
	s_andn2_b64 vcc, exec, s[24:25]
	s_mov_b64 s[8:9], -1
	s_cbranch_vccnz .LBB0_1036

.LBB0_1234:
	s_add_u32 s4, s8, 0x200000
	s_addc_u32 s5, s9, 0
	s_add_u32 s2, s8, 0x19000000
	s_addc_u32 s3, s9, 0
	s_lshl_b32 s1, s14, 8
	s_add_i32 s1, s1, s52
	v_or_b32_e32 v150, s1, v149
	v_ashrrev_i32_e32 v151, 31, v150
	v_lshlrev_b64 v[134:135], 7, v[150:151]
	v_mov_b32_e32 v131, 0
	v_lshl_add_u64 v[128:129], s[4:5], 0, v[134:135]
	v_lshlrev_b32_e32 v130, 5, v148
	v_lshl_add_u64 v[128:129], v[128:129], 0, v[130:131]
	s_barrier
	global_load_dwordx4 v[136:139], v[128:129], off
	global_load_dwordx4 v[142:145], v[128:129], off offset:16
	s_lshl_b32 s0, s44, 5
	s_lshl_b32 s1, s15, 8
	s_or_b32 s0, s1, s0
	v_lshl_or_b32 v128, v148, 3, s0
	v_ashrrev_i32_e32 v129, 31, v128
	v_lshlrev_b64 v[132:133], 11, v[150:151]
	v_lshl_add_u64 v[132:133], v[132:133], 0, v[128:129]
	v_lshlrev_b64 v[146:147], 1, v[132:133]
	v_lshl_add_u64 v[140:141], s[12:13], 0, v[146:147]
	global_load_dwordx4 v[152:155], v[140:141], off
	v_lshl_add_u64 v[140:141], s[2:3], 0, v[146:147]
	global_load_dwordx4 v[156:159], v[140:141], off
	v_or_b32_e32 v146, 0x100, v146
	v_lshl_add_u64 v[160:161], s[12:13], 0, v[146:147]
	v_lshl_add_u64 v[146:147], s[2:3], 0, v[146:147]
	global_load_dwordx4 v[160:163], v[160:161], off
	s_nop 0
	global_load_dwordx4 v[164:167], v[146:147], off
	v_mbcnt_hi_u32_b32 v130, -1, v254
	v_and_b32_e32 v149, 64, v130
	v_xor_b32_e32 v141, 16, v130
	v_add_u32_e32 v149, 64, v149
	v_xor_b32_e32 v151, 32, v130
	v_cmp_lt_i32_e32 vcc, v141, v149
	v_mov_b32_e32 v140, 0x358637bd
	s_mov_b32 s18, 0x800000
	v_cndmask_b32_e32 v141, v130, v141, vcc
	v_cmp_lt_i32_e32 vcc, v151, v149
	v_lshlrev_b32_e32 v195, 2, v141
	s_lshl_b32 s14, s15, 2
	v_cndmask_b32_e32 v130, v130, v151, vcc
	v_lshlrev_b32_e32 v194, 2, v130
	s_mov_b32 s1, 0
	s_ashr_i32 s15, s14, 31
	s_waitcnt vmcnt(0)
	v_mov_b32_e32 v146, v136
	v_mov_b32_e32 v147, v142
	v_mov_b32_e32 v142, v137
	v_mov_b32_e32 v136, v138
	v_mov_b32_e32 v137, v144
	v_mov_b32_e32 v144, v139
	v_pk_add_f32 v[138:139], v[146:147], v[142:143]
	v_pk_add_f32 v[136:137], v[136:137], v[144:145]
	v_lshlrev_b32_e32 v142, 16, v152
	v_pk_add_f32 v[136:137], v[138:139], v[136:137]
	v_and_b32_e32 v143, 0xffff0000, v152
	v_add_f32_e32 v130, 0, v136
	v_add_f32_e32 v130, v130, v137
	ds_bpermute_b32 v139, v195, v130
	v_lshlrev_b32_e32 v146, 16, v153
	v_and_b32_e32 v147, 0xffff0000, v153
	v_lshlrev_b32_e32 v152, 16, v158
	v_and_b32_e32 v153, 0xffff0000, v158
	s_waitcnt lgkmcnt(0)
	v_add_f32_e32 v130, v130, v139
	ds_bpermute_b32 v141, v194, v130
	v_lshlrev_b32_e32 v136, 16, v157
	v_and_b32_e32 v137, 0xffff0000, v157
	v_lshlrev_b32_e32 v138, 16, v154
	v_and_b32_e32 v139, 0xffff0000, v154
	s_waitcnt lgkmcnt(0)
	v_add_f32_e32 v130, v130, v141
	v_fmamk_f32 v130, v130, 0x3a000000, v140
	v_lshlrev_b32_e32 v144, 16, v156
	v_and_b32_e32 v145, 0xffff0000, v156
	v_rsq_f32_e32 v130, v130
	v_lshlrev_b32_e32 v154, 16, v155
	v_and_b32_e32 v155, 0xffff0000, v155
	v_lshlrev_b32_e32 v156, 16, v159
	v_mul_f32_e32 v124, v124, v130
	v_mul_f32_e32 v125, v125, v130
	v_mul_f32_e32 v126, v126, v130
	v_mul_f32_e32 v127, v127, v130
	v_mul_f32_e32 v120, v120, v130
	v_mul_f32_e32 v121, v121, v130
	v_mul_f32_e32 v122, v122, v130
	v_mul_f32_e32 v123, v123, v130
	v_mul_f32_e32 v124, 0xbfb8aa3b, v124
	v_mul_f32_e32 v125, 0xbfb8aa3b, v125
	v_mul_f32_e32 v126, 0xbfb8aa3b, v126
	v_mul_f32_e32 v127, 0xbfb8aa3b, v127
	v_mul_f32_e32 v120, 0xbfb8aa3b, v120
	v_mul_f32_e32 v121, 0xbfb8aa3b, v121
	v_mul_f32_e32 v116, v116, v130
	v_mul_f32_e32 v117, v117, v130
	v_mul_f32_e32 v122, 0xbfb8aa3b, v122
	v_mul_f32_e32 v123, 0xbfb8aa3b, v123
	v_exp_f32_e32 v124, v124
	v_exp_f32_e32 v125, v125
	v_exp_f32_e32 v126, v126
	v_exp_f32_e32 v127, v127
	v_exp_f32_e32 v120, v120
	v_exp_f32_e32 v121, v121
	v_mul_f32_e32 v116, 0xbfb8aa3b, v116
	v_mul_f32_e32 v117, 0xbfb8aa3b, v117
	v_mul_f32_e32 v118, v118, v130
	v_mul_f32_e32 v119, v119, v130
	v_exp_f32_e32 v122, v122
	v_exp_f32_e32 v123, v123
	v_exp_f32_e32 v116, v116
	v_exp_f32_e32 v117, v117
	v_mul_f32_e32 v118, 0xbfb8aa3b, v118
	v_mul_f32_e32 v119, 0xbfb8aa3b, v119
	v_exp_f32_e32 v118, v118
	v_exp_f32_e32 v119, v119
	v_add_f32_e32 v124, 1.0, v124
	v_add_f32_e32 v125, 1.0, v125
	v_add_f32_e32 v126, 1.0, v126
	v_add_f32_e32 v127, 1.0, v127
	v_add_f32_e32 v141, 1.0, v120
	v_add_f32_e32 v149, 1.0, v121
	v_mul_f32_e32 v112, v112, v130
	v_add_f32_e32 v151, 1.0, v122
	v_add_f32_e32 v158, 1.0, v123
	v_rcp_f32_e32 v120, v124
	v_rcp_f32_e32 v121, v125
	v_rcp_f32_e32 v122, v126
	v_rcp_f32_e32 v123, v127
	v_rcp_f32_e32 v124, v141
	v_rcp_f32_e32 v125, v149
	v_add_f32_e32 v116, 1.0, v116
	v_add_f32_e32 v117, 1.0, v117
	v_mul_f32_e32 v112, 0xbfb8aa3b, v112
	v_rcp_f32_e32 v116, v116
	v_rcp_f32_e32 v117, v117
	v_add_f32_e32 v118, 1.0, v118
	v_add_f32_e32 v119, 1.0, v119
	v_exp_f32_e32 v141, v112
	v_mul_f32_e32 v112, v113, v130
	v_rcp_f32_e32 v118, v118
	v_rcp_f32_e32 v119, v119
	v_mul_f32_e32 v112, 0xbfb8aa3b, v112
	v_exp_f32_e32 v149, v112
	v_pk_fma_f32 v[122:123], v[122:123], v[136:137], v[146:147]
	v_pk_fma_f32 v[124:125], v[124:125], v[152:153], v[138:139]
	v_lshlrev_b32_e32 v146, 16, v160
	v_and_b32_e32 v147, 0xffff0000, v160
	v_lshlrev_b32_e32 v152, 16, v164
	v_and_b32_e32 v153, 0xffff0000, v164
	v_mul_f32_e32 v114, v114, v130
	v_pk_fma_f32 v[116:117], v[116:117], v[152:153], v[146:147]
	v_lshlrev_b32_e32 v146, 16, v161
	v_and_b32_e32 v147, 0xffff0000, v161
	v_lshlrev_b32_e32 v152, 16, v165
	v_and_b32_e32 v153, 0xffff0000, v165
	v_mul_f32_e32 v114, 0xbfb8aa3b, v114
	v_pk_fma_f32 v[112:113], v[118:119], v[152:153], v[146:147]
	v_add_f32_e32 v118, 1.0, v141
	v_exp_f32_e32 v141, v114
	v_mul_f32_e32 v114, v115, v130
	v_add_f32_e32 v119, 1.0, v149
	v_mul_f32_e32 v114, 0xbfb8aa3b, v114
	v_rcp_f32_e32 v118, v118
	v_rcp_f32_e32 v119, v119
	v_exp_f32_e32 v130, v114
	v_lshlrev_b32_e32 v146, 16, v162
	v_and_b32_e32 v147, 0xffff0000, v162
	v_lshlrev_b32_e32 v152, 16, v166
	v_and_b32_e32 v153, 0xffff0000, v166
	v_pk_fma_f32 v[114:115], v[118:119], v[152:153], v[146:147]
	v_add_f32_e32 v118, 1.0, v141
	v_add_f32_e32 v119, 1.0, v130
	v_rcp_f32_e32 v118, v118
	v_rcp_f32_e32 v119, v119
	v_rcp_f32_e32 v126, v151
	v_rcp_f32_e32 v127, v158
	v_lshlrev_b32_e32 v146, 16, v163
	v_and_b32_e32 v147, 0xffff0000, v163
	v_lshlrev_b32_e32 v152, 16, v167
	v_and_b32_e32 v153, 0xffff0000, v167
	v_and_b32_e32 v157, 0xffff0000, v159
	v_pk_fma_f32 v[118:119], v[118:119], v[152:153], v[146:147]
	v_pk_fma_f32 v[126:127], v[126:127], v[156:157], v[154:155]
	v_pk_mul_f32 v[154:155], v[114:115], v[114:115]
	v_pk_mul_f32 v[156:157], v[118:119], v[118:119]
	v_pk_mul_f32 v[146:147], v[116:117], v[116:117]
	v_pk_mul_f32 v[152:153], v[112:113], v[112:113]
	v_add_f32_e32 v130, v156, v157
	v_add_f32_e32 v141, v154, v155
	v_pk_fma_f32 v[120:121], v[120:121], v[144:145], v[142:143]
	v_add_f32_e32 v130, v141, v130
	v_add_f32_e32 v141, v152, v153
	v_add_f32_e32 v146, v146, v147
	v_pk_mul_f32 v[136:137], v[120:121], v[120:121]
	v_pk_mul_f32 v[138:139], v[122:123], v[122:123]
	v_pk_mul_f32 v[142:143], v[124:125], v[124:125]
	v_pk_mul_f32 v[144:145], v[126:127], v[126:127]
	v_add_f32_e32 v141, v146, v141
	v_add_f32_e32 v130, v141, v130
	v_add_f32_e32 v141, v144, v145
	v_add_f32_e32 v142, v142, v143
	v_add_f32_e32 v138, v138, v139
	v_add_f32_e32 v136, v136, v137
	v_add_f32_e32 v141, v142, v141
	v_add_f32_e32 v136, v136, v138
	v_add_f32_e32 v136, v136, v141
	v_add_f32_e32 v136, v136, v130
	ds_bpermute_b32 v137, v195, v136
	v_lshlrev_b32_e32 v130, 1, v148
	v_cmp_eq_u32_e32 vcc, 0, v148
	s_waitcnt lgkmcnt(0)
	v_add_f32_e32 v136, v136, v137
	ds_bpermute_b32 v137, v194, v136
	s_and_saveexec_b64 s[16:17], vcc
	s_cbranch_execz .LBB0_1236
	s_waitcnt lgkmcnt(0)
	v_add_f32_e32 v138, v136, v137
	v_lshl_add_u64 v[136:137], s[8:9], 0, v[134:135]
	v_lshl_add_u64 v[136:137], s[14:15], 2, v[136:137]
	s_lshl_b32 s0, s44, 2
	v_lshl_add_u64 v[136:137], v[136:137], 0, s[0:1]
	global_store_dword v[136:137], v138, off

.LBB0_1302:
	s_or_b64 exec, exec, s[0:1]
	v_mov_b32_e32 v131, 0
	v_lshl_add_u64 v[32:33], s[8:9], 0, v[130:131]
	v_lshl_add_u64 v[20:21], v[32:33], 0, v[134:135]
	v_lshl_add_u64 v[28:29], v[32:33], 0, v[138:139]
	s_waitcnt lgkmcnt(0)
	s_barrier
	global_load_dwordx4 v[16:19], v[20:21], off
	s_nop 0
	global_load_dwordx4 v[20:23], v[20:21], off offset:16
	s_nop 0
	global_load_dwordx4 v[24:27], v[28:29], off
	s_nop 0
	global_load_dwordx4 v[28:31], v[28:29], off offset:16
	v_lshl_add_u64 v[34:35], v[32:33], 0, v[142:143]
	v_or_b32_e32 v138, 16, v154
	v_or_b32_e32 v134, 32, v154
	v_or_b32_e32 v130, 48, v154
	v_lshl_add_u64 v[36:37], v[32:33], 0, v[146:147]
	v_lshl_add_u64 v[38:39], v[32:33], 0, v[152:153]
	global_load_dwordx4 v[152:155], v[34:35], off
	global_load_dwordx4 v[196:199], v[34:35], off offset:16
	global_load_dwordx4 v[200:203], v[36:37], off
	global_load_dwordx4 v[204:207], v[36:37], off offset:16
	global_load_dwordx4 v[208:211], v[38:39], off
	global_load_dwordx4 v[212:215], v[38:39], off offset:16
	v_ashrrev_i32_e32 v139, 31, v138
	v_ashrrev_i32_e32 v135, 31, v134
	v_ashrrev_i32_e32 v131, 31, v130
	v_lshlrev_b64 v[142:143], 7, v[138:139]
	v_lshlrev_b64 v[146:147], 7, v[134:135]
	v_lshlrev_b64 v[218:219], 7, v[130:131]
	s_mov_b32 s0, 0x358637bd
	v_lshl_add_u64 v[216:217], v[132:133], 2, s[6:7]
	s_mov_b32 s2, 0x3a000000
	s_mov_b32 s3, 0x800000
	v_mov_b64_e32 v[132:133], s[0:1]
	v_lshl_add_u64 v[136:137], v[136:137], 2, s[6:7]
	s_waitcnt vmcnt(9)
	v_mov_b32_e32 v34, v16
	s_waitcnt vmcnt(8)
	v_mov_b32_e32 v35, v20
	v_mov_b32_e32 v20, v17
	v_mov_b32_e32 v16, v18
	v_mov_b32_e32 v17, v22
	v_mov_b32_e32 v22, v19
	s_waitcnt vmcnt(7)
	v_mov_b32_e32 v18, v24
	s_waitcnt vmcnt(6)
	v_mov_b32_e32 v19, v28
	v_mov_b32_e32 v28, v25
	v_mov_b32_e32 v24, v26
	v_mov_b32_e32 v25, v30
	v_mov_b32_e32 v30, v27
	v_pk_add_f32 v[20:21], v[34:35], v[20:21]
	v_pk_add_f32 v[16:17], v[16:17], v[22:23]
	v_pk_add_f32 v[18:19], v[18:19], v[28:29]
	v_pk_add_f32 v[22:23], v[24:25], v[30:31]
	v_pk_add_f32 v[16:17], v[20:21], v[16:17]
	v_pk_add_f32 v[18:19], v[18:19], v[22:23]
	v_mov_b32_e32 v21, v16
	v_mov_b32_e32 v20, v18
	v_mov_b32_e32 v16, v19
	v_pk_add_f32 v[16:17], v[20:21], v[16:17]
	v_lshl_add_u64 v[20:21], v[32:33], 0, v[142:143]
	v_lshl_add_u64 v[22:23], v[32:33], 0, v[146:147]
	v_lshl_add_u64 v[142:143], v[32:33], 0, v[218:219]
	global_load_dwordx4 v[36:39], v[20:21], off
	global_load_dwordx4 v[32:35], v[20:21], off offset:16
	global_load_dwordx4 v[28:31], v[22:23], off
	global_load_dwordx4 v[24:27], v[22:23], off offset:16
	ds_bpermute_b32 v19, v195, v17
	ds_bpermute_b32 v18, v195, v16
	s_waitcnt lgkmcnt(0)
	v_pk_add_f32 v[16:17], v[16:17], v[18:19]
	ds_bpermute_b32 v19, v194, v17
	ds_bpermute_b32 v18, v194, v16
	s_waitcnt lgkmcnt(0)
	v_pk_add_f32 v[16:17], v[16:17], v[18:19]
	s_nop 0
	v_pk_fma_f32 v[16:17], v[16:17], s[2:3], v[132:133] op_sel_hi:[1,0,0]
	s_nop 0
	v_mul_f32_e32 v18, 0x4b800000, v17
	v_cmp_gt_f32_e32 vcc, s3, v17
	v_mul_f32_e32 v19, 0x4b800000, v16
	v_cmp_gt_f32_e64 s[0:1], s3, v16
	v_cndmask_b32_e32 v17, v17, v18, vcc
	v_rsq_f32_e32 v146, v17
	v_cndmask_b32_e64 v16, v16, v19, s[0:1]
	v_rsq_f32_e32 v147, v16
	global_load_dwordx4 v[20:23], v[142:143], off
	global_load_dwordx4 v[16:19], v[142:143], off offset:16
	v_mul_f32_e32 v142, 0x45800000, v146
	v_cndmask_b32_e32 v142, v146, v142, vcc
	v_mul_f32_e32 v143, 0x45800000, v147
	v_cndmask_b32_e64 v146, v147, v143, s[0:1]
	v_pk_mul_f32 v[120:121], v[120:121], v[142:143] op_sel_hi:[1,0]
	v_pk_mul_f32 v[122:123], v[122:123], v[142:143] op_sel_hi:[1,0]
	v_pk_mul_f32 v[124:125], v[124:125], v[142:143] op_sel_hi:[1,0]
	v_pk_mul_f32 v[126:127], v[126:127], v[142:143] op_sel_hi:[1,0]
	v_pk_mul_f32 v[218:219], v[116:117], v[142:143] op_sel_hi:[1,0]
	v_pk_mul_f32 v[116:117], v[112:113], v[142:143] op_sel_hi:[1,0]
	v_pk_mul_f32 v[220:221], v[114:115], v[142:143] op_sel_hi:[1,0]
	v_pk_mul_f32 v[118:119], v[118:119], v[142:143] op_sel_hi:[1,0]
	v_pk_mul_f32 v[142:143], v[108:109], v[146:147] op_sel_hi:[1,0]
	v_pk_mul_f32 v[222:223], v[110:111], v[146:147] op_sel_hi:[1,0]
	v_pk_mul_f32 v[224:225], v[106:107], v[146:147] op_sel_hi:[1,0]
	v_pk_mul_f32 v[108:109], v[14:15], v[122:123]
	v_pk_mul_f32 v[106:107], v[12:13], v[120:121]
	v_pk_mul_f32 v[104:105], v[104:105], v[146:147] op_sel_hi:[1,0]
	v_pk_mul_f32 v[112:113], v[10:11], v[126:127]
	v_pk_mul_f32 v[110:111], v[8:9], v[124:125]
	v_pk_mul_f32 v[116:117], v[6:7], v[116:117]
	v_pk_mul_f32 v[114:115], v[4:5], v[218:219]
	v_pk_mul_f32 v[120:121], v[2:3], v[118:119]
	v_pk_mul_f32 v[118:119], v[0:1], v[220:221]
	v_pk_mul_f32 v[124:125], v[14:15], v[222:223]
	v_pk_mul_f32 v[122:123], v[12:13], v[142:143]
	global_store_dwordx4 v[216:217], v[106:109], off
	global_store_dwordx4 v[216:217], v[110:113], off offset:16
	global_store_dwordx4 v[216:217], v[114:117], off offset:512
	global_store_dwordx4 v[216:217], v[118:121], off offset:528
	global_store_dwordx4 v[136:137], v[122:125], off
	v_pk_mul_f32 v[106:107], v[10:11], v[104:105]
	v_pk_mul_f32 v[104:105], v[8:9], v[224:225]
	global_store_dwordx4 v[136:137], v[104:107], off offset:16
	s_waitcnt vmcnt(15)
	v_mov_b32_e32 v108, v202
	s_waitcnt vmcnt(14)
	v_mov_b32_e32 v109, v206
	v_mov_b32_e32 v104, v152
	v_mov_b32_e32 v105, v196
	v_mov_b32_e32 v196, v153
	v_mov_b32_e32 v106, v154
	v_mov_b32_e32 v107, v198
	v_mov_b32_e32 v198, v155
	v_pk_add_f32 v[104:105], v[104:105], v[196:197]
	v_pk_add_f32 v[106:107], v[106:107], v[198:199]
	v_mov_b32_e32 v206, v203
	v_pk_add_f32 v[104:105], v[104:105], v[106:107]
	v_mov_b32_e32 v106, v200
	v_mov_b32_e32 v107, v204
	v_mov_b32_e32 v204, v201
	v_pk_add_f32 v[106:107], v[106:107], v[204:205]
	v_pk_add_f32 v[108:109], v[108:109], v[206:207]
	v_pk_mul_f32 v[96:97], v[96:97], v[146:147] op_sel_hi:[1,0]
	v_pk_add_f32 v[106:107], v[106:107], v[108:109]
	v_mov_b32_e32 v109, v104
	v_mov_b32_e32 v108, v106
	v_mov_b32_e32 v104, v107
	v_pk_add_f32 v[108:109], v[108:109], v[104:105]
	ds_bpermute_b32 v111, v195, v109
	ds_bpermute_b32 v110, v195, v108
	v_pk_mul_f32 v[100:101], v[100:101], v[146:147] op_sel_hi:[1,0]
	v_pk_mul_f32 v[106:107], v[6:7], v[96:97]
	v_pk_mul_f32 v[104:105], v[4:5], v[100:101]
	global_store_dwordx4 v[136:137], v[104:107], off offset:512
	s_waitcnt lgkmcnt(0)
	v_pk_add_f32 v[96:97], v[108:109], v[110:111]
	ds_bpermute_b32 v101, v194, v97
	ds_bpermute_b32 v100, v194, v96
	v_pk_mul_f32 v[104:105], v[98:99], v[146:147] op_sel_hi:[1,0]
	v_pk_mul_f32 v[98:99], v[102:103], v[146:147] op_sel_hi:[1,0]
	s_waitcnt lgkmcnt(0)
	v_pk_add_f32 v[96:97], v[96:97], v[100:101]
	s_nop 0
	v_pk_fma_f32 v[100:101], v[96:97], s[2:3], v[132:133] op_sel_hi:[1,0,0]
	v_pk_mul_f32 v[98:99], v[2:3], v[98:99]
	v_mul_f32_e32 v96, 0x4b800000, v101
	v_cmp_gt_f32_e32 vcc, s3, v101
	s_nop 1
	v_cndmask_b32_e32 v96, v101, v96, vcc
	v_rsq_f32_e32 v101, v96
	v_pk_mul_f32 v[96:97], v[0:1], v[104:105]
	global_store_dwordx4 v[136:137], v[96:99], off offset:528
	s_nop 1
	v_mul_f32_e32 v98, 0x45800000, v101
	v_cndmask_b32_e32 v98, v101, v98, vcc
	v_pk_mul_f32 v[90:91], v[90:91], v[98:99] op_sel_hi:[1,0]
	v_pk_mul_f32 v[92:93], v[92:93], v[98:99] op_sel_hi:[1,0]
	v_lshl_add_u64 v[96:97], v[140:141], 2, s[6:7]
	v_pk_mul_f32 v[92:93], v[14:15], v[92:93]
	v_pk_mul_f32 v[90:91], v[12:13], v[90:91]
	v_pk_mul_f32 v[84:85], v[84:85], v[98:99] op_sel_hi:[1,0]
	v_pk_mul_f32 v[88:89], v[88:89], v[98:99] op_sel_hi:[1,0]
	global_store_dwordx4 v[96:97], v[90:93], off
	v_pk_mul_f32 v[80:81], v[80:81], v[98:99] op_sel_hi:[1,0]
	v_cmp_gt_f32_e32 vcc, s3, v100
	v_pk_mul_f32 v[90:91], v[10:11], v[88:89]
	v_pk_mul_f32 v[88:89], v[8:9], v[84:85]
	v_pk_mul_f32 v[84:85], v[86:87], v[98:99] op_sel_hi:[1,0]
	v_pk_mul_f32 v[86:87], v[6:7], v[80:81]
	v_pk_mul_f32 v[84:85], v[4:5], v[84:85]
	global_store_dwordx4 v[96:97], v[84:87], off offset:512
	v_pk_mul_f32 v[80:81], v[82:83], v[98:99] op_sel_hi:[1,0]
	v_pk_mul_f32 v[82:83], v[94:95], v[98:99] op_sel_hi:[1,0]
	v_mul_f32_e32 v84, 0x4b800000, v100
	v_cndmask_b32_e32 v84, v100, v84, vcc
	v_rsq_f32_e32 v84, v84
	v_pk_mul_f32 v[82:83], v[2:3], v[82:83]
	v_pk_mul_f32 v[80:81], v[0:1], v[80:81]
	global_store_dwordx4 v[96:97], v[80:83], off offset:528
	global_store_dwordx4 v[96:97], v[88:91], off offset:16
	s_nop 0
	v_mul_f32_e32 v80, 0x45800000, v84
	v_cndmask_b32_e32 v80, v84, v80, vcc
	v_pk_mul_f32 v[72:73], v[72:73], v[80:81] op_sel_hi:[1,0]
	v_pk_mul_f32 v[74:75], v[74:75], v[80:81] op_sel_hi:[1,0]
	v_lshl_add_u64 v[82:83], v[144:145], 2, s[6:7]
	v_pk_mul_f32 v[74:75], v[10:11], v[74:75]
	v_pk_mul_f32 v[72:73], v[8:9], v[72:73]
	global_store_dwordx4 v[82:83], v[72:75], off offset:16
	v_pk_mul_f32 v[76:77], v[76:77], v[80:81] op_sel_hi:[1,0]
	v_pk_mul_f32 v[78:79], v[78:79], v[80:81] op_sel_hi:[1,0]
	s_waitcnt vmcnt(20)
	v_mov_b32_e32 v72, v208
	s_waitcnt vmcnt(19)
	v_mov_b32_e32 v73, v212
	v_mov_b32_e32 v212, v209
	v_mov_b32_e32 v74, v210
	v_mov_b32_e32 v75, v214
	v_mov_b32_e32 v214, v211
	v_pk_add_f32 v[72:73], v[72:73], v[212:213]
	v_pk_add_f32 v[74:75], v[74:75], v[214:215]
	v_pk_mul_f32 v[78:79], v[14:15], v[78:79]
	v_pk_add_f32 v[72:73], v[72:73], v[74:75]
	s_waitcnt vmcnt(18)
	v_mov_b32_e32 v74, v36
	s_waitcnt vmcnt(17)
	v_mov_b32_e32 v75, v32
	v_mov_b32_e32 v32, v37
	v_mov_b32_e32 v36, v38
	v_mov_b32_e32 v37, v34
	v_mov_b32_e32 v34, v39
	v_pk_add_f32 v[32:33], v[74:75], v[32:33]
	v_pk_add_f32 v[34:35], v[36:37], v[34:35]
	v_pk_mul_f32 v[76:77], v[12:13], v[76:77]
	v_pk_add_f32 v[32:33], v[32:33], v[34:35]
	v_mov_b32_e32 v35, v72
	v_mov_b32_e32 v34, v32
	v_mov_b32_e32 v72, v33
	v_pk_add_f32 v[36:37], v[34:35], v[72:73]
	ds_bpermute_b32 v39, v195, v37
	ds_bpermute_b32 v38, v195, v36
	v_pk_mul_f32 v[32:33], v[68:69], v[80:81] op_sel_hi:[1,0]
	v_pk_mul_f32 v[34:35], v[64:65], v[80:81] op_sel_hi:[1,0]
	v_pk_mul_f32 v[32:33], v[4:5], v[32:33]
	v_pk_mul_f32 v[34:35], v[6:7], v[34:35]
	s_waitcnt lgkmcnt(0)
	v_pk_add_f32 v[36:37], v[36:37], v[38:39]
	ds_bpermute_b32 v39, v194, v37
	ds_bpermute_b32 v38, v194, v36
	global_store_dwordx4 v[82:83], v[32:35], off offset:512
	global_store_dwordx4 v[82:83], v[76:79], off
	s_waitcnt lgkmcnt(0)
	v_pk_add_f32 v[36:37], v[36:37], v[38:39]
	s_nop 0
	v_pk_fma_f32 v[36:37], v[36:37], s[2:3], v[132:133] op_sel_hi:[1,0,0]
	v_pk_mul_f32 v[32:33], v[66:67], v[80:81] op_sel_hi:[1,0]
	v_pk_mul_f32 v[34:35], v[70:71], v[80:81] op_sel_hi:[1,0]
	v_pk_mul_f32 v[32:33], v[0:1], v[32:33]
	v_rsq_f32_e32 v64, v37
	v_pk_mul_f32 v[34:35], v[2:3], v[34:35]
	global_store_dwordx4 v[82:83], v[32:35], off offset:528
	v_lshl_add_u64 v[38:39], v[148:149], 2, s[6:7]
	s_nop 0
	v_pk_mul_f32 v[32:33], v[58:59], v[64:65] op_sel_hi:[1,0]
	v_pk_mul_f32 v[34:35], v[60:61], v[64:65] op_sel_hi:[1,0]
	v_pk_mul_f32 v[32:33], v[12:13], v[32:33]
	v_pk_mul_f32 v[34:35], v[14:15], v[34:35]
	global_store_dwordx4 v[38:39], v[32:35], off
	v_mul_f32_e32 v37, 0x4b800000, v36
	v_cmp_gt_f32_e32 vcc, s3, v36
	v_pk_mul_f32 v[32:33], v[52:53], v[64:65] op_sel_hi:[1,0]
	v_pk_mul_f32 v[34:35], v[56:57], v[64:65] op_sel_hi:[1,0]
	v_pk_mul_f32 v[32:33], v[8:9], v[32:33]
	v_pk_mul_f32 v[34:35], v[10:11], v[34:35]
	v_cndmask_b32_e32 v36, v36, v37, vcc
	global_store_dwordx4 v[38:39], v[32:35], off offset:16
	v_rsq_f32_e32 v36, v36
	s_nop 0
	v_pk_mul_f32 v[32:33], v[54:55], v[64:65] op_sel_hi:[1,0]
	v_pk_mul_f32 v[34:35], v[48:49], v[64:65] op_sel_hi:[1,0]
	v_pk_mul_f32 v[32:33], v[4:5], v[32:33]
	v_pk_mul_f32 v[34:35], v[6:7], v[34:35]
	global_store_dwordx4 v[38:39], v[32:35], off offset:512
	v_lshlrev_b64 v[48:49], 2, v[128:129]
	s_nop 0
	v_pk_mul_f32 v[32:33], v[50:51], v[64:65] op_sel_hi:[1,0]
	v_pk_mul_f32 v[34:35], v[62:63], v[64:65] op_sel_hi:[1,0]
	v_pk_mul_f32 v[32:33], v[0:1], v[32:33]
	v_pk_mul_f32 v[34:35], v[2:3], v[34:35]
	global_store_dwordx4 v[38:39], v[32:35], off offset:528
	v_lshlrev_b64 v[38:39], 13, v[138:139]
	v_lshl_add_u64 v[38:39], s[6:7], 0, v[38:39]
	v_mul_f32_e32 v32, 0x45800000, v36
	v_cndmask_b32_e32 v36, v36, v32, vcc
	v_pk_mul_f32 v[32:33], v[158:159], v[36:37] op_sel_hi:[1,0]
	v_pk_mul_f32 v[34:35], v[160:161], v[36:37] op_sel_hi:[1,0]
	v_pk_mul_f32 v[32:33], v[12:13], v[32:33]
	v_pk_mul_f32 v[34:35], v[14:15], v[34:35]
	v_lshl_add_u64 v[38:39], v[38:39], 0, v[48:49]
	global_store_dwordx4 v[38:39], v[32:35], off
	s_nop 1
	v_pk_mul_f32 v[32:33], v[46:47], v[36:37] op_sel_hi:[1,0]
	v_pk_mul_f32 v[34:35], v[156:157], v[36:37] op_sel_hi:[1,0]
	v_pk_mul_f32 v[32:33], v[8:9], v[32:33]
	v_pk_mul_f32 v[34:35], v[10:11], v[34:35]
	global_store_dwordx4 v[38:39], v[32:35], off offset:16
	s_nop 1
	v_pk_mul_f32 v[32:33], v[44:45], v[36:37] op_sel_hi:[1,0]
	s_waitcnt vmcnt(25)
	v_mov_b32_e32 v44, v28
	s_waitcnt vmcnt(24)
	v_mov_b32_e32 v45, v24
	v_mov_b32_e32 v24, v29
	v_mov_b32_e32 v28, v30
	v_mov_b32_e32 v29, v26
	v_mov_b32_e32 v26, v31
	v_pk_add_f32 v[24:25], v[44:45], v[24:25]
	v_pk_add_f32 v[26:27], v[28:29], v[26:27]
	v_pk_mul_f32 v[34:35], v[162:163], v[36:37] op_sel_hi:[1,0]
	v_pk_add_f32 v[24:25], v[24:25], v[26:27]
	s_waitcnt vmcnt(23)
	v_mov_b32_e32 v26, v20
	s_waitcnt vmcnt(22)
	v_mov_b32_e32 v27, v16
	v_mov_b32_e32 v16, v21
	v_mov_b32_e32 v20, v22
	v_mov_b32_e32 v21, v18
	v_mov_b32_e32 v18, v23
	v_pk_add_f32 v[16:17], v[26:27], v[16:17]
	v_pk_add_f32 v[18:19], v[20:21], v[18:19]
	s_nop 0
	v_pk_add_f32 v[16:17], v[16:17], v[18:19]
	v_mov_b32_e32 v19, v24
	v_mov_b32_e32 v18, v16
	v_mov_b32_e32 v24, v17
	v_pk_add_f32 v[20:21], v[18:19], v[24:25]
	ds_bpermute_b32 v23, v195, v21
	ds_bpermute_b32 v22, v195, v20
	v_pk_mul_f32 v[18:19], v[6:7], v[34:35]
	v_pk_mul_f32 v[16:17], v[4:5], v[32:33]
	global_store_dwordx4 v[38:39], v[16:19], off offset:512
	s_waitcnt lgkmcnt(0)
	v_pk_add_f32 v[20:21], v[20:21], v[22:23]
	ds_bpermute_b32 v23, v194, v21
	ds_bpermute_b32 v22, v194, v20
	v_pk_mul_f32 v[16:17], v[40:41], v[36:37] op_sel_hi:[1,0]
	v_pk_mul_f32 v[18:19], v[42:43], v[36:37] op_sel_hi:[1,0]
	v_pk_mul_f32 v[16:17], v[0:1], v[16:17]
	v_pk_mul_f32 v[18:19], v[2:3], v[18:19]
	global_store_dwordx4 v[38:39], v[16:19], off offset:528
	s_waitcnt lgkmcnt(0)
	s_nop 0
	v_pk_add_f32 v[16:17], v[20:21], v[22:23]
	s_nop 0
	v_pk_fma_f32 v[20:21], v[16:17], s[2:3], v[132:133] op_sel_hi:[1,0,0]
	s_nop 0
	v_rsq_f32_e32 v24, v21
	v_lshlrev_b64 v[16:17], 13, v[134:135]
	v_lshl_add_u64 v[16:17], s[6:7], 0, v[16:17]
	v_lshl_add_u64 v[22:23], v[16:17], 0, v[48:49]
	v_pk_mul_f32 v[16:17], v[170:171], v[24:25] op_sel_hi:[1,0]
	v_pk_mul_f32 v[18:19], v[172:173], v[24:25] op_sel_hi:[1,0]
	v_pk_mul_f32 v[16:17], v[12:13], v[16:17]
	v_pk_mul_f32 v[18:19], v[14:15], v[18:19]
	global_store_dwordx4 v[22:23], v[16:19], off
	v_mul_f32_e32 v21, 0x4b800000, v20
	v_cmp_gt_f32_e32 vcc, s3, v20
	v_pk_mul_f32 v[16:17], v[164:165], v[24:25] op_sel_hi:[1,0]
	v_pk_mul_f32 v[18:19], v[166:167], v[24:25] op_sel_hi:[1,0]
	v_pk_mul_f32 v[16:17], v[8:9], v[16:17]
	v_pk_mul_f32 v[18:19], v[10:11], v[18:19]
	v_cndmask_b32_e32 v20, v20, v21, vcc
	global_store_dwordx4 v[22:23], v[16:19], off offset:16
	v_rsq_f32_e32 v20, v20
	s_nop 0
	v_pk_mul_f32 v[16:17], v[168:169], v[24:25] op_sel_hi:[1,0]
	v_pk_mul_f32 v[18:19], v[174:175], v[24:25] op_sel_hi:[1,0]
	v_pk_mul_f32 v[16:17], v[4:5], v[16:17]
	v_pk_mul_f32 v[18:19], v[6:7], v[18:19]
	global_store_dwordx4 v[22:23], v[16:19], off offset:512
	s_nop 1
	v_pk_mul_f32 v[16:17], v[176:177], v[24:25] op_sel_hi:[1,0]
	v_pk_mul_f32 v[18:19], v[178:179], v[24:25] op_sel_hi:[1,0]
	v_pk_mul_f32 v[16:17], v[0:1], v[16:17]
	v_pk_mul_f32 v[18:19], v[2:3], v[18:19]
	global_store_dwordx4 v[22:23], v[16:19], off offset:528
	s_nop 1
	v_mul_f32_e32 v16, 0x45800000, v20
	v_cndmask_b32_e32 v16, v20, v16, vcc
	v_pk_mul_f32 v[18:19], v[184:185], v[16:17] op_sel_hi:[1,0]
	v_pk_mul_f32 v[20:21], v[186:187], v[16:17] op_sel_hi:[1,0]
	v_pk_mul_f32 v[12:13], v[12:13], v[18:19]
	v_lshlrev_b64 v[18:19], 13, v[130:131]
	v_lshl_add_u64 v[18:19], s[6:7], 0, v[18:19]
	v_pk_mul_f32 v[14:15], v[14:15], v[20:21]
	v_lshl_add_u64 v[18:19], v[18:19], 0, v[48:49]
	global_store_dwordx4 v[18:19], v[12:15], off
	s_nop 1
	v_pk_mul_f32 v[12:13], v[180:181], v[16:17] op_sel_hi:[1,0]
	v_pk_mul_f32 v[14:15], v[182:183], v[16:17] op_sel_hi:[1,0]
	v_pk_mul_f32 v[8:9], v[8:9], v[12:13]
	v_pk_mul_f32 v[10:11], v[10:11], v[14:15]
	global_store_dwordx4 v[18:19], v[8:11], off offset:16
	s_nop 1
	v_pk_mul_f32 v[8:9], v[150:151], v[16:17] op_sel_hi:[1,0]
	v_pk_mul_f32 v[10:11], v[188:189], v[16:17] op_sel_hi:[1,0]
	v_pk_mul_f32 v[4:5], v[4:5], v[8:9]
	v_pk_mul_f32 v[6:7], v[6:7], v[10:11]
	global_store_dwordx4 v[18:19], v[4:7], off offset:512
	s_nop 1
	v_pk_mul_f32 v[4:5], v[190:191], v[16:17] op_sel_hi:[1,0]
	v_pk_mul_f32 v[6:7], v[192:193], v[16:17] op_sel_hi:[1,0]
	v_pk_mul_f32 v[0:1], v[0:1], v[4:5]
	v_pk_mul_f32 v[2:3], v[2:3], v[6:7]
	global_store_dwordx4 v[18:19], v[0:3], off offset:528
